# gdn_prep stage C forward substitution: quad-distributed ds_read_b64 L reads + DPP quad_perm broadcast FMAs (4x less LDS traffic), on top of pipelined compress loop
# speedup vs baseline: 1.0138x; 1.0017x over previous
; __device__ __forceinline__ void ph_nsa_compress_fast(const bf16* __restrict__ proj, const bf16* __restrict__ W1T, const bf16* __restrict__ W2T, const float* __restrict__ C1, const float* __restrict__ kg, ...
;     ...
;         const int lane = tid & 63, wave = tid >> 6, r16 = lane & 15, a = lane >> 4;
;         const int half = item & 1, kv = (item >> 1) & 1, g = (item >> 2) & 1, b = item >> 3;
;         const int mt = half * 8 + wave, n = 16 * mt + r16;
;         const bf16* arow = proj + (size_t)b * SEQ * NPROJ + (kv ? PC_VCC : PC_KCC) + g * 128 + 8 * a;
;         const bf16* w1t = W1T + (size_t)kv * 128 * 4096;
;         u32x4 st[4];
;         auto gload = [&](int l) {
; #pragma unroll
;             for (int i = 0; i < 4; ++i) { const int c = tid + 512 * i; st[i] = *(const u32x4*)(w1t + (size_t)(c >> 4) * 4096 + l * 128 + (c & 15) * 8); } };
;         auto lwrite = [&](int buf) {
; #pragma unroll
;             for (int i = 0; i < 4; ++i) { const int c = tid + 512 * i; *(u32x4*)(lds_dyn + buf * CP_STAGE + (c >> 4) * CP_STR + (c & 15) * 16) = st[i]; } };
;         f32x4v acc[8];
; #pragma unroll
;         for (int i = 0; i < 8; ++i) acc[i] = (f32x4v){0.f, 0.f, 0.f, 0.f};
;         __syncthreads();
;         gload(0); lwrite(0);
;         __syncthreads();
; #pragma unroll 1
;         for (int l = 0; l < 32; ++l) {
;             const int buf = l & 1;
;             if (l < 31) gload(l + 1);
;             const int tok = 16 * n + l < SEQ ? 16 * n + l : SEQ - 1;
;             bf16x8 af[4];
; #pragma unroll
;             for (int s = 0; s < 4; ++s) af[s] = ld_frag(arow + (size_t)tok * NPROJ + 32 * s);
.LBB0_1234:
	s_bfe_u32 s4, s38, 0x10001
	s_lshl_b32 s0, s75, 8
	s_lshl_b32 s64, s4, 20
	s_and_b32 s8, s0, 0x800
	s_bfe_u32 s39, s38, 0x10002
	s_ashr_i32 s40, s38, 3
	s_bitcmp1_b32 s38, 1
	s_cselect_b64 s[0:1], -1, 0
	s_cmp_eq_u32 s4, 0
	s_movk_i32 s7, 0x2600
	s_mul_i32 s6, s40, 0x3400000
	s_cselect_b32 s7, s7, 0x2800
	s_lshl_b32 s42, s4, 7
	s_mul_hi_i32 s5, s40, 0x3400000
	s_add_u32 s4, s2, s6
	v_mov_b32_e32 v2, v1
	s_addc_u32 s5, s3, s5
	s_add_u32 s4, s4, s7
	v_ashrrev_i32_e32 v4, 4, v2
	s_addc_u32 s5, s5, 0
	s_lshl_b32 s6, s39, 8
	v_ashrrev_i32_e32 v5, 31, v4
	s_add_u32 s4, s4, s6
	v_lshlrev_b64 v[6:7], 13, v[4:5]
	v_lshlrev_b32_e32 v5, 4, v2
	s_addc_u32 s5, s5, 0
	v_and_b32_e32 v52, 0xf0, v5
	v_add_u32_e32 v5, 0x200, v2
	s_add_u32 s6, s20, s64
	v_ashrrev_i32_e32 v10, 4, v5
	s_addc_u32 s7, s21, 0
	v_ashrrev_i32_e32 v11, 31, v10
	v_lshl_add_u64 v[8:9], s[6:7], 0, v[6:7]
	v_mov_b32_e32 v53, v3
	v_lshlrev_b64 v[12:13], 13, v[10:11]
	v_lshl_add_u64 v[8:9], v[8:9], 0, v[52:53]
	v_lshl_add_u64 v[14:15], s[6:7], 0, v[12:13]
	v_add_u32_e32 v5, 0x400, v2
	s_barrier
	v_lshl_add_u64 v[14:15], v[14:15], 0, v[52:53]
	global_load_dwordx4 v[28:31], v[8:9], off
	global_load_dwordx4 v[32:35], v[14:15], off
	v_ashrrev_i32_e32 v8, 4, v5
	v_add_u32_e32 v5, 0x600, v2
	v_ashrrev_i32_e32 v9, 31, v8
	v_ashrrev_i32_e32 v18, 4, v5
	v_lshlrev_b64 v[14:15], 13, v[8:9]
	v_ashrrev_i32_e32 v19, 31, v18
	v_lshl_add_u64 v[16:17], s[6:7], 0, v[14:15]
	v_lshlrev_b64 v[20:21], 13, v[18:19]
	v_lshl_add_u64 v[16:17], v[16:17], 0, v[52:53]
	v_lshl_add_u64 v[22:23], s[6:7], 0, v[20:21]
	v_lshl_add_u64 v[22:23], v[22:23], 0, v[52:53]
	global_load_dwordx4 v[36:39], v[16:17], off
	global_load_dwordx4 v[40:43], v[22:23], off
	v_and_b32_e32 v57, 15, v2
	v_ashrrev_i32_e32 v70, 6, v2
	v_bfe_u32 v68, v2, 4, 2
	v_mul_lo_u32 v71, v4, s93
	v_lshlrev_b32_e32 v16, 4, v57
	v_mul_lo_u32 v72, v10, s93
	v_mul_lo_u32 v73, v8, s93
	v_mul_lo_u32 v74, v18, s93
	v_lshl_add_u64 v[4:5], s[64:65], 0, v[6:7]
	v_lshl_add_u64 v[6:7], s[64:65], 0, v[12:13]
	v_lshl_add_u64 v[8:9], s[64:65], 0, v[14:15]
	v_lshl_add_u64 v[10:11], s[64:65], 0, v[20:21]
	v_lshrrev_b32_e32 v69, 4, v2
	v_lshlrev_b32_e32 v2, 4, v68
	v_mul_u32_u24_e32 v53, 0x110, v57
	v_lshl_add_u32 v17, v70, 8, s8
	v_add3_u32 v19, 0, v71, v52
	v_add3_u32 v18, 0, v72, v52
	v_add3_u32 v22, 0, v73, v52
	v_add3_u32 v23, 0, v74, v52
	v_or_b32_e32 v4, v4, v16
	v_or_b32_e32 v6, v6, v16
	v_or_b32_e32 v8, v8, v16
	v_or_b32_e32 v10, v10, v16
	v_mov_b32_e32 v48, 0
	s_mov_b32 s26, 0
	v_lshlrev_b32_e32 v56, 3, v68
	v_add3_u32 v75, 0, v53, v2
	v_lshl_add_u64 v[54:55], s[16:17], 0, v[4:5]
	v_lshl_add_u64 v[58:59], s[16:17], 0, v[6:7]
	v_lshl_add_u64 v[60:61], s[16:17], 0, v[8:9]
	v_lshl_add_u64 v[62:63], s[16:17], 0, v[10:11]
	v_lshl_add_u64 v[64:65], s[4:5], 0, v[2:3]
	v_or_b32_e32 v76, v17, v16
	s_mov_b64 s[4:5], 0
	v_mov_b32_e32 v49, v48
	v_mov_b32_e32 v50, v48
	v_mov_b32_e32 v51, v48
	v_mov_b32_e32 v44, v48
	v_mov_b32_e32 v45, v48
	v_mov_b32_e32 v46, v48
	v_mov_b32_e32 v47, v48
	v_mov_b32_e32 v24, v48
	v_mov_b32_e32 v25, v48
	s_waitcnt vmcnt(3)
	ds_write_b128 v19, v[28:31]
	s_waitcnt vmcnt(2)
	ds_write_b128 v18, v[32:35]
	s_waitcnt vmcnt(1)
	ds_write_b128 v22, v[36:39]
	s_waitcnt vmcnt(0)
	ds_write_b128 v23, v[40:43]
	v_mov_b32_e32 v26, v48
	v_mov_b32_e32 v27, v48
	v_mov_b32_e32 v20, v48
	v_mov_b32_e32 v21, v48
	v_mov_b32_e32 v22, v48
	v_mov_b32_e32 v23, v48
	v_mov_b32_e32 v16, v48
	v_mov_b32_e32 v17, v48
	v_mov_b32_e32 v18, v48
	v_mov_b32_e32 v19, v48
	v_mov_b32_e32 v12, v48
	v_mov_b32_e32 v13, v48
	v_mov_b32_e32 v14, v48
	v_mov_b32_e32 v15, v48
	v_mov_b32_e32 v8, v48
	v_mov_b32_e32 v9, v48
	v_mov_b32_e32 v10, v48
	v_mov_b32_e32 v11, v48
	v_mov_b32_e32 v4, v48
	v_mov_b32_e32 v5, v48
	v_mov_b32_e32 v6, v48
	v_mov_b32_e32 v7, v48
	v_add_u32_e32 v78, s26, v76
	v_cmp_gt_i32_e32 vcc, s79, v78
	v_mov_b64_e32 v[66:67], 0x19fe600
	s_and_saveexec_b64 s[8:9], vcc
	s_movk_i32 s27, 0x1a00
	v_mad_i64_i32 v[66:67], s[44:45], v78, s27, 0
	s_or_b64 exec, exec, s[8:9]
	v_lshl_add_u64 v[66:67], v[66:67], 1, v[64:65]
	global_load_dwordx4 v[164:167], v[66:67], off
	global_load_dwordx4 v[168:171], v[66:67], off offset:64
	global_load_dwordx4 v[172:175], v[66:67], off offset:128
	global_load_dwordx4 v[176:179], v[66:67], off offset:192
	s_waitcnt lgkmcnt(0)
	s_barrier
	s_branch .LBB0_1236
; #define MFMA16(a, b, c) __builtin_amdgcn_mfma_f32_16x16x32_bf16((a), (b), (c), 0, 0, 0)
; __device__ __forceinline__ void ph_nsa_compress_fast(const bf16* __restrict__ proj, const bf16* __restrict__ W1T, const bf16* __restrict__ W2T, const float* __restrict__ C1, const float* __restrict__ kg, ...
;     ...
;         for (int l = 0; l < 32; ++l) {
;             const int buf = l & 1;
;             if (l < 31) gload(l + 1);
;             const int tok = 16 * n + l < SEQ ? 16 * n + l : SEQ - 1;
;             bf16x8 af[4];
; #pragma unroll
;             for (int s = 0; s < 4; ++s) af[s] = ld_frag(arow + (size_t)tok * NPROJ + 32 * s);
;             const unsigned char* wb = lds_dyn + buf * CP_STAGE + r16 * CP_STR + 16 * a;
; #pragma unroll
;             for (int s = 0; s < 4; ++s)
; #pragma unroll
;                 for (int nt = 0; nt < 8; ++nt) acc[nt] = MFMA16(af[s], __builtin_bit_cast(bf16x8, *(const u32x4*)(wb + nt * 16 * CP_STR + 64 * s)), acc[nt]);
;             if (l < 31) lwrite(buf ^ 1);
;             __syncthreads();
.LBB0_1236:
	v_lshl_add_u64 v[40:41], v[62:63], 0, s[4:5]
	v_lshl_add_u64 v[36:37], v[60:61], 0, s[4:5]
	v_lshl_add_u64 v[32:33], v[58:59], 0, s[4:5]
	v_lshl_add_u64 v[28:29], v[54:55], 0, s[4:5]
	global_load_dwordx4 v[28:31], v[28:29], off
	s_nop 0
	global_load_dwordx4 v[32:35], v[32:33], off
	s_nop 0
	global_load_dwordx4 v[36:39], v[36:37], off
	s_nop 0
	global_load_dwordx4 v[40:43], v[40:41], off
	s_add_i32 s8, s26, 1
	v_add_u32_e32 v78, s8, v76
	v_cmp_gt_i32_e32 vcc, s79, v78
	v_mov_b64_e32 v[66:67], 0x19fe600
	s_and_saveexec_b64 s[8:9], vcc
	s_movk_i32 s27, 0x1a00
	v_mad_i64_i32 v[66:67], s[44:45], v78, s27, 0
	s_or_b64 exec, exec, s[8:9]
	v_lshl_add_u64 v[66:67], v[66:67], 1, v[64:65]
	global_load_dwordx4 v[116:119], v[66:67], off
	global_load_dwordx4 v[120:123], v[66:67], off offset:64
	global_load_dwordx4 v[124:127], v[66:67], off offset:128
	global_load_dwordx4 v[244:247], v[66:67], off offset:192
	v_mov_b32_e32 v77, v75
	ds_read_b128 v[132:135], v77
	ds_read_b128 v[136:139], v77 offset:4352
	ds_read_b128 v[140:143], v77 offset:8704
	ds_read_b128 v[144:147], v77 offset:13056
	ds_read_b128 v[148:151], v77 offset:17408
	ds_read_b128 v[152:155], v77 offset:21760
	ds_read_b128 v[156:159], v77 offset:26112
	ds_read_b128 v[160:163], v77 offset:30464
	ds_read_b128 v[196:199], v77 offset:64
	ds_read_b128 v[200:203], v77 offset:4416
	ds_read_b128 v[204:207], v77 offset:8768
	ds_read_b128 v[208:211], v77 offset:13120
	ds_read_b128 v[212:215], v77 offset:17472
	ds_read_b128 v[216:219], v77 offset:21824
	ds_read_b128 v[220:223], v77 offset:26176
	ds_read_b128 v[224:227], v77 offset:30528
	s_waitcnt vmcnt(8)
	s_waitcnt lgkmcnt(8)
	v_mfma_f32_16x16x32_bf16 v[48:51], v[164:167], v[132:135], v[48:51]
	v_mfma_f32_16x16x32_bf16 v[44:47], v[164:167], v[136:139], v[44:47]
	v_mfma_f32_16x16x32_bf16 v[24:27], v[164:167], v[140:143], v[24:27]
	v_mfma_f32_16x16x32_bf16 v[20:23], v[164:167], v[144:147], v[20:23]
	v_mfma_f32_16x16x32_bf16 v[16:19], v[164:167], v[148:151], v[16:19]
	v_mfma_f32_16x16x32_bf16 v[12:15], v[164:167], v[152:155], v[12:15]
	v_mfma_f32_16x16x32_bf16 v[8:11], v[164:167], v[156:159], v[8:11]
	v_mfma_f32_16x16x32_bf16 v[4:7], v[164:167], v[160:163], v[4:7]
	ds_read_b128 v[132:135], v77 offset:128
	ds_read_b128 v[136:139], v77 offset:4480
	ds_read_b128 v[140:143], v77 offset:8832
	ds_read_b128 v[144:147], v77 offset:13184
	ds_read_b128 v[148:151], v77 offset:17536
	ds_read_b128 v[152:155], v77 offset:21888
	ds_read_b128 v[156:159], v77 offset:26240
	ds_read_b128 v[160:163], v77 offset:30592
	s_waitcnt lgkmcnt(8)
	v_mfma_f32_16x16x32_bf16 v[48:51], v[168:171], v[196:199], v[48:51]
	v_mfma_f32_16x16x32_bf16 v[44:47], v[168:171], v[200:203], v[44:47]
	v_mfma_f32_16x16x32_bf16 v[24:27], v[168:171], v[204:207], v[24:27]
	v_mfma_f32_16x16x32_bf16 v[20:23], v[168:171], v[208:211], v[20:23]
	v_mfma_f32_16x16x32_bf16 v[16:19], v[168:171], v[212:215], v[16:19]
	v_mfma_f32_16x16x32_bf16 v[12:15], v[168:171], v[216:219], v[12:15]
	v_mfma_f32_16x16x32_bf16 v[8:11], v[168:171], v[220:223], v[8:11]
	v_mfma_f32_16x16x32_bf16 v[4:7], v[168:171], v[224:227], v[4:7]
	ds_read_b128 v[196:199], v77 offset:192
	ds_read_b128 v[200:203], v77 offset:4544
	ds_read_b128 v[204:207], v77 offset:8896
	ds_read_b128 v[208:211], v77 offset:13248
	ds_read_b128 v[212:215], v77 offset:17600
	ds_read_b128 v[216:219], v77 offset:21952
	ds_read_b128 v[220:223], v77 offset:26304
	ds_read_b128 v[224:227], v77 offset:30656
	s_waitcnt lgkmcnt(8)
	v_mfma_f32_16x16x32_bf16 v[48:51], v[172:175], v[132:135], v[48:51]
	v_mfma_f32_16x16x32_bf16 v[44:47], v[172:175], v[136:139], v[44:47]
	v_mfma_f32_16x16x32_bf16 v[24:27], v[172:175], v[140:143], v[24:27]
	v_mfma_f32_16x16x32_bf16 v[20:23], v[172:175], v[144:147], v[20:23]
	v_mfma_f32_16x16x32_bf16 v[16:19], v[172:175], v[148:151], v[16:19]
	v_mfma_f32_16x16x32_bf16 v[12:15], v[172:175], v[152:155], v[12:15]
	v_mfma_f32_16x16x32_bf16 v[8:11], v[172:175], v[156:159], v[8:11]
	v_mfma_f32_16x16x32_bf16 v[4:7], v[172:175], v[160:163], v[4:7]
	s_waitcnt lgkmcnt(0)
	v_mfma_f32_16x16x32_bf16 v[48:51], v[176:179], v[196:199], v[48:51]
	v_mfma_f32_16x16x32_bf16 v[44:47], v[176:179], v[200:203], v[44:47]
	v_mfma_f32_16x16x32_bf16 v[24:27], v[176:179], v[204:207], v[24:27]
	v_mfma_f32_16x16x32_bf16 v[20:23], v[176:179], v[208:211], v[20:23]
	v_mfma_f32_16x16x32_bf16 v[16:19], v[176:179], v[212:215], v[16:19]
	v_mfma_f32_16x16x32_bf16 v[12:15], v[176:179], v[216:219], v[12:15]
	v_mfma_f32_16x16x32_bf16 v[8:11], v[176:179], v[220:223], v[8:11]
	v_mfma_f32_16x16x32_bf16 v[4:7], v[176:179], v[224:227], v[4:7]
	s_waitcnt vmcnt(4)
	s_mov_b32 s6, 0x8800
	v_add3_u32 v86, s6, v71, v52
	v_add3_u32 v87, s6, v72, v52
	v_add3_u32 v88, s6, v73, v52
	v_add3_u32 v89, s6, v74, v52
	ds_write_b128 v86, v[28:31]
	ds_write_b128 v87, v[32:35]
	ds_write_b128 v88, v[36:39]
	ds_write_b128 v89, v[40:43]
	s_add_i32 s26, s26, 1
	s_add_u32 s4, s4, 0x100
	s_addc_u32 s5, s5, 0
	s_waitcnt lgkmcnt(0)
	s_barrier
	v_add_u32_e32 v77, 0x8800, v75
	s_cmpk_eq_i32 s4, 0x1f00
	s_cbranch_scc1 .Lcp_odd_last
; #define MFMA16(a, b, c) __builtin_amdgcn_mfma_f32_16x16x32_bf16((a), (b), (c), 0, 0, 0)
; __device__ __forceinline__ void ph_nsa_compress_fast(const bf16* __restrict__ proj, const bf16* __restrict__ W1T, const bf16* __restrict__ W2T, const float* __restrict__ C1, const float* __restrict__ kg, ...
;     ...
;         for (int l = 0; l < 32; ++l) {
;             const int buf = l & 1;
;             if (l < 31) gload(l + 1);
;             const int tok = 16 * n + l < SEQ ? 16 * n + l : SEQ - 1;
;             bf16x8 af[4];
; #pragma unroll
;             for (int s = 0; s < 4; ++s) af[s] = ld_frag(arow + (size_t)tok * NPROJ + 32 * s);
;             const unsigned char* wb = lds_dyn + buf * CP_STAGE + r16 * CP_STR + 16 * a;
; #pragma unroll
;             for (int s = 0; s < 4; ++s)
; #pragma unroll
;                 for (int nt = 0; nt < 8; ++nt) acc[nt] = MFMA16(af[s], __builtin_bit_cast(bf16x8, *(const u32x4*)(wb + nt * 16 * CP_STR + 64 * s)), acc[nt]);
;             if (l < 31) lwrite(buf ^ 1);
;             __syncthreads();
	v_lshl_add_u64 v[40:41], v[62:63], 0, s[4:5]
	v_lshl_add_u64 v[36:37], v[60:61], 0, s[4:5]
	v_lshl_add_u64 v[32:33], v[58:59], 0, s[4:5]
	v_lshl_add_u64 v[28:29], v[54:55], 0, s[4:5]
	global_load_dwordx4 v[28:31], v[28:29], off
	s_nop 0
	global_load_dwordx4 v[32:35], v[32:33], off
	s_nop 0
	global_load_dwordx4 v[36:39], v[36:37], off
	s_nop 0
	global_load_dwordx4 v[40:43], v[40:41], off
	s_add_i32 s8, s26, 1
	v_add_u32_e32 v78, s8, v76
	v_cmp_gt_i32_e32 vcc, s79, v78
	v_mov_b64_e32 v[66:67], 0x19fe600
	s_and_saveexec_b64 s[8:9], vcc
	s_movk_i32 s27, 0x1a00
	v_mad_i64_i32 v[66:67], s[44:45], v78, s27, 0
	s_or_b64 exec, exec, s[8:9]
	v_lshl_add_u64 v[66:67], v[66:67], 1, v[64:65]
	global_load_dwordx4 v[164:167], v[66:67], off
	global_load_dwordx4 v[168:171], v[66:67], off offset:64
	global_load_dwordx4 v[172:175], v[66:67], off offset:128
	global_load_dwordx4 v[176:179], v[66:67], off offset:192
	ds_read_b128 v[132:135], v77
	ds_read_b128 v[136:139], v77 offset:4352
	ds_read_b128 v[140:143], v77 offset:8704
	ds_read_b128 v[144:147], v77 offset:13056
	ds_read_b128 v[148:151], v77 offset:17408
	ds_read_b128 v[152:155], v77 offset:21760
	ds_read_b128 v[156:159], v77 offset:26112
	ds_read_b128 v[160:163], v77 offset:30464
	ds_read_b128 v[196:199], v77 offset:64
	ds_read_b128 v[200:203], v77 offset:4416
	ds_read_b128 v[204:207], v77 offset:8768
	ds_read_b128 v[208:211], v77 offset:13120
	ds_read_b128 v[212:215], v77 offset:17472
	ds_read_b128 v[216:219], v77 offset:21824
	ds_read_b128 v[220:223], v77 offset:26176
	ds_read_b128 v[224:227], v77 offset:30528
	s_waitcnt vmcnt(8)
	s_waitcnt lgkmcnt(8)
	v_mfma_f32_16x16x32_bf16 v[48:51], v[116:119], v[132:135], v[48:51]
	v_mfma_f32_16x16x32_bf16 v[44:47], v[116:119], v[136:139], v[44:47]
	v_mfma_f32_16x16x32_bf16 v[24:27], v[116:119], v[140:143], v[24:27]
	v_mfma_f32_16x16x32_bf16 v[20:23], v[116:119], v[144:147], v[20:23]
	v_mfma_f32_16x16x32_bf16 v[16:19], v[116:119], v[148:151], v[16:19]
	v_mfma_f32_16x16x32_bf16 v[12:15], v[116:119], v[152:155], v[12:15]
	v_mfma_f32_16x16x32_bf16 v[8:11], v[116:119], v[156:159], v[8:11]
	v_mfma_f32_16x16x32_bf16 v[4:7], v[116:119], v[160:163], v[4:7]
	ds_read_b128 v[132:135], v77 offset:128
	ds_read_b128 v[136:139], v77 offset:4480
	ds_read_b128 v[140:143], v77 offset:8832
	ds_read_b128 v[144:147], v77 offset:13184
	ds_read_b128 v[148:151], v77 offset:17536
	ds_read_b128 v[152:155], v77 offset:21888
	ds_read_b128 v[156:159], v77 offset:26240
	ds_read_b128 v[160:163], v77 offset:30592
	s_waitcnt lgkmcnt(8)
	v_mfma_f32_16x16x32_bf16 v[48:51], v[120:123], v[196:199], v[48:51]
	v_mfma_f32_16x16x32_bf16 v[44:47], v[120:123], v[200:203], v[44:47]
	v_mfma_f32_16x16x32_bf16 v[24:27], v[120:123], v[204:207], v[24:27]
	v_mfma_f32_16x16x32_bf16 v[20:23], v[120:123], v[208:211], v[20:23]
	v_mfma_f32_16x16x32_bf16 v[16:19], v[120:123], v[212:215], v[16:19]
	v_mfma_f32_16x16x32_bf16 v[12:15], v[120:123], v[216:219], v[12:15]
	v_mfma_f32_16x16x32_bf16 v[8:11], v[120:123], v[220:223], v[8:11]
	v_mfma_f32_16x16x32_bf16 v[4:7], v[120:123], v[224:227], v[4:7]
	ds_read_b128 v[196:199], v77 offset:192
	ds_read_b128 v[200:203], v77 offset:4544
	ds_read_b128 v[204:207], v77 offset:8896
	ds_read_b128 v[208:211], v77 offset:13248
	ds_read_b128 v[212:215], v77 offset:17600
	ds_read_b128 v[216:219], v77 offset:21952
	ds_read_b128 v[220:223], v77 offset:26304
	ds_read_b128 v[224:227], v77 offset:30656
	s_waitcnt lgkmcnt(8)
	v_mfma_f32_16x16x32_bf16 v[48:51], v[124:127], v[132:135], v[48:51]
	v_mfma_f32_16x16x32_bf16 v[44:47], v[124:127], v[136:139], v[44:47]
	v_mfma_f32_16x16x32_bf16 v[24:27], v[124:127], v[140:143], v[24:27]
	v_mfma_f32_16x16x32_bf16 v[20:23], v[124:127], v[144:147], v[20:23]
	v_mfma_f32_16x16x32_bf16 v[16:19], v[124:127], v[148:151], v[16:19]
	v_mfma_f32_16x16x32_bf16 v[12:15], v[124:127], v[152:155], v[12:15]
	v_mfma_f32_16x16x32_bf16 v[8:11], v[124:127], v[156:159], v[8:11]
	v_mfma_f32_16x16x32_bf16 v[4:7], v[124:127], v[160:163], v[4:7]
	s_waitcnt lgkmcnt(0)
	v_mfma_f32_16x16x32_bf16 v[48:51], v[244:247], v[196:199], v[48:51]
	v_mfma_f32_16x16x32_bf16 v[44:47], v[244:247], v[200:203], v[44:47]
	v_mfma_f32_16x16x32_bf16 v[24:27], v[244:247], v[204:207], v[24:27]
	v_mfma_f32_16x16x32_bf16 v[20:23], v[244:247], v[208:211], v[20:23]
	v_mfma_f32_16x16x32_bf16 v[16:19], v[244:247], v[212:215], v[16:19]
	v_mfma_f32_16x16x32_bf16 v[12:15], v[244:247], v[216:219], v[12:15]
	v_mfma_f32_16x16x32_bf16 v[8:11], v[244:247], v[220:223], v[8:11]
	v_mfma_f32_16x16x32_bf16 v[4:7], v[244:247], v[224:227], v[4:7]
	s_waitcnt vmcnt(4)
	s_movk_i32 s6, 0x0
	v_add3_u32 v86, s6, v71, v52
	v_add3_u32 v87, s6, v72, v52
	v_add3_u32 v88, s6, v73, v52
	v_add3_u32 v89, s6, v74, v52
	ds_write_b128 v86, v[28:31]
	ds_write_b128 v87, v[32:35]
	ds_write_b128 v88, v[36:39]
	ds_write_b128 v89, v[40:43]
	s_add_i32 s26, s26, 1
	s_add_u32 s4, s4, 0x100
	s_addc_u32 s5, s5, 0
	s_waitcnt lgkmcnt(0)
	s_barrier
	s_branch .LBB0_1236
; #define MFMA16(a, b, c) __builtin_amdgcn_mfma_f32_16x16x32_bf16((a), (b), (c), 0, 0, 0)
; __device__ __forceinline__ void ph_nsa_compress_fast(const bf16* __restrict__ proj, const bf16* __restrict__ W1T, const bf16* __restrict__ W2T, const float* __restrict__ C1, const float* __restrict__ kg, ...
;     ...
;         for (int l = 0; l < 32; ++l) {
;             const int buf = l & 1;
;             if (l < 31) gload(l + 1);
;             const int tok = 16 * n + l < SEQ ? 16 * n + l : SEQ - 1;
;             bf16x8 af[4];
; #pragma unroll
;             for (int s = 0; s < 4; ++s) af[s] = ld_frag(arow + (size_t)tok * NPROJ + 32 * s);
;             const unsigned char* wb = lds_dyn + buf * CP_STAGE + r16 * CP_STR + 16 * a;
; #pragma unroll
;             for (int s = 0; s < 4; ++s)
; #pragma unroll
;                 for (int nt = 0; nt < 8; ++nt) acc[nt] = MFMA16(af[s], __builtin_bit_cast(bf16x8, *(const u32x4*)(wb + nt * 16 * CP_STR + 64 * s)), acc[nt]);
;             if (l < 31) lwrite(buf ^ 1);
;             __syncthreads();
.Lcp_odd_last:
	ds_read_b128 v[132:135], v77
	ds_read_b128 v[136:139], v77 offset:4352
	ds_read_b128 v[140:143], v77 offset:8704
	ds_read_b128 v[144:147], v77 offset:13056
	ds_read_b128 v[148:151], v77 offset:17408
	ds_read_b128 v[152:155], v77 offset:21760
	ds_read_b128 v[156:159], v77 offset:26112
	ds_read_b128 v[160:163], v77 offset:30464
	ds_read_b128 v[196:199], v77 offset:64
	ds_read_b128 v[200:203], v77 offset:4416
	ds_read_b128 v[204:207], v77 offset:8768
	ds_read_b128 v[208:211], v77 offset:13120
	ds_read_b128 v[212:215], v77 offset:17472
	ds_read_b128 v[216:219], v77 offset:21824
	ds_read_b128 v[220:223], v77 offset:26176
	ds_read_b128 v[224:227], v77 offset:30528
	s_waitcnt vmcnt(0)
	s_waitcnt lgkmcnt(8)
	v_mfma_f32_16x16x32_bf16 v[48:51], v[116:119], v[132:135], v[48:51]
	v_mfma_f32_16x16x32_bf16 v[44:47], v[116:119], v[136:139], v[44:47]
	v_mfma_f32_16x16x32_bf16 v[24:27], v[116:119], v[140:143], v[24:27]
	v_mfma_f32_16x16x32_bf16 v[20:23], v[116:119], v[144:147], v[20:23]
	v_mfma_f32_16x16x32_bf16 v[16:19], v[116:119], v[148:151], v[16:19]
	v_mfma_f32_16x16x32_bf16 v[12:15], v[116:119], v[152:155], v[12:15]
	v_mfma_f32_16x16x32_bf16 v[8:11], v[116:119], v[156:159], v[8:11]
	v_mfma_f32_16x16x32_bf16 v[4:7], v[116:119], v[160:163], v[4:7]
	ds_read_b128 v[132:135], v77 offset:128
	ds_read_b128 v[136:139], v77 offset:4480
	ds_read_b128 v[140:143], v77 offset:8832
	ds_read_b128 v[144:147], v77 offset:13184
	ds_read_b128 v[148:151], v77 offset:17536
	ds_read_b128 v[152:155], v77 offset:21888
	ds_read_b128 v[156:159], v77 offset:26240
	ds_read_b128 v[160:163], v77 offset:30592
	s_waitcnt lgkmcnt(8)
	v_mfma_f32_16x16x32_bf16 v[48:51], v[120:123], v[196:199], v[48:51]
	v_mfma_f32_16x16x32_bf16 v[44:47], v[120:123], v[200:203], v[44:47]
	v_mfma_f32_16x16x32_bf16 v[24:27], v[120:123], v[204:207], v[24:27]
	v_mfma_f32_16x16x32_bf16 v[20:23], v[120:123], v[208:211], v[20:23]
	v_mfma_f32_16x16x32_bf16 v[16:19], v[120:123], v[212:215], v[16:19]
	v_mfma_f32_16x16x32_bf16 v[12:15], v[120:123], v[216:219], v[12:15]
	v_mfma_f32_16x16x32_bf16 v[8:11], v[120:123], v[220:223], v[8:11]
	v_mfma_f32_16x16x32_bf16 v[4:7], v[120:123], v[224:227], v[4:7]
	ds_read_b128 v[196:199], v77 offset:192
	ds_read_b128 v[200:203], v77 offset:4544
	ds_read_b128 v[204:207], v77 offset:8896
	ds_read_b128 v[208:211], v77 offset:13248
	ds_read_b128 v[212:215], v77 offset:17600
	ds_read_b128 v[216:219], v77 offset:21952
	ds_read_b128 v[220:223], v77 offset:26304
	ds_read_b128 v[224:227], v77 offset:30656
	s_waitcnt lgkmcnt(8)
	v_mfma_f32_16x16x32_bf16 v[48:51], v[124:127], v[132:135], v[48:51]
	v_mfma_f32_16x16x32_bf16 v[44:47], v[124:127], v[136:139], v[44:47]
	v_mfma_f32_16x16x32_bf16 v[24:27], v[124:127], v[140:143], v[24:27]
	v_mfma_f32_16x16x32_bf16 v[20:23], v[124:127], v[144:147], v[20:23]
	v_mfma_f32_16x16x32_bf16 v[16:19], v[124:127], v[148:151], v[16:19]
	v_mfma_f32_16x16x32_bf16 v[12:15], v[124:127], v[152:155], v[12:15]
	v_mfma_f32_16x16x32_bf16 v[8:11], v[124:127], v[156:159], v[8:11]
	v_mfma_f32_16x16x32_bf16 v[4:7], v[124:127], v[160:163], v[4:7]
	s_waitcnt lgkmcnt(0)
	v_mfma_f32_16x16x32_bf16 v[48:51], v[244:247], v[196:199], v[48:51]
	v_mfma_f32_16x16x32_bf16 v[44:47], v[244:247], v[200:203], v[44:47]
	v_mfma_f32_16x16x32_bf16 v[24:27], v[244:247], v[204:207], v[24:27]
	v_mfma_f32_16x16x32_bf16 v[20:23], v[244:247], v[208:211], v[20:23]
	v_mfma_f32_16x16x32_bf16 v[16:19], v[244:247], v[212:215], v[16:19]
	v_mfma_f32_16x16x32_bf16 v[12:15], v[244:247], v[216:219], v[12:15]
	v_mfma_f32_16x16x32_bf16 v[8:11], v[244:247], v[220:223], v[8:11]
	v_mfma_f32_16x16x32_bf16 v[4:7], v[244:247], v[224:227], v[4:7]
	s_add_i32 s26, s26, 1
	s_add_u32 s4, s4, 0x100
	s_addc_u32 s5, s5, 0
	s_waitcnt lgkmcnt(0)
	s_barrier
	s_branch .LBB0_1242

; __device__ __forceinline__ float bf2f(bf16 v) { return __uint_as_float(((unsigned)v) << 16); }
; #define GDN_LOADROW(buf, rr_, i_) do { _Pragma("unroll") for (int j4 = 0; j4 < ((i_) + 3) / 4; ++j4) buf[j4] = *(const f32x4*)(Lm + (i_) * GP_LSTR + 4 * j4); rr_ = bf2f(*(const bf16*)(xsrc + (i_) * GP_STR * 2)) * scl[i_]; } while (0)
; template <int STRIP> __device__ __forceinline__ void ph_gdn_prep_fast(const bf16* __restrict__ proj, const float* __restrict__ small, const float* __restrict__ conv_w, const float* __restrict__ a_log, const float* __restrict__ dt_bias, ...
;     ...
;             const int cs = wave >> 2, ci = 2 * pair + cs;
;             unsigned char* L = lds_dyn + cs * GP_CHUNK; const float* sgc = (const float*)(L + GP_SC); const float* sbeta = sgc + 64; const float* segc = sgc + 128; const float* sekd = sgc + 192;
;             const int c = (wave & 3) * 64 + lane; const bool isw = c >= 128; const int cc = c & 127;
;             const unsigned char* xsrc = L + (isw ? GP_K : GP_V) + cc * 2;
;             const float* Lm = (const float*)(L + GP_L);
;             float U[64];
;             const float* scl = isw ? (sgc + 256) : sbeta;
;             f32x4 bA[16], bB[16]; float rA, rB = 0.f;
;             rA = bf2f(*(const bf16*)xsrc) * scl[0];
;     ...
; #pragma unroll
;             for (int i = 0; i < 64; i += 2) {
;                 GDN_LOADROW(bB, rB, i + 1);
;                 GDN_ROW(bA, rA, i);
;                 if (i + 2 < 64) GDN_LOADROW(bA, rA, i + 2);
;                 GDN_ROW(bB, rB, i + 1);
;             }
.LBB0_1303:
	s_or_b64 exec, exec, s[8:9]
	v_ashrrev_i32_e32 v8, 8, v78
	s_mov_b32 s0, 0x11500
	v_and_b32_e32 v4, 0x80, v78
	v_and_b32_e32 v2, 0x80, v78
	v_mad_i32_i24 v10, v8, s0, 0
	v_cmp_ne_u32_e32 vcc, 0, v2
	v_and_b32_e32 v2, 0x7f, v78
	v_cmp_eq_u32_e64 s[0:1], 0, v4
	v_mov_b32_e32 v4, 0x8800
	v_lshlrev_b32_e32 v18, 1, v2
	v_cndmask_b32_e64 v4, v236, v4, s[0:1]
	s_waitcnt lgkmcnt(0)
	s_barrier
	v_add3_u32 v123, v10, v4, v18
	v_mov_b32_e32 v126, 0x11400
	v_mov_b32_e32 v127, 0x11100
	v_and_b32_e32 v125, 3, v78
	v_cndmask_b32_e64 v126, v126, v127, s[0:1]
	v_lshlrev_b32_e32 v125, 3, v125
	v_add_u32_e32 v124, v10, v126
	v_add_u32_e32 v125, 0xcc00, v125
	v_add_u32_e32 v125, v10, v125
	v_mov_b32_e32 v244, 0
	v_mov_b32_e32 v245, 0
	v_mov_b32_e32 v246, 0
	v_mov_b32_e32 v247, 0
	v_mov_b32_e32 v248, 0
	v_mov_b32_e32 v249, 0
	v_mov_b32_e32 v250, 0
	v_mov_b32_e32 v251, 0
	v_mov_b32_e32 v252, 0
	v_mov_b32_e32 v253, 0
	v_mov_b32_e32 v126, 0
	v_mov_b32_e32 v127, 0
	ds_read_b32 v208, v124 offset:0
	ds_read_u16_d16_hi v244, v123 offset:0
	ds_read_b64 v[132:133], v125 offset:272
	ds_read_b32 v209, v124 offset:4
	ds_read_u16_d16_hi v245, v123 offset:272
	ds_read_b64 v[134:135], v125 offset:544
	ds_read_b32 v210, v124 offset:8
	ds_read_u16_d16_hi v246, v123 offset:544
	ds_read_b64 v[136:137], v125 offset:816
	ds_read_b32 v211, v124 offset:12
	ds_read_u16_d16_hi v247, v123 offset:816
	ds_read_b64 v[138:139], v125 offset:1088
	ds_read_b32 v212, v124 offset:16
	ds_read_u16_d16_hi v248, v123 offset:1088
	ds_read_b64 v[140:141], v125 offset:1360
	ds_read_b32 v213, v124 offset:20
	ds_read_u16_d16_hi v249, v123 offset:1360
	ds_read_b64 v[142:143], v125 offset:1632
	ds_read_b32 v214, v124 offset:24
	ds_read_u16_d16_hi v250, v123 offset:1632
	ds_read_b64 v[144:145], v125 offset:1904
	ds_read_b32 v215, v124 offset:28
	ds_read_u16_d16_hi v251, v123 offset:1904
	ds_read_b64 v[146:147], v125 offset:2176
	ds_read_b32 v216, v124 offset:32
	ds_read_u16_d16_hi v252, v123 offset:2176
	ds_read_b64 v[148:149], v125 offset:2448
	ds_read_b64 v[150:151], v125 offset:2480
	ds_read_b32 v217, v124 offset:36
	ds_read_u16_d16_hi v253, v123 offset:2448
	ds_read_b64 v[152:153], v125 offset:2720
	ds_read_b64 v[154:155], v125 offset:2752
	ds_read_b32 v218, v124 offset:40
	ds_read_u16_d16_hi v126, v123 offset:2720
	s_waitcnt lgkmcnt(15)
	v_fma_f32 v4, v208, v244, 0
	s_waitcnt lgkmcnt(15)
	v_mul_f32_dpp v120, v132, v4 quad_perm:[0,0,0,0] row_mask:0xf bank_mask:0xf
	v_fma_f32 v116, v209, v245, -v120
	v_add_f32_e32 v5, 0, v116
	s_waitcnt lgkmcnt(15)
	v_mul_f32_dpp v120, v134, v4 quad_perm:[0,0,0,0] row_mask:0xf bank_mask:0xf
	v_fma_f32 v116, v210, v246, -v120
	v_mul_f32_dpp v117, -v135, v5 quad_perm:[0,0,0,0] row_mask:0xf bank_mask:0xf
	v_add_f32_e32 v6, v117, v116
	s_waitcnt lgkmcnt(15)
	v_mul_f32_dpp v120, v136, v4 quad_perm:[0,0,0,0] row_mask:0xf bank_mask:0xf
	v_fma_f32 v116, v211, v247, -v120
	v_mul_f32_dpp v117, -v137, v5 quad_perm:[0,0,0,0] row_mask:0xf bank_mask:0xf
	v_mul_f32_dpp v118, -v136, v6 quad_perm:[1,1,1,1] row_mask:0xf bank_mask:0xf
	v_add_f32_e32 v121, v117, v116
	v_add_f32_e32 v12, v118, v121
	s_waitcnt lgkmcnt(15)
	v_mul_f32_dpp v120, v138, v4 quad_perm:[0,0,0,0] row_mask:0xf bank_mask:0xf
	v_fma_f32 v116, v212, v248, -v120
	v_mul_f32_dpp v117, -v139, v5 quad_perm:[0,0,0,0] row_mask:0xf bank_mask:0xf
	v_mul_f32_dpp v118, -v138, v6 quad_perm:[1,1,1,1] row_mask:0xf bank_mask:0xf
	v_mul_f32_dpp v119, -v139, v12 quad_perm:[1,1,1,1] row_mask:0xf bank_mask:0xf
	ds_read_b64 v[156:157], v125 offset:2992
	v_add_f32_e32 v121, v117, v116
	v_add_f32_e32 v122, v118, v119
	v_add_f32_e32 v7, v122, v121
	s_waitcnt lgkmcnt(15)
	v_mul_f32_dpp v120, v140, v4 quad_perm:[0,0,0,0] row_mask:0xf bank_mask:0xf
	v_fma_f32 v116, v213, v249, -v120
	v_mul_f32_dpp v117, -v141, v5 quad_perm:[0,0,0,0] row_mask:0xf bank_mask:0xf
	v_mul_f32_dpp v118, -v140, v6 quad_perm:[1,1,1,1] row_mask:0xf bank_mask:0xf
	v_mul_f32_dpp v119, -v141, v12 quad_perm:[1,1,1,1] row_mask:0xf bank_mask:0xf
	ds_read_b64 v[158:159], v125 offset:3024
	v_fmac_f32_dpp v116, -v140, v7 quad_perm:[2,2,2,2] row_mask:0xf bank_mask:0xf
	v_add_f32_e32 v121, v117, v116
	v_add_f32_e32 v122, v118, v119
	v_add_f32_e32 v13, v122, v121
	s_waitcnt lgkmcnt(15)
	v_mul_f32_dpp v120, v142, v4 quad_perm:[0,0,0,0] row_mask:0xf bank_mask:0xf
	v_fma_f32 v116, v214, v250, -v120
	v_mul_f32_dpp v117, -v143, v5 quad_perm:[0,0,0,0] row_mask:0xf bank_mask:0xf
	v_mul_f32_dpp v118, -v142, v6 quad_perm:[1,1,1,1] row_mask:0xf bank_mask:0xf
	v_mul_f32_dpp v119, -v143, v12 quad_perm:[1,1,1,1] row_mask:0xf bank_mask:0xf
	ds_read_b32 v219, v124 offset:44
	v_fmac_f32_dpp v116, -v142, v7 quad_perm:[2,2,2,2] row_mask:0xf bank_mask:0xf
	v_fmac_f32_dpp v117, -v143, v13 quad_perm:[2,2,2,2] row_mask:0xf bank_mask:0xf
	v_add_f32_e32 v121, v117, v116
	v_add_f32_e32 v122, v118, v119
	v_add_f32_e32 v14, v122, v121
	s_waitcnt lgkmcnt(14)
	v_mul_f32_dpp v120, v144, v4 quad_perm:[0,0,0,0] row_mask:0xf bank_mask:0xf
	v_fma_f32 v116, v215, v251, -v120
	v_mul_f32_dpp v117, -v145, v5 quad_perm:[0,0,0,0] row_mask:0xf bank_mask:0xf
	v_mul_f32_dpp v118, -v144, v6 quad_perm:[1,1,1,1] row_mask:0xf bank_mask:0xf
	v_mul_f32_dpp v119, -v145, v12 quad_perm:[1,1,1,1] row_mask:0xf bank_mask:0xf
	ds_read_u16_d16_hi v127, v123 offset:2992
	v_fmac_f32_dpp v116, -v144, v7 quad_perm:[2,2,2,2] row_mask:0xf bank_mask:0xf
	v_fmac_f32_dpp v117, -v145, v13 quad_perm:[2,2,2,2] row_mask:0xf bank_mask:0xf
	v_fmac_f32_dpp v118, -v144, v14 quad_perm:[3,3,3,3] row_mask:0xf bank_mask:0xf
	ds_read_b64 v[160:161], v125 offset:3264
	v_add_f32_e32 v121, v117, v116
	v_add_f32_e32 v122, v118, v119
	v_add_f32_e32 v15, v122, v121
	s_waitcnt lgkmcnt(13)
; __device__ __forceinline__ float bf2f(bf16 v) { return __uint_as_float(((unsigned)v) << 16); }
; #define GDN_LOADROW(buf, rr_, i_) do { _Pragma("unroll") for (int j4 = 0; j4 < ((i_) + 3) / 4; ++j4) buf[j4] = *(const f32x4*)(Lm + (i_) * GP_LSTR + 4 * j4); rr_ = bf2f(*(const bf16*)(xsrc + (i_) * GP_STR * 2)) * scl[i_]; } while (0)
; template <int STRIP> __device__ __forceinline__ void ph_gdn_prep_fast(const bf16* __restrict__ proj, const float* __restrict__ small, const float* __restrict__ conv_w, const float* __restrict__ a_log, const float* __restrict__ dt_bias, ...
;     ...
;             f32x4 bA[16], bB[16]; float rA, rB = 0.f;
;             rA = bf2f(*(const bf16*)xsrc) * scl[0];
;     ...
; #pragma unroll
;             for (int i = 0; i < 64; i += 2) {
;                 GDN_LOADROW(bB, rB, i + 1);
;                 GDN_ROW(bA, rA, i);
;                 if (i + 2 < 64) GDN_LOADROW(bA, rA, i + 2);
;                 GDN_ROW(bB, rB, i + 1);
;             }
	v_mul_f32_dpp v120, v146, v4 quad_perm:[0,0,0,0] row_mask:0xf bank_mask:0xf
	v_fma_f32 v116, v216, v252, -v120
	v_mul_f32_dpp v117, -v147, v5 quad_perm:[0,0,0,0] row_mask:0xf bank_mask:0xf
	v_mul_f32_dpp v118, -v146, v6 quad_perm:[1,1,1,1] row_mask:0xf bank_mask:0xf
	v_mul_f32_dpp v119, -v147, v12 quad_perm:[1,1,1,1] row_mask:0xf bank_mask:0xf
	ds_read_b64 v[162:163], v125 offset:3296
	v_fmac_f32_dpp v116, -v146, v7 quad_perm:[2,2,2,2] row_mask:0xf bank_mask:0xf
	v_fmac_f32_dpp v117, -v147, v13 quad_perm:[2,2,2,2] row_mask:0xf bank_mask:0xf
	v_fmac_f32_dpp v118, -v146, v14 quad_perm:[3,3,3,3] row_mask:0xf bank_mask:0xf
	ds_read_b32 v220, v124 offset:48
	v_fmac_f32_dpp v119, -v147, v15 quad_perm:[3,3,3,3] row_mask:0xf bank_mask:0xf
	v_add_f32_e32 v121, v117, v116
	v_add_f32_e32 v122, v118, v119
	v_add_f32_e32 v16, v122, v121
	s_waitcnt lgkmcnt(11)
	v_mul_f32_dpp v120, v148, v4 quad_perm:[0,0,0,0] row_mask:0xf bank_mask:0xf
	v_fma_f32 v116, v217, v253, -v120
	v_mul_f32_dpp v117, -v149, v5 quad_perm:[0,0,0,0] row_mask:0xf bank_mask:0xf
	v_mul_f32_dpp v118, -v148, v6 quad_perm:[1,1,1,1] row_mask:0xf bank_mask:0xf
	v_mul_f32_dpp v119, -v149, v12 quad_perm:[1,1,1,1] row_mask:0xf bank_mask:0xf
	ds_read_u16_d16_hi v244, v123 offset:3264
	v_fmac_f32_dpp v116, -v148, v7 quad_perm:[2,2,2,2] row_mask:0xf bank_mask:0xf
	v_fmac_f32_dpp v117, -v149, v13 quad_perm:[2,2,2,2] row_mask:0xf bank_mask:0xf
	v_fmac_f32_dpp v118, -v148, v14 quad_perm:[3,3,3,3] row_mask:0xf bank_mask:0xf
	ds_read_b64 v[164:165], v125 offset:3536
	v_fmac_f32_dpp v119, -v149, v15 quad_perm:[3,3,3,3] row_mask:0xf bank_mask:0xf
	v_fmac_f32_dpp v116, -v150, v16 quad_perm:[0,0,0,0] row_mask:0xf bank_mask:0xf
	v_add_f32_e32 v121, v117, v116
	v_add_f32_e32 v122, v118, v119
	v_add_f32_e32 v17, v122, v121
	s_waitcnt lgkmcnt(9)
	v_mul_f32_dpp v120, v152, v4 quad_perm:[0,0,0,0] row_mask:0xf bank_mask:0xf
	v_fma_f32 v116, v218, v126, -v120
	v_mul_f32_dpp v117, -v153, v5 quad_perm:[0,0,0,0] row_mask:0xf bank_mask:0xf
	v_mul_f32_dpp v118, -v152, v6 quad_perm:[1,1,1,1] row_mask:0xf bank_mask:0xf
	v_mul_f32_dpp v119, -v153, v12 quad_perm:[1,1,1,1] row_mask:0xf bank_mask:0xf
	ds_read_b64 v[166:167], v125 offset:3568
	v_fmac_f32_dpp v116, -v152, v7 quad_perm:[2,2,2,2] row_mask:0xf bank_mask:0xf
	v_fmac_f32_dpp v117, -v153, v13 quad_perm:[2,2,2,2] row_mask:0xf bank_mask:0xf
	v_fmac_f32_dpp v118, -v152, v14 quad_perm:[3,3,3,3] row_mask:0xf bank_mask:0xf
	ds_read_b32 v221, v124 offset:52
	v_fmac_f32_dpp v119, -v153, v15 quad_perm:[3,3,3,3] row_mask:0xf bank_mask:0xf
	v_fmac_f32_dpp v116, -v154, v16 quad_perm:[0,0,0,0] row_mask:0xf bank_mask:0xf
	v_fmac_f32_dpp v117, -v155, v17 quad_perm:[0,0,0,0] row_mask:0xf bank_mask:0xf
	ds_read_u16_d16_hi v245, v123 offset:3536
	v_add_f32_e32 v121, v117, v116
	v_add_f32_e32 v122, v118, v119
	v_add_f32_e32 v19, v122, v121
	s_waitcnt lgkmcnt(8)
	v_mul_f32_dpp v120, v156, v4 quad_perm:[0,0,0,0] row_mask:0xf bank_mask:0xf
	v_fma_f32 v116, v219, v127, -v120
	v_mul_f32_dpp v117, -v157, v5 quad_perm:[0,0,0,0] row_mask:0xf bank_mask:0xf
	v_mul_f32_dpp v118, -v156, v6 quad_perm:[1,1,1,1] row_mask:0xf bank_mask:0xf
	v_mul_f32_dpp v119, -v157, v12 quad_perm:[1,1,1,1] row_mask:0xf bank_mask:0xf
	ds_read_b64 v[168:169], v125 offset:3808
	v_fmac_f32_dpp v116, -v156, v7 quad_perm:[2,2,2,2] row_mask:0xf bank_mask:0xf
	v_fmac_f32_dpp v117, -v157, v13 quad_perm:[2,2,2,2] row_mask:0xf bank_mask:0xf
	v_fmac_f32_dpp v118, -v156, v14 quad_perm:[3,3,3,3] row_mask:0xf bank_mask:0xf
	ds_read_b64 v[170:171], v125 offset:3840
	v_fmac_f32_dpp v119, -v157, v15 quad_perm:[3,3,3,3] row_mask:0xf bank_mask:0xf
	v_fmac_f32_dpp v116, -v158, v16 quad_perm:[0,0,0,0] row_mask:0xf bank_mask:0xf
	v_fmac_f32_dpp v117, -v159, v17 quad_perm:[0,0,0,0] row_mask:0xf bank_mask:0xf
	ds_read_b32 v222, v124 offset:56
	v_fmac_f32_dpp v118, -v158, v19 quad_perm:[1,1,1,1] row_mask:0xf bank_mask:0xf
	v_add_f32_e32 v121, v117, v116
	v_add_f32_e32 v122, v118, v119
	v_add_f32_e32 v20, v122, v121
	s_waitcnt lgkmcnt(7)
	v_mul_f32_dpp v120, v160, v4 quad_perm:[0,0,0,0] row_mask:0xf bank_mask:0xf
	v_fma_f32 v116, v220, v244, -v120
	v_mul_f32_dpp v117, -v161, v5 quad_perm:[0,0,0,0] row_mask:0xf bank_mask:0xf
	v_mul_f32_dpp v118, -v160, v6 quad_perm:[1,1,1,1] row_mask:0xf bank_mask:0xf
	v_mul_f32_dpp v119, -v161, v12 quad_perm:[1,1,1,1] row_mask:0xf bank_mask:0xf
	ds_read_u16_d16_hi v246, v123 offset:3808
	v_fmac_f32_dpp v116, -v160, v7 quad_perm:[2,2,2,2] row_mask:0xf bank_mask:0xf
	v_fmac_f32_dpp v117, -v161, v13 quad_perm:[2,2,2,2] row_mask:0xf bank_mask:0xf
	v_fmac_f32_dpp v118, -v160, v14 quad_perm:[3,3,3,3] row_mask:0xf bank_mask:0xf
	ds_read_b64 v[172:173], v125 offset:4080
	v_fmac_f32_dpp v119, -v161, v15 quad_perm:[3,3,3,3] row_mask:0xf bank_mask:0xf
	v_fmac_f32_dpp v116, -v162, v16 quad_perm:[0,0,0,0] row_mask:0xf bank_mask:0xf
	v_fmac_f32_dpp v117, -v163, v17 quad_perm:[0,0,0,0] row_mask:0xf bank_mask:0xf
	ds_read_b64 v[174:175], v125 offset:4112
	v_fmac_f32_dpp v118, -v162, v19 quad_perm:[1,1,1,1] row_mask:0xf bank_mask:0xf
	v_fmac_f32_dpp v119, -v163, v20 quad_perm:[1,1,1,1] row_mask:0xf bank_mask:0xf
	v_add_f32_e32 v121, v117, v116
	v_add_f32_e32 v122, v118, v119
	v_add_f32_e32 v21, v122, v121
	s_waitcnt lgkmcnt(6)
; __device__ __forceinline__ float bf2f(bf16 v) { return __uint_as_float(((unsigned)v) << 16); }
; #define GDN_LOADROW(buf, rr_, i_) do { _Pragma("unroll") for (int j4 = 0; j4 < ((i_) + 3) / 4; ++j4) buf[j4] = *(const f32x4*)(Lm + (i_) * GP_LSTR + 4 * j4); rr_ = bf2f(*(const bf16*)(xsrc + (i_) * GP_STR * 2)) * scl[i_]; } while (0)
; template <int STRIP> __device__ __forceinline__ void ph_gdn_prep_fast(const bf16* __restrict__ proj, const float* __restrict__ small, const float* __restrict__ conv_w, const float* __restrict__ a_log, const float* __restrict__ dt_bias, ...
;     ...
;             f32x4 bA[16], bB[16]; float rA, rB = 0.f;
;             rA = bf2f(*(const bf16*)xsrc) * scl[0];
;     ...
; #pragma unroll
;             for (int i = 0; i < 64; i += 2) {
;                 GDN_LOADROW(bB, rB, i + 1);
;                 GDN_ROW(bA, rA, i);
;                 if (i + 2 < 64) GDN_LOADROW(bA, rA, i + 2);
;                 GDN_ROW(bB, rB, i + 1);
;             }
	v_mul_f32_dpp v120, v164, v4 quad_perm:[0,0,0,0] row_mask:0xf bank_mask:0xf
	v_fma_f32 v116, v221, v245, -v120
	v_mul_f32_dpp v117, -v165, v5 quad_perm:[0,0,0,0] row_mask:0xf bank_mask:0xf
	v_mul_f32_dpp v118, -v164, v6 quad_perm:[1,1,1,1] row_mask:0xf bank_mask:0xf
	v_mul_f32_dpp v119, -v165, v12 quad_perm:[1,1,1,1] row_mask:0xf bank_mask:0xf
	ds_read_b32 v223, v124 offset:60
	v_fmac_f32_dpp v116, -v164, v7 quad_perm:[2,2,2,2] row_mask:0xf bank_mask:0xf
	v_fmac_f32_dpp v117, -v165, v13 quad_perm:[2,2,2,2] row_mask:0xf bank_mask:0xf
	v_fmac_f32_dpp v118, -v164, v14 quad_perm:[3,3,3,3] row_mask:0xf bank_mask:0xf
	ds_read_u16_d16_hi v247, v123 offset:4080
	v_fmac_f32_dpp v119, -v165, v15 quad_perm:[3,3,3,3] row_mask:0xf bank_mask:0xf
	v_fmac_f32_dpp v116, -v166, v16 quad_perm:[0,0,0,0] row_mask:0xf bank_mask:0xf
	v_fmac_f32_dpp v117, -v167, v17 quad_perm:[0,0,0,0] row_mask:0xf bank_mask:0xf
	ds_read_b64 v[176:177], v125 offset:4352
	v_fmac_f32_dpp v118, -v166, v19 quad_perm:[1,1,1,1] row_mask:0xf bank_mask:0xf
	v_fmac_f32_dpp v119, -v167, v20 quad_perm:[1,1,1,1] row_mask:0xf bank_mask:0xf
	v_fmac_f32_dpp v116, -v166, v21 quad_perm:[2,2,2,2] row_mask:0xf bank_mask:0xf
	ds_read_b64 v[178:179], v125 offset:4384
	v_add_f32_e32 v121, v117, v116
	v_add_f32_e32 v122, v118, v119
	v_add_f32_e32 v22, v122, v121
	s_waitcnt lgkmcnt(6)
	v_mul_f32_dpp v120, v168, v4 quad_perm:[0,0,0,0] row_mask:0xf bank_mask:0xf
	v_fma_f32 v116, v222, v246, -v120
	v_mul_f32_dpp v117, -v169, v5 quad_perm:[0,0,0,0] row_mask:0xf bank_mask:0xf
	v_mul_f32_dpp v118, -v168, v6 quad_perm:[1,1,1,1] row_mask:0xf bank_mask:0xf
	v_mul_f32_dpp v119, -v169, v12 quad_perm:[1,1,1,1] row_mask:0xf bank_mask:0xf
	ds_read_b32 v224, v124 offset:64
	v_fmac_f32_dpp v116, -v168, v7 quad_perm:[2,2,2,2] row_mask:0xf bank_mask:0xf
	v_fmac_f32_dpp v117, -v169, v13 quad_perm:[2,2,2,2] row_mask:0xf bank_mask:0xf
	v_fmac_f32_dpp v118, -v168, v14 quad_perm:[3,3,3,3] row_mask:0xf bank_mask:0xf
	ds_read_u16_d16_hi v248, v123 offset:4352
	v_fmac_f32_dpp v119, -v169, v15 quad_perm:[3,3,3,3] row_mask:0xf bank_mask:0xf
	v_fmac_f32_dpp v116, -v170, v16 quad_perm:[0,0,0,0] row_mask:0xf bank_mask:0xf
	v_fmac_f32_dpp v117, -v171, v17 quad_perm:[0,0,0,0] row_mask:0xf bank_mask:0xf
	ds_read_b64 v[186:187], v125 offset:4624
	v_fmac_f32_dpp v118, -v170, v19 quad_perm:[1,1,1,1] row_mask:0xf bank_mask:0xf
	v_fmac_f32_dpp v119, -v171, v20 quad_perm:[1,1,1,1] row_mask:0xf bank_mask:0xf
	v_fmac_f32_dpp v116, -v170, v21 quad_perm:[2,2,2,2] row_mask:0xf bank_mask:0xf
	ds_read_b64 v[188:189], v125 offset:4656
	v_fmac_f32_dpp v117, -v171, v22 quad_perm:[2,2,2,2] row_mask:0xf bank_mask:0xf
	v_add_f32_e32 v121, v117, v116
	v_add_f32_e32 v122, v118, v119
	v_add_f32_e32 v23, v122, v121
	s_waitcnt lgkmcnt(6)
	v_mul_f32_dpp v120, v172, v4 quad_perm:[0,0,0,0] row_mask:0xf bank_mask:0xf
	v_fma_f32 v116, v223, v247, -v120
	v_mul_f32_dpp v117, -v173, v5 quad_perm:[0,0,0,0] row_mask:0xf bank_mask:0xf
	v_mul_f32_dpp v118, -v172, v6 quad_perm:[1,1,1,1] row_mask:0xf bank_mask:0xf
	v_mul_f32_dpp v119, -v173, v12 quad_perm:[1,1,1,1] row_mask:0xf bank_mask:0xf
	ds_read_b64 v[190:191], v125 offset:4688
	v_fmac_f32_dpp v116, -v172, v7 quad_perm:[2,2,2,2] row_mask:0xf bank_mask:0xf
	v_fmac_f32_dpp v117, -v173, v13 quad_perm:[2,2,2,2] row_mask:0xf bank_mask:0xf
	v_fmac_f32_dpp v118, -v172, v14 quad_perm:[3,3,3,3] row_mask:0xf bank_mask:0xf
	ds_read_b32 v225, v124 offset:68
	v_fmac_f32_dpp v119, -v173, v15 quad_perm:[3,3,3,3] row_mask:0xf bank_mask:0xf
	v_fmac_f32_dpp v116, -v174, v16 quad_perm:[0,0,0,0] row_mask:0xf bank_mask:0xf
	v_fmac_f32_dpp v117, -v175, v17 quad_perm:[0,0,0,0] row_mask:0xf bank_mask:0xf
	ds_read_u16_d16_hi v249, v123 offset:4624
	v_fmac_f32_dpp v118, -v174, v19 quad_perm:[1,1,1,1] row_mask:0xf bank_mask:0xf
	v_fmac_f32_dpp v119, -v175, v20 quad_perm:[1,1,1,1] row_mask:0xf bank_mask:0xf
	v_fmac_f32_dpp v116, -v174, v21 quad_perm:[2,2,2,2] row_mask:0xf bank_mask:0xf
	ds_read_b64 v[192:193], v125 offset:4896
	v_fmac_f32_dpp v117, -v175, v22 quad_perm:[2,2,2,2] row_mask:0xf bank_mask:0xf
	v_fmac_f32_dpp v118, -v174, v23 quad_perm:[3,3,3,3] row_mask:0xf bank_mask:0xf
	v_add_f32_e32 v121, v117, v116
	v_add_f32_e32 v122, v118, v119
	v_add_f32_e32 v24, v122, v121
	s_waitcnt lgkmcnt(6)
	v_mul_f32_dpp v120, v176, v4 quad_perm:[0,0,0,0] row_mask:0xf bank_mask:0xf
	v_fma_f32 v116, v224, v248, -v120
	v_mul_f32_dpp v117, -v177, v5 quad_perm:[0,0,0,0] row_mask:0xf bank_mask:0xf
	v_mul_f32_dpp v118, -v176, v6 quad_perm:[1,1,1,1] row_mask:0xf bank_mask:0xf
	v_mul_f32_dpp v119, -v177, v12 quad_perm:[1,1,1,1] row_mask:0xf bank_mask:0xf
	ds_read_b64 v[194:195], v125 offset:4928
	v_fmac_f32_dpp v116, -v176, v7 quad_perm:[2,2,2,2] row_mask:0xf bank_mask:0xf
	v_fmac_f32_dpp v117, -v177, v13 quad_perm:[2,2,2,2] row_mask:0xf bank_mask:0xf
	v_fmac_f32_dpp v118, -v176, v14 quad_perm:[3,3,3,3] row_mask:0xf bank_mask:0xf
	ds_read_b64 v[196:197], v125 offset:4960
	v_fmac_f32_dpp v119, -v177, v15 quad_perm:[3,3,3,3] row_mask:0xf bank_mask:0xf
	v_fmac_f32_dpp v116, -v178, v16 quad_perm:[0,0,0,0] row_mask:0xf bank_mask:0xf
	v_fmac_f32_dpp v117, -v179, v17 quad_perm:[0,0,0,0] row_mask:0xf bank_mask:0xf
	ds_read_b32 v226, v124 offset:72
	v_fmac_f32_dpp v118, -v178, v19 quad_perm:[1,1,1,1] row_mask:0xf bank_mask:0xf
	v_fmac_f32_dpp v119, -v179, v20 quad_perm:[1,1,1,1] row_mask:0xf bank_mask:0xf
	v_fmac_f32_dpp v116, -v178, v21 quad_perm:[2,2,2,2] row_mask:0xf bank_mask:0xf
	ds_read_u16_d16_hi v250, v123 offset:4896
	v_fmac_f32_dpp v117, -v179, v22 quad_perm:[2,2,2,2] row_mask:0xf bank_mask:0xf
	v_fmac_f32_dpp v118, -v178, v23 quad_perm:[3,3,3,3] row_mask:0xf bank_mask:0xf
	v_fmac_f32_dpp v119, -v179, v24 quad_perm:[3,3,3,3] row_mask:0xf bank_mask:0xf
	ds_read_b64 v[198:199], v125 offset:5168
	v_add_f32_e32 v121, v117, v116
	v_add_f32_e32 v122, v118, v119
	v_add_f32_e32 v25, v122, v121
	s_waitcnt lgkmcnt(6)
; __device__ __forceinline__ float bf2f(bf16 v) { return __uint_as_float(((unsigned)v) << 16); }
; #define GDN_LOADROW(buf, rr_, i_) do { _Pragma("unroll") for (int j4 = 0; j4 < ((i_) + 3) / 4; ++j4) buf[j4] = *(const f32x4*)(Lm + (i_) * GP_LSTR + 4 * j4); rr_ = bf2f(*(const bf16*)(xsrc + (i_) * GP_STR * 2)) * scl[i_]; } while (0)
; template <int STRIP> __device__ __forceinline__ void ph_gdn_prep_fast(const bf16* __restrict__ proj, const float* __restrict__ small, const float* __restrict__ conv_w, const float* __restrict__ a_log, const float* __restrict__ dt_bias, ...
;     ...
;             f32x4 bA[16], bB[16]; float rA, rB = 0.f;
;             rA = bf2f(*(const bf16*)xsrc) * scl[0];
;     ...
; #pragma unroll
;             for (int i = 0; i < 64; i += 2) {
;                 GDN_LOADROW(bB, rB, i + 1);
;                 GDN_ROW(bA, rA, i);
;                 if (i + 2 < 64) GDN_LOADROW(bA, rA, i + 2);
;                 GDN_ROW(bB, rB, i + 1);
;             }
	v_mul_f32_dpp v120, v186, v4 quad_perm:[0,0,0,0] row_mask:0xf bank_mask:0xf
	v_fma_f32 v116, v225, v249, -v120
	v_mul_f32_dpp v117, -v187, v5 quad_perm:[0,0,0,0] row_mask:0xf bank_mask:0xf
	v_mul_f32_dpp v118, -v186, v6 quad_perm:[1,1,1,1] row_mask:0xf bank_mask:0xf
	v_mul_f32_dpp v119, -v187, v12 quad_perm:[1,1,1,1] row_mask:0xf bank_mask:0xf
	ds_read_b64 v[200:201], v125 offset:5200
	v_fmac_f32_dpp v116, -v186, v7 quad_perm:[2,2,2,2] row_mask:0xf bank_mask:0xf
	v_fmac_f32_dpp v117, -v187, v13 quad_perm:[2,2,2,2] row_mask:0xf bank_mask:0xf
	v_fmac_f32_dpp v118, -v186, v14 quad_perm:[3,3,3,3] row_mask:0xf bank_mask:0xf
	ds_read_b64 v[202:203], v125 offset:5232
	v_fmac_f32_dpp v119, -v187, v15 quad_perm:[3,3,3,3] row_mask:0xf bank_mask:0xf
	v_fmac_f32_dpp v116, -v188, v16 quad_perm:[0,0,0,0] row_mask:0xf bank_mask:0xf
	v_fmac_f32_dpp v117, -v189, v17 quad_perm:[0,0,0,0] row_mask:0xf bank_mask:0xf
	ds_read_b32 v227, v124 offset:76
	v_fmac_f32_dpp v118, -v188, v19 quad_perm:[1,1,1,1] row_mask:0xf bank_mask:0xf
	v_fmac_f32_dpp v119, -v189, v20 quad_perm:[1,1,1,1] row_mask:0xf bank_mask:0xf
	v_fmac_f32_dpp v116, -v188, v21 quad_perm:[2,2,2,2] row_mask:0xf bank_mask:0xf
	ds_read_u16_d16_hi v251, v123 offset:5168
	v_fmac_f32_dpp v117, -v189, v22 quad_perm:[2,2,2,2] row_mask:0xf bank_mask:0xf
	v_fmac_f32_dpp v118, -v188, v23 quad_perm:[3,3,3,3] row_mask:0xf bank_mask:0xf
	v_fmac_f32_dpp v119, -v189, v24 quad_perm:[3,3,3,3] row_mask:0xf bank_mask:0xf
	ds_read_b64 v[204:205], v125 offset:5440
	v_fmac_f32_dpp v116, -v190, v25 quad_perm:[0,0,0,0] row_mask:0xf bank_mask:0xf
	v_add_f32_e32 v121, v117, v116
	v_add_f32_e32 v122, v118, v119
	v_add_f32_e32 v27, v122, v121
	s_waitcnt lgkmcnt(6)
	v_mul_f32_dpp v120, v192, v4 quad_perm:[0,0,0,0] row_mask:0xf bank_mask:0xf
	v_fma_f32 v116, v226, v250, -v120
	v_mul_f32_dpp v117, -v193, v5 quad_perm:[0,0,0,0] row_mask:0xf bank_mask:0xf
	v_mul_f32_dpp v118, -v192, v6 quad_perm:[1,1,1,1] row_mask:0xf bank_mask:0xf
	v_mul_f32_dpp v119, -v193, v12 quad_perm:[1,1,1,1] row_mask:0xf bank_mask:0xf
	ds_read_b64 v[206:207], v125 offset:5472
	v_fmac_f32_dpp v116, -v192, v7 quad_perm:[2,2,2,2] row_mask:0xf bank_mask:0xf
	v_fmac_f32_dpp v117, -v193, v13 quad_perm:[2,2,2,2] row_mask:0xf bank_mask:0xf
	v_fmac_f32_dpp v118, -v192, v14 quad_perm:[3,3,3,3] row_mask:0xf bank_mask:0xf
	ds_read_b64 v[132:133], v125 offset:5504
	v_fmac_f32_dpp v119, -v193, v15 quad_perm:[3,3,3,3] row_mask:0xf bank_mask:0xf
	v_fmac_f32_dpp v116, -v194, v16 quad_perm:[0,0,0,0] row_mask:0xf bank_mask:0xf
	v_fmac_f32_dpp v117, -v195, v17 quad_perm:[0,0,0,0] row_mask:0xf bank_mask:0xf
	ds_read_b32 v228, v124 offset:80
	v_fmac_f32_dpp v118, -v194, v19 quad_perm:[1,1,1,1] row_mask:0xf bank_mask:0xf
	v_fmac_f32_dpp v119, -v195, v20 quad_perm:[1,1,1,1] row_mask:0xf bank_mask:0xf
	v_fmac_f32_dpp v116, -v194, v21 quad_perm:[2,2,2,2] row_mask:0xf bank_mask:0xf
	ds_read_u16_d16_hi v252, v123 offset:5440
	v_fmac_f32_dpp v117, -v195, v22 quad_perm:[2,2,2,2] row_mask:0xf bank_mask:0xf
	v_fmac_f32_dpp v118, -v194, v23 quad_perm:[3,3,3,3] row_mask:0xf bank_mask:0xf
	v_fmac_f32_dpp v119, -v195, v24 quad_perm:[3,3,3,3] row_mask:0xf bank_mask:0xf
	ds_read_b64 v[134:135], v125 offset:5712
	v_fmac_f32_dpp v116, -v196, v25 quad_perm:[0,0,0,0] row_mask:0xf bank_mask:0xf
	v_fmac_f32_dpp v117, -v197, v27 quad_perm:[0,0,0,0] row_mask:0xf bank_mask:0xf
	v_add_f32_e32 v121, v117, v116
	v_add_f32_e32 v122, v118, v119
	v_add_f32_e32 v28, v122, v121
	s_waitcnt lgkmcnt(6)
	v_mul_f32_dpp v120, v198, v4 quad_perm:[0,0,0,0] row_mask:0xf bank_mask:0xf
	v_fma_f32 v116, v227, v251, -v120
	v_mul_f32_dpp v117, -v199, v5 quad_perm:[0,0,0,0] row_mask:0xf bank_mask:0xf
	v_mul_f32_dpp v118, -v198, v6 quad_perm:[1,1,1,1] row_mask:0xf bank_mask:0xf
	v_mul_f32_dpp v119, -v199, v12 quad_perm:[1,1,1,1] row_mask:0xf bank_mask:0xf
	ds_read_b64 v[136:137], v125 offset:5744
	v_fmac_f32_dpp v116, -v198, v7 quad_perm:[2,2,2,2] row_mask:0xf bank_mask:0xf
	v_fmac_f32_dpp v117, -v199, v13 quad_perm:[2,2,2,2] row_mask:0xf bank_mask:0xf
	v_fmac_f32_dpp v118, -v198, v14 quad_perm:[3,3,3,3] row_mask:0xf bank_mask:0xf
	ds_read_b64 v[138:139], v125 offset:5776
	v_fmac_f32_dpp v119, -v199, v15 quad_perm:[3,3,3,3] row_mask:0xf bank_mask:0xf
	v_fmac_f32_dpp v116, -v200, v16 quad_perm:[0,0,0,0] row_mask:0xf bank_mask:0xf
	v_fmac_f32_dpp v117, -v201, v17 quad_perm:[0,0,0,0] row_mask:0xf bank_mask:0xf
	ds_read_b32 v229, v124 offset:84
	v_fmac_f32_dpp v118, -v200, v19 quad_perm:[1,1,1,1] row_mask:0xf bank_mask:0xf
	v_fmac_f32_dpp v119, -v201, v20 quad_perm:[1,1,1,1] row_mask:0xf bank_mask:0xf
	v_fmac_f32_dpp v116, -v200, v21 quad_perm:[2,2,2,2] row_mask:0xf bank_mask:0xf
	ds_read_u16_d16_hi v253, v123 offset:5712
	v_fmac_f32_dpp v117, -v201, v22 quad_perm:[2,2,2,2] row_mask:0xf bank_mask:0xf
	v_fmac_f32_dpp v118, -v200, v23 quad_perm:[3,3,3,3] row_mask:0xf bank_mask:0xf
	v_fmac_f32_dpp v119, -v201, v24 quad_perm:[3,3,3,3] row_mask:0xf bank_mask:0xf
	ds_read_b64 v[140:141], v125 offset:5984
	v_fmac_f32_dpp v116, -v202, v25 quad_perm:[0,0,0,0] row_mask:0xf bank_mask:0xf
	v_fmac_f32_dpp v117, -v203, v27 quad_perm:[0,0,0,0] row_mask:0xf bank_mask:0xf
	v_fmac_f32_dpp v118, -v202, v28 quad_perm:[1,1,1,1] row_mask:0xf bank_mask:0xf
	ds_read_b64 v[142:143], v125 offset:6016
	v_add_f32_e32 v121, v117, v116
	v_add_f32_e32 v122, v118, v119
	v_add_f32_e32 v29, v122, v121
	s_waitcnt lgkmcnt(7)
; __device__ __forceinline__ float bf2f(bf16 v) { return __uint_as_float(((unsigned)v) << 16); }
; #define GDN_LOADROW(buf, rr_, i_) do { _Pragma("unroll") for (int j4 = 0; j4 < ((i_) + 3) / 4; ++j4) buf[j4] = *(const f32x4*)(Lm + (i_) * GP_LSTR + 4 * j4); rr_ = bf2f(*(const bf16*)(xsrc + (i_) * GP_STR * 2)) * scl[i_]; } while (0)
; template <int STRIP> __device__ __forceinline__ void ph_gdn_prep_fast(const bf16* __restrict__ proj, const float* __restrict__ small, const float* __restrict__ conv_w, const float* __restrict__ a_log, const float* __restrict__ dt_bias, ...
;     ...
;             f32x4 bA[16], bB[16]; float rA, rB = 0.f;
;             rA = bf2f(*(const bf16*)xsrc) * scl[0];
;     ...
; #pragma unroll
;             for (int i = 0; i < 64; i += 2) {
;                 GDN_LOADROW(bB, rB, i + 1);
;                 GDN_ROW(bA, rA, i);
;                 if (i + 2 < 64) GDN_LOADROW(bA, rA, i + 2);
;                 GDN_ROW(bB, rB, i + 1);
;             }
	v_mul_f32_dpp v120, v204, v4 quad_perm:[0,0,0,0] row_mask:0xf bank_mask:0xf
	v_fma_f32 v116, v228, v252, -v120
	v_mul_f32_dpp v117, -v205, v5 quad_perm:[0,0,0,0] row_mask:0xf bank_mask:0xf
	v_mul_f32_dpp v118, -v204, v6 quad_perm:[1,1,1,1] row_mask:0xf bank_mask:0xf
	v_mul_f32_dpp v119, -v205, v12 quad_perm:[1,1,1,1] row_mask:0xf bank_mask:0xf
	ds_read_b64 v[144:145], v125 offset:6048
	v_fmac_f32_dpp v116, -v204, v7 quad_perm:[2,2,2,2] row_mask:0xf bank_mask:0xf
	v_fmac_f32_dpp v117, -v205, v13 quad_perm:[2,2,2,2] row_mask:0xf bank_mask:0xf
	v_fmac_f32_dpp v118, -v204, v14 quad_perm:[3,3,3,3] row_mask:0xf bank_mask:0xf
	ds_read_b32 v181, v124 offset:88
	v_fmac_f32_dpp v119, -v205, v15 quad_perm:[3,3,3,3] row_mask:0xf bank_mask:0xf
	v_fmac_f32_dpp v116, -v206, v16 quad_perm:[0,0,0,0] row_mask:0xf bank_mask:0xf
	v_fmac_f32_dpp v117, -v207, v17 quad_perm:[0,0,0,0] row_mask:0xf bank_mask:0xf
	ds_read_u16_d16_hi v126, v123 offset:5984
	v_fmac_f32_dpp v118, -v206, v19 quad_perm:[1,1,1,1] row_mask:0xf bank_mask:0xf
	v_fmac_f32_dpp v119, -v207, v20 quad_perm:[1,1,1,1] row_mask:0xf bank_mask:0xf
	v_fmac_f32_dpp v116, -v206, v21 quad_perm:[2,2,2,2] row_mask:0xf bank_mask:0xf
	ds_read_b64 v[146:147], v125 offset:6256
	v_fmac_f32_dpp v117, -v207, v22 quad_perm:[2,2,2,2] row_mask:0xf bank_mask:0xf
	v_fmac_f32_dpp v118, -v206, v23 quad_perm:[3,3,3,3] row_mask:0xf bank_mask:0xf
	v_fmac_f32_dpp v119, -v207, v24 quad_perm:[3,3,3,3] row_mask:0xf bank_mask:0xf
	ds_read_b64 v[148:149], v125 offset:6288
	v_fmac_f32_dpp v116, -v132, v25 quad_perm:[0,0,0,0] row_mask:0xf bank_mask:0xf
	v_fmac_f32_dpp v117, -v133, v27 quad_perm:[0,0,0,0] row_mask:0xf bank_mask:0xf
	v_fmac_f32_dpp v118, -v132, v28 quad_perm:[1,1,1,1] row_mask:0xf bank_mask:0xf
	ds_read_b64 v[150:151], v125 offset:6320
	v_fmac_f32_dpp v119, -v133, v29 quad_perm:[1,1,1,1] row_mask:0xf bank_mask:0xf
	v_add_f32_e32 v121, v117, v116
	v_add_f32_e32 v122, v118, v119
	v_add_f32_e32 v30, v122, v121
	s_waitcnt lgkmcnt(8)
	v_mul_f32_dpp v120, v134, v4 quad_perm:[0,0,0,0] row_mask:0xf bank_mask:0xf
	v_fma_f32 v116, v229, v253, -v120
	v_mul_f32_dpp v117, -v135, v5 quad_perm:[0,0,0,0] row_mask:0xf bank_mask:0xf
	v_mul_f32_dpp v118, -v134, v6 quad_perm:[1,1,1,1] row_mask:0xf bank_mask:0xf
	v_mul_f32_dpp v119, -v135, v12 quad_perm:[1,1,1,1] row_mask:0xf bank_mask:0xf
	ds_read_b32 v182, v124 offset:92
	v_fmac_f32_dpp v116, -v134, v7 quad_perm:[2,2,2,2] row_mask:0xf bank_mask:0xf
	v_fmac_f32_dpp v117, -v135, v13 quad_perm:[2,2,2,2] row_mask:0xf bank_mask:0xf
	v_fmac_f32_dpp v118, -v134, v14 quad_perm:[3,3,3,3] row_mask:0xf bank_mask:0xf
	ds_read_u16_d16_hi v127, v123 offset:6256
	v_fmac_f32_dpp v119, -v135, v15 quad_perm:[3,3,3,3] row_mask:0xf bank_mask:0xf
	v_fmac_f32_dpp v116, -v136, v16 quad_perm:[0,0,0,0] row_mask:0xf bank_mask:0xf
	v_fmac_f32_dpp v117, -v137, v17 quad_perm:[0,0,0,0] row_mask:0xf bank_mask:0xf
	ds_read_b64 v[152:153], v125 offset:6528
	v_fmac_f32_dpp v118, -v136, v19 quad_perm:[1,1,1,1] row_mask:0xf bank_mask:0xf
	v_fmac_f32_dpp v119, -v137, v20 quad_perm:[1,1,1,1] row_mask:0xf bank_mask:0xf
	v_fmac_f32_dpp v116, -v136, v21 quad_perm:[2,2,2,2] row_mask:0xf bank_mask:0xf
	ds_read_b64 v[154:155], v125 offset:6560
	v_fmac_f32_dpp v117, -v137, v22 quad_perm:[2,2,2,2] row_mask:0xf bank_mask:0xf
	v_fmac_f32_dpp v118, -v136, v23 quad_perm:[3,3,3,3] row_mask:0xf bank_mask:0xf
	v_fmac_f32_dpp v119, -v137, v24 quad_perm:[3,3,3,3] row_mask:0xf bank_mask:0xf
	ds_read_b64 v[156:157], v125 offset:6592
	v_fmac_f32_dpp v116, -v138, v25 quad_perm:[0,0,0,0] row_mask:0xf bank_mask:0xf
	v_fmac_f32_dpp v117, -v139, v27 quad_perm:[0,0,0,0] row_mask:0xf bank_mask:0xf
	v_fmac_f32_dpp v118, -v138, v28 quad_perm:[1,1,1,1] row_mask:0xf bank_mask:0xf
	ds_read_b32 v183, v124 offset:96
	v_fmac_f32_dpp v119, -v139, v29 quad_perm:[1,1,1,1] row_mask:0xf bank_mask:0xf
	v_fmac_f32_dpp v116, -v138, v30 quad_perm:[2,2,2,2] row_mask:0xf bank_mask:0xf
	v_add_f32_e32 v121, v117, v116
	v_add_f32_e32 v122, v118, v119
	v_add_f32_e32 v31, v122, v121
	s_waitcnt lgkmcnt(9)
	v_mul_f32_dpp v120, v140, v4 quad_perm:[0,0,0,0] row_mask:0xf bank_mask:0xf
	v_fma_f32 v116, v181, v126, -v120
	v_mul_f32_dpp v117, -v141, v5 quad_perm:[0,0,0,0] row_mask:0xf bank_mask:0xf
	v_mul_f32_dpp v118, -v140, v6 quad_perm:[1,1,1,1] row_mask:0xf bank_mask:0xf
	v_mul_f32_dpp v119, -v141, v12 quad_perm:[1,1,1,1] row_mask:0xf bank_mask:0xf
	ds_read_u16_d16_hi v244, v123 offset:6528
	v_fmac_f32_dpp v116, -v140, v7 quad_perm:[2,2,2,2] row_mask:0xf bank_mask:0xf
	v_fmac_f32_dpp v117, -v141, v13 quad_perm:[2,2,2,2] row_mask:0xf bank_mask:0xf
	v_fmac_f32_dpp v118, -v140, v14 quad_perm:[3,3,3,3] row_mask:0xf bank_mask:0xf
	ds_read_b64 v[158:159], v125 offset:6800
	v_fmac_f32_dpp v119, -v141, v15 quad_perm:[3,3,3,3] row_mask:0xf bank_mask:0xf
	v_fmac_f32_dpp v116, -v142, v16 quad_perm:[0,0,0,0] row_mask:0xf bank_mask:0xf
	v_fmac_f32_dpp v117, -v143, v17 quad_perm:[0,0,0,0] row_mask:0xf bank_mask:0xf
	ds_read_b64 v[160:161], v125 offset:6832
	v_fmac_f32_dpp v118, -v142, v19 quad_perm:[1,1,1,1] row_mask:0xf bank_mask:0xf
	v_fmac_f32_dpp v119, -v143, v20 quad_perm:[1,1,1,1] row_mask:0xf bank_mask:0xf
	v_fmac_f32_dpp v116, -v142, v21 quad_perm:[2,2,2,2] row_mask:0xf bank_mask:0xf
	ds_read_b64 v[162:163], v125 offset:6864
	v_fmac_f32_dpp v117, -v143, v22 quad_perm:[2,2,2,2] row_mask:0xf bank_mask:0xf
	v_fmac_f32_dpp v118, -v142, v23 quad_perm:[3,3,3,3] row_mask:0xf bank_mask:0xf
	v_fmac_f32_dpp v119, -v143, v24 quad_perm:[3,3,3,3] row_mask:0xf bank_mask:0xf
	ds_read_b64 v[164:165], v125 offset:6896
	v_fmac_f32_dpp v116, -v144, v25 quad_perm:[0,0,0,0] row_mask:0xf bank_mask:0xf
	v_fmac_f32_dpp v117, -v145, v27 quad_perm:[0,0,0,0] row_mask:0xf bank_mask:0xf
	v_fmac_f32_dpp v118, -v144, v28 quad_perm:[1,1,1,1] row_mask:0xf bank_mask:0xf
	ds_read_b32 v185, v124 offset:100
	v_fmac_f32_dpp v119, -v145, v29 quad_perm:[1,1,1,1] row_mask:0xf bank_mask:0xf
	v_fmac_f32_dpp v116, -v144, v30 quad_perm:[2,2,2,2] row_mask:0xf bank_mask:0xf
	v_fmac_f32_dpp v117, -v145, v31 quad_perm:[2,2,2,2] row_mask:0xf bank_mask:0xf
	ds_read_u16_d16_hi v245, v123 offset:6800
	v_add_f32_e32 v121, v117, v116
	v_add_f32_e32 v122, v118, v119
	v_add_f32_e32 v32, v122, v121
	s_waitcnt lgkmcnt(11)
; __device__ __forceinline__ float bf2f(bf16 v) { return __uint_as_float(((unsigned)v) << 16); }
; #define GDN_LOADROW(buf, rr_, i_) do { _Pragma("unroll") for (int j4 = 0; j4 < ((i_) + 3) / 4; ++j4) buf[j4] = *(const f32x4*)(Lm + (i_) * GP_LSTR + 4 * j4); rr_ = bf2f(*(const bf16*)(xsrc + (i_) * GP_STR * 2)) * scl[i_]; } while (0)
; template <int STRIP> __device__ __forceinline__ void ph_gdn_prep_fast(const bf16* __restrict__ proj, const float* __restrict__ small, const float* __restrict__ conv_w, const float* __restrict__ a_log, const float* __restrict__ dt_bias, ...
;     ...
;             f32x4 bA[16], bB[16]; float rA, rB = 0.f;
;             rA = bf2f(*(const bf16*)xsrc) * scl[0];
;     ...
; #pragma unroll
;             for (int i = 0; i < 64; i += 2) {
;                 GDN_LOADROW(bB, rB, i + 1);
;                 GDN_ROW(bA, rA, i);
;                 if (i + 2 < 64) GDN_LOADROW(bA, rA, i + 2);
;                 GDN_ROW(bB, rB, i + 1);
;             }
	v_mul_f32_dpp v120, v146, v4 quad_perm:[0,0,0,0] row_mask:0xf bank_mask:0xf
	v_fma_f32 v116, v182, v127, -v120
	v_mul_f32_dpp v117, -v147, v5 quad_perm:[0,0,0,0] row_mask:0xf bank_mask:0xf
	v_mul_f32_dpp v118, -v146, v6 quad_perm:[1,1,1,1] row_mask:0xf bank_mask:0xf
	v_mul_f32_dpp v119, -v147, v12 quad_perm:[1,1,1,1] row_mask:0xf bank_mask:0xf
	ds_read_b64 v[166:167], v125 offset:7072
	v_fmac_f32_dpp v116, -v146, v7 quad_perm:[2,2,2,2] row_mask:0xf bank_mask:0xf
	v_fmac_f32_dpp v117, -v147, v13 quad_perm:[2,2,2,2] row_mask:0xf bank_mask:0xf
	v_fmac_f32_dpp v118, -v146, v14 quad_perm:[3,3,3,3] row_mask:0xf bank_mask:0xf
	ds_read_b64 v[168:169], v125 offset:7104
	v_fmac_f32_dpp v119, -v147, v15 quad_perm:[3,3,3,3] row_mask:0xf bank_mask:0xf
	v_fmac_f32_dpp v116, -v148, v16 quad_perm:[0,0,0,0] row_mask:0xf bank_mask:0xf
	v_fmac_f32_dpp v117, -v149, v17 quad_perm:[0,0,0,0] row_mask:0xf bank_mask:0xf
	ds_read_b64 v[170:171], v125 offset:7136
	v_fmac_f32_dpp v118, -v148, v19 quad_perm:[1,1,1,1] row_mask:0xf bank_mask:0xf
	v_fmac_f32_dpp v119, -v149, v20 quad_perm:[1,1,1,1] row_mask:0xf bank_mask:0xf
	v_fmac_f32_dpp v116, -v148, v21 quad_perm:[2,2,2,2] row_mask:0xf bank_mask:0xf
	ds_read_b64 v[172:173], v125 offset:7168
	v_fmac_f32_dpp v117, -v149, v22 quad_perm:[2,2,2,2] row_mask:0xf bank_mask:0xf
	v_fmac_f32_dpp v118, -v148, v23 quad_perm:[3,3,3,3] row_mask:0xf bank_mask:0xf
	v_fmac_f32_dpp v119, -v149, v24 quad_perm:[3,3,3,3] row_mask:0xf bank_mask:0xf
	ds_read_b32 v208, v124 offset:104
	v_fmac_f32_dpp v116, -v150, v25 quad_perm:[0,0,0,0] row_mask:0xf bank_mask:0xf
	v_fmac_f32_dpp v117, -v151, v27 quad_perm:[0,0,0,0] row_mask:0xf bank_mask:0xf
	v_fmac_f32_dpp v118, -v150, v28 quad_perm:[1,1,1,1] row_mask:0xf bank_mask:0xf
	ds_read_u16_d16_hi v246, v123 offset:7072
	v_fmac_f32_dpp v119, -v151, v29 quad_perm:[1,1,1,1] row_mask:0xf bank_mask:0xf
	v_fmac_f32_dpp v116, -v150, v30 quad_perm:[2,2,2,2] row_mask:0xf bank_mask:0xf
	v_fmac_f32_dpp v117, -v151, v31 quad_perm:[2,2,2,2] row_mask:0xf bank_mask:0xf
	ds_read_b64 v[174:175], v125 offset:7344
	v_fmac_f32_dpp v118, -v150, v32 quad_perm:[3,3,3,3] row_mask:0xf bank_mask:0xf
	v_add_f32_e32 v121, v117, v116
	v_add_f32_e32 v122, v118, v119
	v_add_f32_e32 v33, v122, v121
	s_waitcnt lgkmcnt(13)
	v_mul_f32_dpp v120, v152, v4 quad_perm:[0,0,0,0] row_mask:0xf bank_mask:0xf
	v_fma_f32 v116, v183, v244, -v120
	v_mul_f32_dpp v117, -v153, v5 quad_perm:[0,0,0,0] row_mask:0xf bank_mask:0xf
	v_mul_f32_dpp v118, -v152, v6 quad_perm:[1,1,1,1] row_mask:0xf bank_mask:0xf
	v_mul_f32_dpp v119, -v153, v12 quad_perm:[1,1,1,1] row_mask:0xf bank_mask:0xf
	ds_read_b64 v[176:177], v125 offset:7376
	v_fmac_f32_dpp v116, -v152, v7 quad_perm:[2,2,2,2] row_mask:0xf bank_mask:0xf
	v_fmac_f32_dpp v117, -v153, v13 quad_perm:[2,2,2,2] row_mask:0xf bank_mask:0xf
	v_fmac_f32_dpp v118, -v152, v14 quad_perm:[3,3,3,3] row_mask:0xf bank_mask:0xf
	ds_read_b64 v[178:179], v125 offset:7408
	v_fmac_f32_dpp v119, -v153, v15 quad_perm:[3,3,3,3] row_mask:0xf bank_mask:0xf
	v_fmac_f32_dpp v116, -v154, v16 quad_perm:[0,0,0,0] row_mask:0xf bank_mask:0xf
	v_fmac_f32_dpp v117, -v155, v17 quad_perm:[0,0,0,0] row_mask:0xf bank_mask:0xf
	ds_read_b64 v[186:187], v125 offset:7440
	v_fmac_f32_dpp v118, -v154, v19 quad_perm:[1,1,1,1] row_mask:0xf bank_mask:0xf
	v_fmac_f32_dpp v119, -v155, v20 quad_perm:[1,1,1,1] row_mask:0xf bank_mask:0xf
	v_fmac_f32_dpp v116, -v154, v21 quad_perm:[2,2,2,2] row_mask:0xf bank_mask:0xf
	ds_read_b32 v209, v124 offset:108
	v_fmac_f32_dpp v117, -v155, v22 quad_perm:[2,2,2,2] row_mask:0xf bank_mask:0xf
	v_fmac_f32_dpp v118, -v154, v23 quad_perm:[3,3,3,3] row_mask:0xf bank_mask:0xf
	v_fmac_f32_dpp v119, -v155, v24 quad_perm:[3,3,3,3] row_mask:0xf bank_mask:0xf
	ds_read_u16_d16_hi v247, v123 offset:7344
	v_fmac_f32_dpp v116, -v156, v25 quad_perm:[0,0,0,0] row_mask:0xf bank_mask:0xf
	v_fmac_f32_dpp v117, -v157, v27 quad_perm:[0,0,0,0] row_mask:0xf bank_mask:0xf
	v_fmac_f32_dpp v118, -v156, v28 quad_perm:[1,1,1,1] row_mask:0xf bank_mask:0xf
	ds_read_b64 v[188:189], v125 offset:7616
	v_fmac_f32_dpp v119, -v157, v29 quad_perm:[1,1,1,1] row_mask:0xf bank_mask:0xf
	v_fmac_f32_dpp v116, -v156, v30 quad_perm:[2,2,2,2] row_mask:0xf bank_mask:0xf
	v_fmac_f32_dpp v117, -v157, v31 quad_perm:[2,2,2,2] row_mask:0xf bank_mask:0xf
	ds_read_b64 v[190:191], v125 offset:7648
	v_fmac_f32_dpp v118, -v156, v32 quad_perm:[3,3,3,3] row_mask:0xf bank_mask:0xf
	v_fmac_f32_dpp v119, -v157, v33 quad_perm:[3,3,3,3] row_mask:0xf bank_mask:0xf
	v_add_f32_e32 v121, v117, v116
	v_add_f32_e32 v122, v118, v119
	v_add_f32_e32 v34, v122, v121
	s_waitcnt lgkmcnt(14)
; __device__ __forceinline__ float bf2f(bf16 v) { return __uint_as_float(((unsigned)v) << 16); }
; #define GDN_LOADROW(buf, rr_, i_) do { _Pragma("unroll") for (int j4 = 0; j4 < ((i_) + 3) / 4; ++j4) buf[j4] = *(const f32x4*)(Lm + (i_) * GP_LSTR + 4 * j4); rr_ = bf2f(*(const bf16*)(xsrc + (i_) * GP_STR * 2)) * scl[i_]; } while (0)
; template <int STRIP> __device__ __forceinline__ void ph_gdn_prep_fast(const bf16* __restrict__ proj, const float* __restrict__ small, const float* __restrict__ conv_w, const float* __restrict__ a_log, const float* __restrict__ dt_bias, ...
;     ...
;             f32x4 bA[16], bB[16]; float rA, rB = 0.f;
;             rA = bf2f(*(const bf16*)xsrc) * scl[0];
;     ...
; #pragma unroll
;             for (int i = 0; i < 64; i += 2) {
;                 GDN_LOADROW(bB, rB, i + 1);
;                 GDN_ROW(bA, rA, i);
;                 if (i + 2 < 64) GDN_LOADROW(bA, rA, i + 2);
;                 GDN_ROW(bB, rB, i + 1);
;             }
	v_mul_f32_dpp v120, v158, v4 quad_perm:[0,0,0,0] row_mask:0xf bank_mask:0xf
	v_fma_f32 v116, v185, v245, -v120
	v_mul_f32_dpp v117, -v159, v5 quad_perm:[0,0,0,0] row_mask:0xf bank_mask:0xf
	v_mul_f32_dpp v118, -v158, v6 quad_perm:[1,1,1,1] row_mask:0xf bank_mask:0xf
	v_mul_f32_dpp v119, -v159, v12 quad_perm:[1,1,1,1] row_mask:0xf bank_mask:0xf
	ds_read_b64 v[192:193], v125 offset:7680
	v_fmac_f32_dpp v116, -v158, v7 quad_perm:[2,2,2,2] row_mask:0xf bank_mask:0xf
	v_fmac_f32_dpp v117, -v159, v13 quad_perm:[2,2,2,2] row_mask:0xf bank_mask:0xf
	v_fmac_f32_dpp v118, -v158, v14 quad_perm:[3,3,3,3] row_mask:0xf bank_mask:0xf
	ds_read_b64 v[194:195], v125 offset:7712
	v_fmac_f32_dpp v119, -v159, v15 quad_perm:[3,3,3,3] row_mask:0xf bank_mask:0xf
	v_fmac_f32_dpp v116, -v160, v16 quad_perm:[0,0,0,0] row_mask:0xf bank_mask:0xf
	v_fmac_f32_dpp v117, -v161, v17 quad_perm:[0,0,0,0] row_mask:0xf bank_mask:0xf
	ds_read_b32 v210, v124 offset:112
	v_fmac_f32_dpp v118, -v160, v19 quad_perm:[1,1,1,1] row_mask:0xf bank_mask:0xf
	v_fmac_f32_dpp v119, -v161, v20 quad_perm:[1,1,1,1] row_mask:0xf bank_mask:0xf
	v_fmac_f32_dpp v116, -v160, v21 quad_perm:[2,2,2,2] row_mask:0xf bank_mask:0xf
	ds_read_u16_d16_hi v248, v123 offset:7616
	v_fmac_f32_dpp v117, -v161, v22 quad_perm:[2,2,2,2] row_mask:0xf bank_mask:0xf
	v_fmac_f32_dpp v118, -v160, v23 quad_perm:[3,3,3,3] row_mask:0xf bank_mask:0xf
	v_fmac_f32_dpp v119, -v161, v24 quad_perm:[3,3,3,3] row_mask:0xf bank_mask:0xf
	ds_read_b64 v[196:197], v125 offset:7888
	v_fmac_f32_dpp v116, -v162, v25 quad_perm:[0,0,0,0] row_mask:0xf bank_mask:0xf
	v_fmac_f32_dpp v117, -v163, v27 quad_perm:[0,0,0,0] row_mask:0xf bank_mask:0xf
	v_fmac_f32_dpp v118, -v162, v28 quad_perm:[1,1,1,1] row_mask:0xf bank_mask:0xf
	ds_read_b64 v[198:199], v125 offset:7920
	v_fmac_f32_dpp v119, -v163, v29 quad_perm:[1,1,1,1] row_mask:0xf bank_mask:0xf
	v_fmac_f32_dpp v116, -v162, v30 quad_perm:[2,2,2,2] row_mask:0xf bank_mask:0xf
	v_fmac_f32_dpp v117, -v163, v31 quad_perm:[2,2,2,2] row_mask:0xf bank_mask:0xf
	ds_read_b64 v[200:201], v125 offset:7952
	v_fmac_f32_dpp v118, -v162, v32 quad_perm:[3,3,3,3] row_mask:0xf bank_mask:0xf
	v_fmac_f32_dpp v119, -v163, v33 quad_perm:[3,3,3,3] row_mask:0xf bank_mask:0xf
	v_fmac_f32_dpp v116, -v164, v34 quad_perm:[0,0,0,0] row_mask:0xf bank_mask:0xf
	ds_read_b64 v[202:203], v125 offset:7984
	v_add_f32_e32 v121, v117, v116
	v_add_f32_e32 v122, v118, v119
	v_add_f32_e32 v35, v122, v121
	s_waitcnt lgkmcnt(15)
	v_mul_f32_dpp v120, v166, v4 quad_perm:[0,0,0,0] row_mask:0xf bank_mask:0xf
	v_fma_f32 v116, v208, v246, -v120
	v_mul_f32_dpp v117, -v167, v5 quad_perm:[0,0,0,0] row_mask:0xf bank_mask:0xf
	v_mul_f32_dpp v118, -v166, v6 quad_perm:[1,1,1,1] row_mask:0xf bank_mask:0xf
	v_mul_f32_dpp v119, -v167, v12 quad_perm:[1,1,1,1] row_mask:0xf bank_mask:0xf
	ds_read_b32 v211, v124 offset:116
	v_fmac_f32_dpp v116, -v166, v7 quad_perm:[2,2,2,2] row_mask:0xf bank_mask:0xf
	v_fmac_f32_dpp v117, -v167, v13 quad_perm:[2,2,2,2] row_mask:0xf bank_mask:0xf
	v_fmac_f32_dpp v118, -v166, v14 quad_perm:[3,3,3,3] row_mask:0xf bank_mask:0xf
	ds_read_u16_d16_hi v249, v123 offset:7888
	v_fmac_f32_dpp v119, -v167, v15 quad_perm:[3,3,3,3] row_mask:0xf bank_mask:0xf
	v_fmac_f32_dpp v116, -v168, v16 quad_perm:[0,0,0,0] row_mask:0xf bank_mask:0xf
	v_fmac_f32_dpp v117, -v169, v17 quad_perm:[0,0,0,0] row_mask:0xf bank_mask:0xf
	ds_read_b64 v[204:205], v125 offset:8160
	v_fmac_f32_dpp v118, -v168, v19 quad_perm:[1,1,1,1] row_mask:0xf bank_mask:0xf
	v_fmac_f32_dpp v119, -v169, v20 quad_perm:[1,1,1,1] row_mask:0xf bank_mask:0xf
	v_fmac_f32_dpp v116, -v168, v21 quad_perm:[2,2,2,2] row_mask:0xf bank_mask:0xf
	ds_read_b64 v[206:207], v125 offset:8192
	v_fmac_f32_dpp v117, -v169, v22 quad_perm:[2,2,2,2] row_mask:0xf bank_mask:0xf
	v_fmac_f32_dpp v118, -v168, v23 quad_perm:[3,3,3,3] row_mask:0xf bank_mask:0xf
	v_fmac_f32_dpp v119, -v169, v24 quad_perm:[3,3,3,3] row_mask:0xf bank_mask:0xf
	ds_read_b64 v[132:133], v125 offset:8224
	v_fmac_f32_dpp v116, -v170, v25 quad_perm:[0,0,0,0] row_mask:0xf bank_mask:0xf
	v_fmac_f32_dpp v117, -v171, v27 quad_perm:[0,0,0,0] row_mask:0xf bank_mask:0xf
	v_fmac_f32_dpp v118, -v170, v28 quad_perm:[1,1,1,1] row_mask:0xf bank_mask:0xf
	ds_read_b64 v[134:135], v125 offset:8256
	v_fmac_f32_dpp v119, -v171, v29 quad_perm:[1,1,1,1] row_mask:0xf bank_mask:0xf
	v_fmac_f32_dpp v116, -v170, v30 quad_perm:[2,2,2,2] row_mask:0xf bank_mask:0xf
	v_fmac_f32_dpp v117, -v171, v31 quad_perm:[2,2,2,2] row_mask:0xf bank_mask:0xf
	ds_read_b32 v212, v124 offset:120
	v_fmac_f32_dpp v118, -v170, v32 quad_perm:[3,3,3,3] row_mask:0xf bank_mask:0xf
	v_fmac_f32_dpp v119, -v171, v33 quad_perm:[3,3,3,3] row_mask:0xf bank_mask:0xf
	v_fmac_f32_dpp v116, -v172, v34 quad_perm:[0,0,0,0] row_mask:0xf bank_mask:0xf
	ds_read_u16_d16_hi v250, v123 offset:8160
	v_fmac_f32_dpp v117, -v173, v35 quad_perm:[0,0,0,0] row_mask:0xf bank_mask:0xf
	v_add_f32_e32 v121, v117, v116
	v_add_f32_e32 v122, v118, v119
	v_add_f32_e32 v36, v122, v121
	s_waitcnt lgkmcnt(15)
; __device__ __forceinline__ float bf2f(bf16 v) { return __uint_as_float(((unsigned)v) << 16); }
; #define GDN_LOADROW(buf, rr_, i_) do { _Pragma("unroll") for (int j4 = 0; j4 < ((i_) + 3) / 4; ++j4) buf[j4] = *(const f32x4*)(Lm + (i_) * GP_LSTR + 4 * j4); rr_ = bf2f(*(const bf16*)(xsrc + (i_) * GP_STR * 2)) * scl[i_]; } while (0)
; template <int STRIP> __device__ __forceinline__ void ph_gdn_prep_fast(const bf16* __restrict__ proj, const float* __restrict__ small, const float* __restrict__ conv_w, const float* __restrict__ a_log, const float* __restrict__ dt_bias, ...
;     ...
;             f32x4 bA[16], bB[16]; float rA, rB = 0.f;
;             rA = bf2f(*(const bf16*)xsrc) * scl[0];
;     ...
; #pragma unroll
;             for (int i = 0; i < 64; i += 2) {
;                 GDN_LOADROW(bB, rB, i + 1);
;                 GDN_ROW(bA, rA, i);
;                 if (i + 2 < 64) GDN_LOADROW(bA, rA, i + 2);
;                 GDN_ROW(bB, rB, i + 1);
;             }
	v_mul_f32_dpp v120, v174, v4 quad_perm:[0,0,0,0] row_mask:0xf bank_mask:0xf
	v_fma_f32 v116, v209, v247, -v120
	v_mul_f32_dpp v117, -v175, v5 quad_perm:[0,0,0,0] row_mask:0xf bank_mask:0xf
	v_mul_f32_dpp v118, -v174, v6 quad_perm:[1,1,1,1] row_mask:0xf bank_mask:0xf
	v_mul_f32_dpp v119, -v175, v12 quad_perm:[1,1,1,1] row_mask:0xf bank_mask:0xf
	ds_read_b64 v[136:137], v125 offset:8432
	v_fmac_f32_dpp v116, -v174, v7 quad_perm:[2,2,2,2] row_mask:0xf bank_mask:0xf
	v_fmac_f32_dpp v117, -v175, v13 quad_perm:[2,2,2,2] row_mask:0xf bank_mask:0xf
	v_fmac_f32_dpp v118, -v174, v14 quad_perm:[3,3,3,3] row_mask:0xf bank_mask:0xf
	ds_read_b64 v[138:139], v125 offset:8464
	v_fmac_f32_dpp v119, -v175, v15 quad_perm:[3,3,3,3] row_mask:0xf bank_mask:0xf
	v_fmac_f32_dpp v116, -v176, v16 quad_perm:[0,0,0,0] row_mask:0xf bank_mask:0xf
	v_fmac_f32_dpp v117, -v177, v17 quad_perm:[0,0,0,0] row_mask:0xf bank_mask:0xf
	ds_read_b64 v[140:141], v125 offset:8496
	v_fmac_f32_dpp v118, -v176, v19 quad_perm:[1,1,1,1] row_mask:0xf bank_mask:0xf
	v_fmac_f32_dpp v119, -v177, v20 quad_perm:[1,1,1,1] row_mask:0xf bank_mask:0xf
	v_fmac_f32_dpp v116, -v176, v21 quad_perm:[2,2,2,2] row_mask:0xf bank_mask:0xf
	ds_read_b64 v[142:143], v125 offset:8528
	v_fmac_f32_dpp v117, -v177, v22 quad_perm:[2,2,2,2] row_mask:0xf bank_mask:0xf
	v_fmac_f32_dpp v118, -v176, v23 quad_perm:[3,3,3,3] row_mask:0xf bank_mask:0xf
	v_fmac_f32_dpp v119, -v177, v24 quad_perm:[3,3,3,3] row_mask:0xf bank_mask:0xf
	ds_read_b32 v213, v124 offset:124
	v_fmac_f32_dpp v116, -v178, v25 quad_perm:[0,0,0,0] row_mask:0xf bank_mask:0xf
	v_fmac_f32_dpp v117, -v179, v27 quad_perm:[0,0,0,0] row_mask:0xf bank_mask:0xf
	v_fmac_f32_dpp v118, -v178, v28 quad_perm:[1,1,1,1] row_mask:0xf bank_mask:0xf
	ds_read_u16_d16_hi v251, v123 offset:8432
	v_fmac_f32_dpp v119, -v179, v29 quad_perm:[1,1,1,1] row_mask:0xf bank_mask:0xf
	v_fmac_f32_dpp v116, -v178, v30 quad_perm:[2,2,2,2] row_mask:0xf bank_mask:0xf
	v_fmac_f32_dpp v117, -v179, v31 quad_perm:[2,2,2,2] row_mask:0xf bank_mask:0xf
	v_fmac_f32_dpp v118, -v178, v32 quad_perm:[3,3,3,3] row_mask:0xf bank_mask:0xf
	v_fmac_f32_dpp v119, -v179, v33 quad_perm:[3,3,3,3] row_mask:0xf bank_mask:0xf
	v_fmac_f32_dpp v116, -v186, v34 quad_perm:[0,0,0,0] row_mask:0xf bank_mask:0xf
	v_fmac_f32_dpp v117, -v187, v35 quad_perm:[0,0,0,0] row_mask:0xf bank_mask:0xf
	v_fmac_f32_dpp v118, -v186, v36 quad_perm:[1,1,1,1] row_mask:0xf bank_mask:0xf
	v_add_f32_e32 v121, v117, v116
	v_add_f32_e32 v122, v118, v119
	v_add_f32_e32 v37, v122, v121
	s_waitcnt lgkmcnt(15)
	v_mul_f32_dpp v120, v188, v4 quad_perm:[0,0,0,0] row_mask:0xf bank_mask:0xf
	v_fma_f32 v116, v210, v248, -v120
	v_mul_f32_dpp v117, -v189, v5 quad_perm:[0,0,0,0] row_mask:0xf bank_mask:0xf
	v_mul_f32_dpp v118, -v188, v6 quad_perm:[1,1,1,1] row_mask:0xf bank_mask:0xf
	v_mul_f32_dpp v119, -v189, v12 quad_perm:[1,1,1,1] row_mask:0xf bank_mask:0xf
	ds_read_b64 v[144:145], v125 offset:8704
	v_fmac_f32_dpp v116, -v188, v7 quad_perm:[2,2,2,2] row_mask:0xf bank_mask:0xf
	v_fmac_f32_dpp v117, -v189, v13 quad_perm:[2,2,2,2] row_mask:0xf bank_mask:0xf
	v_fmac_f32_dpp v118, -v188, v14 quad_perm:[3,3,3,3] row_mask:0xf bank_mask:0xf
	ds_read_b64 v[146:147], v125 offset:8736
	v_fmac_f32_dpp v119, -v189, v15 quad_perm:[3,3,3,3] row_mask:0xf bank_mask:0xf
	v_fmac_f32_dpp v116, -v190, v16 quad_perm:[0,0,0,0] row_mask:0xf bank_mask:0xf
	v_fmac_f32_dpp v117, -v191, v17 quad_perm:[0,0,0,0] row_mask:0xf bank_mask:0xf
	ds_read_b64 v[148:149], v125 offset:8768
	v_fmac_f32_dpp v118, -v190, v19 quad_perm:[1,1,1,1] row_mask:0xf bank_mask:0xf
	v_fmac_f32_dpp v119, -v191, v20 quad_perm:[1,1,1,1] row_mask:0xf bank_mask:0xf
	v_fmac_f32_dpp v116, -v190, v21 quad_perm:[2,2,2,2] row_mask:0xf bank_mask:0xf
	ds_read_b64 v[150:151], v125 offset:8800
	v_fmac_f32_dpp v117, -v191, v22 quad_perm:[2,2,2,2] row_mask:0xf bank_mask:0xf
	v_fmac_f32_dpp v118, -v190, v23 quad_perm:[3,3,3,3] row_mask:0xf bank_mask:0xf
	v_fmac_f32_dpp v119, -v191, v24 quad_perm:[3,3,3,3] row_mask:0xf bank_mask:0xf
	ds_read_b32 v214, v124 offset:128
	v_fmac_f32_dpp v116, -v192, v25 quad_perm:[0,0,0,0] row_mask:0xf bank_mask:0xf
	v_fmac_f32_dpp v117, -v193, v27 quad_perm:[0,0,0,0] row_mask:0xf bank_mask:0xf
	v_fmac_f32_dpp v118, -v192, v28 quad_perm:[1,1,1,1] row_mask:0xf bank_mask:0xf
	ds_read_u16_d16_hi v252, v123 offset:8704
	v_fmac_f32_dpp v119, -v193, v29 quad_perm:[1,1,1,1] row_mask:0xf bank_mask:0xf
	v_fmac_f32_dpp v116, -v192, v30 quad_perm:[2,2,2,2] row_mask:0xf bank_mask:0xf
	v_fmac_f32_dpp v117, -v193, v31 quad_perm:[2,2,2,2] row_mask:0xf bank_mask:0xf
	v_fmac_f32_dpp v118, -v192, v32 quad_perm:[3,3,3,3] row_mask:0xf bank_mask:0xf
	v_fmac_f32_dpp v119, -v193, v33 quad_perm:[3,3,3,3] row_mask:0xf bank_mask:0xf
	v_fmac_f32_dpp v116, -v194, v34 quad_perm:[0,0,0,0] row_mask:0xf bank_mask:0xf
	v_fmac_f32_dpp v117, -v195, v35 quad_perm:[0,0,0,0] row_mask:0xf bank_mask:0xf
	v_fmac_f32_dpp v118, -v194, v36 quad_perm:[1,1,1,1] row_mask:0xf bank_mask:0xf
	v_fmac_f32_dpp v119, -v195, v37 quad_perm:[1,1,1,1] row_mask:0xf bank_mask:0xf
	v_add_f32_e32 v121, v117, v116
	v_add_f32_e32 v122, v118, v119
	v_add_f32_e32 v38, v122, v121
	s_waitcnt lgkmcnt(15)
; __device__ __forceinline__ float bf2f(bf16 v) { return __uint_as_float(((unsigned)v) << 16); }
; #define GDN_LOADROW(buf, rr_, i_) do { _Pragma("unroll") for (int j4 = 0; j4 < ((i_) + 3) / 4; ++j4) buf[j4] = *(const f32x4*)(Lm + (i_) * GP_LSTR + 4 * j4); rr_ = bf2f(*(const bf16*)(xsrc + (i_) * GP_STR * 2)) * scl[i_]; } while (0)
; template <int STRIP> __device__ __forceinline__ void ph_gdn_prep_fast(const bf16* __restrict__ proj, const float* __restrict__ small, const float* __restrict__ conv_w, const float* __restrict__ a_log, const float* __restrict__ dt_bias, ...
;     ...
;             f32x4 bA[16], bB[16]; float rA, rB = 0.f;
;             rA = bf2f(*(const bf16*)xsrc) * scl[0];
;     ...
; #pragma unroll
;             for (int i = 0; i < 64; i += 2) {
;                 GDN_LOADROW(bB, rB, i + 1);
;                 GDN_ROW(bA, rA, i);
;                 if (i + 2 < 64) GDN_LOADROW(bA, rA, i + 2);
;                 GDN_ROW(bB, rB, i + 1);
;             }
	v_mul_f32_dpp v120, v196, v4 quad_perm:[0,0,0,0] row_mask:0xf bank_mask:0xf
	v_fma_f32 v116, v211, v249, -v120
	v_mul_f32_dpp v117, -v197, v5 quad_perm:[0,0,0,0] row_mask:0xf bank_mask:0xf
	v_mul_f32_dpp v118, -v196, v6 quad_perm:[1,1,1,1] row_mask:0xf bank_mask:0xf
	v_mul_f32_dpp v119, -v197, v12 quad_perm:[1,1,1,1] row_mask:0xf bank_mask:0xf
	ds_read_b64 v[152:153], v125 offset:8976
	v_fmac_f32_dpp v116, -v196, v7 quad_perm:[2,2,2,2] row_mask:0xf bank_mask:0xf
	v_fmac_f32_dpp v117, -v197, v13 quad_perm:[2,2,2,2] row_mask:0xf bank_mask:0xf
	v_fmac_f32_dpp v118, -v196, v14 quad_perm:[3,3,3,3] row_mask:0xf bank_mask:0xf
	ds_read_b64 v[154:155], v125 offset:9008
	v_fmac_f32_dpp v119, -v197, v15 quad_perm:[3,3,3,3] row_mask:0xf bank_mask:0xf
	v_fmac_f32_dpp v116, -v198, v16 quad_perm:[0,0,0,0] row_mask:0xf bank_mask:0xf
	v_fmac_f32_dpp v117, -v199, v17 quad_perm:[0,0,0,0] row_mask:0xf bank_mask:0xf
	ds_read_b64 v[156:157], v125 offset:9040
	v_fmac_f32_dpp v118, -v198, v19 quad_perm:[1,1,1,1] row_mask:0xf bank_mask:0xf
	v_fmac_f32_dpp v119, -v199, v20 quad_perm:[1,1,1,1] row_mask:0xf bank_mask:0xf
	v_fmac_f32_dpp v116, -v198, v21 quad_perm:[2,2,2,2] row_mask:0xf bank_mask:0xf
	ds_read_b64 v[158:159], v125 offset:9072
	v_fmac_f32_dpp v117, -v199, v22 quad_perm:[2,2,2,2] row_mask:0xf bank_mask:0xf
	v_fmac_f32_dpp v118, -v198, v23 quad_perm:[3,3,3,3] row_mask:0xf bank_mask:0xf
	v_fmac_f32_dpp v119, -v199, v24 quad_perm:[3,3,3,3] row_mask:0xf bank_mask:0xf
	ds_read_b64 v[160:161], v125 offset:9104
	v_fmac_f32_dpp v116, -v200, v25 quad_perm:[0,0,0,0] row_mask:0xf bank_mask:0xf
	v_fmac_f32_dpp v117, -v201, v27 quad_perm:[0,0,0,0] row_mask:0xf bank_mask:0xf
	v_fmac_f32_dpp v118, -v200, v28 quad_perm:[1,1,1,1] row_mask:0xf bank_mask:0xf
	ds_read_b32 v215, v124 offset:132
	v_fmac_f32_dpp v119, -v201, v29 quad_perm:[1,1,1,1] row_mask:0xf bank_mask:0xf
	v_fmac_f32_dpp v116, -v200, v30 quad_perm:[2,2,2,2] row_mask:0xf bank_mask:0xf
	v_fmac_f32_dpp v117, -v201, v31 quad_perm:[2,2,2,2] row_mask:0xf bank_mask:0xf
	ds_read_u16_d16_hi v253, v123 offset:8976
	v_fmac_f32_dpp v118, -v200, v32 quad_perm:[3,3,3,3] row_mask:0xf bank_mask:0xf
	v_fmac_f32_dpp v119, -v201, v33 quad_perm:[3,3,3,3] row_mask:0xf bank_mask:0xf
	v_fmac_f32_dpp v116, -v202, v34 quad_perm:[0,0,0,0] row_mask:0xf bank_mask:0xf
	v_fmac_f32_dpp v117, -v203, v35 quad_perm:[0,0,0,0] row_mask:0xf bank_mask:0xf
	v_fmac_f32_dpp v118, -v202, v36 quad_perm:[1,1,1,1] row_mask:0xf bank_mask:0xf
	v_fmac_f32_dpp v119, -v203, v37 quad_perm:[1,1,1,1] row_mask:0xf bank_mask:0xf
	v_fmac_f32_dpp v116, -v202, v38 quad_perm:[2,2,2,2] row_mask:0xf bank_mask:0xf
	v_add_f32_e32 v121, v117, v116
	v_add_f32_e32 v122, v118, v119
	v_add_f32_e32 v39, v122, v121
	s_waitcnt lgkmcnt(15)
	v_mul_f32_dpp v120, v204, v4 quad_perm:[0,0,0,0] row_mask:0xf bank_mask:0xf
	v_fma_f32 v116, v212, v250, -v120
	v_mul_f32_dpp v117, -v205, v5 quad_perm:[0,0,0,0] row_mask:0xf bank_mask:0xf
	v_mul_f32_dpp v118, -v204, v6 quad_perm:[1,1,1,1] row_mask:0xf bank_mask:0xf
	v_mul_f32_dpp v119, -v205, v12 quad_perm:[1,1,1,1] row_mask:0xf bank_mask:0xf
	ds_read_b64 v[162:163], v125 offset:9248
	v_fmac_f32_dpp v116, -v204, v7 quad_perm:[2,2,2,2] row_mask:0xf bank_mask:0xf
	v_fmac_f32_dpp v117, -v205, v13 quad_perm:[2,2,2,2] row_mask:0xf bank_mask:0xf
	v_fmac_f32_dpp v118, -v204, v14 quad_perm:[3,3,3,3] row_mask:0xf bank_mask:0xf
	ds_read_b64 v[164:165], v125 offset:9280
	v_fmac_f32_dpp v119, -v205, v15 quad_perm:[3,3,3,3] row_mask:0xf bank_mask:0xf
	v_fmac_f32_dpp v116, -v206, v16 quad_perm:[0,0,0,0] row_mask:0xf bank_mask:0xf
	v_fmac_f32_dpp v117, -v207, v17 quad_perm:[0,0,0,0] row_mask:0xf bank_mask:0xf
	ds_read_b64 v[166:167], v125 offset:9312
	v_fmac_f32_dpp v118, -v206, v19 quad_perm:[1,1,1,1] row_mask:0xf bank_mask:0xf
	v_fmac_f32_dpp v119, -v207, v20 quad_perm:[1,1,1,1] row_mask:0xf bank_mask:0xf
	v_fmac_f32_dpp v116, -v206, v21 quad_perm:[2,2,2,2] row_mask:0xf bank_mask:0xf
	ds_read_b64 v[168:169], v125 offset:9344
	v_fmac_f32_dpp v117, -v207, v22 quad_perm:[2,2,2,2] row_mask:0xf bank_mask:0xf
	v_fmac_f32_dpp v118, -v206, v23 quad_perm:[3,3,3,3] row_mask:0xf bank_mask:0xf
	v_fmac_f32_dpp v119, -v207, v24 quad_perm:[3,3,3,3] row_mask:0xf bank_mask:0xf
	ds_read_b64 v[170:171], v125 offset:9376
	v_fmac_f32_dpp v116, -v132, v25 quad_perm:[0,0,0,0] row_mask:0xf bank_mask:0xf
	v_fmac_f32_dpp v117, -v133, v27 quad_perm:[0,0,0,0] row_mask:0xf bank_mask:0xf
	v_fmac_f32_dpp v118, -v132, v28 quad_perm:[1,1,1,1] row_mask:0xf bank_mask:0xf
	ds_read_b32 v216, v124 offset:136
	v_fmac_f32_dpp v119, -v133, v29 quad_perm:[1,1,1,1] row_mask:0xf bank_mask:0xf
	v_fmac_f32_dpp v116, -v132, v30 quad_perm:[2,2,2,2] row_mask:0xf bank_mask:0xf
	v_fmac_f32_dpp v117, -v133, v31 quad_perm:[2,2,2,2] row_mask:0xf bank_mask:0xf
	ds_read_u16_d16_hi v126, v123 offset:9248
	v_fmac_f32_dpp v118, -v132, v32 quad_perm:[3,3,3,3] row_mask:0xf bank_mask:0xf
	v_fmac_f32_dpp v119, -v133, v33 quad_perm:[3,3,3,3] row_mask:0xf bank_mask:0xf
	v_fmac_f32_dpp v116, -v134, v34 quad_perm:[0,0,0,0] row_mask:0xf bank_mask:0xf
	v_fmac_f32_dpp v117, -v135, v35 quad_perm:[0,0,0,0] row_mask:0xf bank_mask:0xf
	v_fmac_f32_dpp v118, -v134, v36 quad_perm:[1,1,1,1] row_mask:0xf bank_mask:0xf
	v_fmac_f32_dpp v119, -v135, v37 quad_perm:[1,1,1,1] row_mask:0xf bank_mask:0xf
	v_fmac_f32_dpp v116, -v134, v38 quad_perm:[2,2,2,2] row_mask:0xf bank_mask:0xf
	v_fmac_f32_dpp v117, -v135, v39 quad_perm:[2,2,2,2] row_mask:0xf bank_mask:0xf
	v_add_f32_e32 v121, v117, v116
	v_add_f32_e32 v122, v118, v119
	v_add_f32_e32 v40, v122, v121
	s_waitcnt lgkmcnt(15)
; #define GDN_LOADROW(buf, rr_, i_) do { _Pragma("unroll") for (int j4 = 0; j4 < ((i_) + 3) / 4; ++j4) buf[j4] = *(const f32x4*)(Lm + (i_) * GP_LSTR + 4 * j4); rr_ = bf2f(*(const bf16*)(xsrc + (i_) * GP_STR * 2)) * scl[i_]; } while (0)
; template <int STRIP> __device__ __forceinline__ void ph_gdn_prep_fast(const bf16* __restrict__ proj, const float* __restrict__ small, const float* __restrict__ conv_w, const float* __restrict__ a_log, const float* __restrict__ dt_bias, ...
;     ...
; #pragma unroll
;             for (int i = 0; i < 64; i += 2) {
;                 GDN_LOADROW(bB, rB, i + 1);
;                 GDN_ROW(bA, rA, i);
;                 if (i + 2 < 64) GDN_LOADROW(bA, rA, i + 2);
;                 GDN_ROW(bB, rB, i + 1);
	v_mul_f32_dpp v120, v136, v4 quad_perm:[0,0,0,0] row_mask:0xf bank_mask:0xf
	v_fma_f32 v116, v213, v251, -v120
	v_mul_f32_dpp v117, -v137, v5 quad_perm:[0,0,0,0] row_mask:0xf bank_mask:0xf
	v_mul_f32_dpp v118, -v136, v6 quad_perm:[1,1,1,1] row_mask:0xf bank_mask:0xf
	v_mul_f32_dpp v119, -v137, v12 quad_perm:[1,1,1,1] row_mask:0xf bank_mask:0xf
	v_fmac_f32_dpp v116, -v136, v7 quad_perm:[2,2,2,2] row_mask:0xf bank_mask:0xf
	v_fmac_f32_dpp v117, -v137, v13 quad_perm:[2,2,2,2] row_mask:0xf bank_mask:0xf
	v_fmac_f32_dpp v118, -v136, v14 quad_perm:[3,3,3,3] row_mask:0xf bank_mask:0xf
	v_fmac_f32_dpp v119, -v137, v15 quad_perm:[3,3,3,3] row_mask:0xf bank_mask:0xf
	v_fmac_f32_dpp v116, -v138, v16 quad_perm:[0,0,0,0] row_mask:0xf bank_mask:0xf
	v_fmac_f32_dpp v117, -v139, v17 quad_perm:[0,0,0,0] row_mask:0xf bank_mask:0xf
	v_fmac_f32_dpp v118, -v138, v19 quad_perm:[1,1,1,1] row_mask:0xf bank_mask:0xf
	v_fmac_f32_dpp v119, -v139, v20 quad_perm:[1,1,1,1] row_mask:0xf bank_mask:0xf
	v_fmac_f32_dpp v116, -v138, v21 quad_perm:[2,2,2,2] row_mask:0xf bank_mask:0xf
	v_fmac_f32_dpp v117, -v139, v22 quad_perm:[2,2,2,2] row_mask:0xf bank_mask:0xf
	v_fmac_f32_dpp v118, -v138, v23 quad_perm:[3,3,3,3] row_mask:0xf bank_mask:0xf
	v_fmac_f32_dpp v119, -v139, v24 quad_perm:[3,3,3,3] row_mask:0xf bank_mask:0xf
	v_fmac_f32_dpp v116, -v140, v25 quad_perm:[0,0,0,0] row_mask:0xf bank_mask:0xf
	v_fmac_f32_dpp v117, -v141, v27 quad_perm:[0,0,0,0] row_mask:0xf bank_mask:0xf
	v_fmac_f32_dpp v118, -v140, v28 quad_perm:[1,1,1,1] row_mask:0xf bank_mask:0xf
	v_fmac_f32_dpp v119, -v141, v29 quad_perm:[1,1,1,1] row_mask:0xf bank_mask:0xf
	v_fmac_f32_dpp v116, -v140, v30 quad_perm:[2,2,2,2] row_mask:0xf bank_mask:0xf
	v_fmac_f32_dpp v117, -v141, v31 quad_perm:[2,2,2,2] row_mask:0xf bank_mask:0xf
	v_fmac_f32_dpp v118, -v140, v32 quad_perm:[3,3,3,3] row_mask:0xf bank_mask:0xf
	v_fmac_f32_dpp v119, -v141, v33 quad_perm:[3,3,3,3] row_mask:0xf bank_mask:0xf
	v_fmac_f32_dpp v116, -v142, v34 quad_perm:[0,0,0,0] row_mask:0xf bank_mask:0xf
	v_fmac_f32_dpp v117, -v143, v35 quad_perm:[0,0,0,0] row_mask:0xf bank_mask:0xf
	v_fmac_f32_dpp v118, -v142, v36 quad_perm:[1,1,1,1] row_mask:0xf bank_mask:0xf
	v_fmac_f32_dpp v119, -v143, v37 quad_perm:[1,1,1,1] row_mask:0xf bank_mask:0xf
	v_fmac_f32_dpp v116, -v142, v38 quad_perm:[2,2,2,2] row_mask:0xf bank_mask:0xf
	v_fmac_f32_dpp v117, -v143, v39 quad_perm:[2,2,2,2] row_mask:0xf bank_mask:0xf
	v_fmac_f32_dpp v118, -v142, v40 quad_perm:[3,3,3,3] row_mask:0xf bank_mask:0xf
	v_add_f32_e32 v121, v117, v116
	v_add_f32_e32 v122, v118, v119
	v_add_f32_e32 v41, v122, v121
	s_waitcnt lgkmcnt(14)
	v_mul_f32_dpp v120, v144, v4 quad_perm:[0,0,0,0] row_mask:0xf bank_mask:0xf
	v_fma_f32 v116, v214, v252, -v120
	v_mul_f32_dpp v117, -v145, v5 quad_perm:[0,0,0,0] row_mask:0xf bank_mask:0xf
	v_mul_f32_dpp v118, -v144, v6 quad_perm:[1,1,1,1] row_mask:0xf bank_mask:0xf
	v_mul_f32_dpp v119, -v145, v12 quad_perm:[1,1,1,1] row_mask:0xf bank_mask:0xf
	ds_read_b64 v[172:173], v125 offset:9520
	v_fmac_f32_dpp v116, -v144, v7 quad_perm:[2,2,2,2] row_mask:0xf bank_mask:0xf
	v_fmac_f32_dpp v117, -v145, v13 quad_perm:[2,2,2,2] row_mask:0xf bank_mask:0xf
	v_fmac_f32_dpp v118, -v144, v14 quad_perm:[3,3,3,3] row_mask:0xf bank_mask:0xf
	ds_read_b64 v[174:175], v125 offset:9552
	v_fmac_f32_dpp v119, -v145, v15 quad_perm:[3,3,3,3] row_mask:0xf bank_mask:0xf
	v_fmac_f32_dpp v116, -v146, v16 quad_perm:[0,0,0,0] row_mask:0xf bank_mask:0xf
	v_fmac_f32_dpp v117, -v147, v17 quad_perm:[0,0,0,0] row_mask:0xf bank_mask:0xf
	ds_read_b64 v[176:177], v125 offset:9584
	v_fmac_f32_dpp v118, -v146, v19 quad_perm:[1,1,1,1] row_mask:0xf bank_mask:0xf
	v_fmac_f32_dpp v119, -v147, v20 quad_perm:[1,1,1,1] row_mask:0xf bank_mask:0xf
	v_fmac_f32_dpp v116, -v146, v21 quad_perm:[2,2,2,2] row_mask:0xf bank_mask:0xf
	ds_read_b64 v[178:179], v125 offset:9616
	v_fmac_f32_dpp v117, -v147, v22 quad_perm:[2,2,2,2] row_mask:0xf bank_mask:0xf
	v_fmac_f32_dpp v118, -v146, v23 quad_perm:[3,3,3,3] row_mask:0xf bank_mask:0xf
	v_fmac_f32_dpp v119, -v147, v24 quad_perm:[3,3,3,3] row_mask:0xf bank_mask:0xf
	ds_read_b64 v[186:187], v125 offset:9648
	v_fmac_f32_dpp v116, -v148, v25 quad_perm:[0,0,0,0] row_mask:0xf bank_mask:0xf
	v_fmac_f32_dpp v117, -v149, v27 quad_perm:[0,0,0,0] row_mask:0xf bank_mask:0xf
	v_fmac_f32_dpp v118, -v148, v28 quad_perm:[1,1,1,1] row_mask:0xf bank_mask:0xf
	ds_read_b32 v217, v124 offset:140
	v_fmac_f32_dpp v119, -v149, v29 quad_perm:[1,1,1,1] row_mask:0xf bank_mask:0xf
	v_fmac_f32_dpp v116, -v148, v30 quad_perm:[2,2,2,2] row_mask:0xf bank_mask:0xf
	v_fmac_f32_dpp v117, -v149, v31 quad_perm:[2,2,2,2] row_mask:0xf bank_mask:0xf
	ds_read_u16_d16_hi v127, v123 offset:9520
	v_fmac_f32_dpp v118, -v148, v32 quad_perm:[3,3,3,3] row_mask:0xf bank_mask:0xf
	v_fmac_f32_dpp v119, -v149, v33 quad_perm:[3,3,3,3] row_mask:0xf bank_mask:0xf
	v_fmac_f32_dpp v116, -v150, v34 quad_perm:[0,0,0,0] row_mask:0xf bank_mask:0xf
	v_fmac_f32_dpp v117, -v151, v35 quad_perm:[0,0,0,0] row_mask:0xf bank_mask:0xf
	v_fmac_f32_dpp v118, -v150, v36 quad_perm:[1,1,1,1] row_mask:0xf bank_mask:0xf
	v_fmac_f32_dpp v119, -v151, v37 quad_perm:[1,1,1,1] row_mask:0xf bank_mask:0xf
	v_fmac_f32_dpp v116, -v150, v38 quad_perm:[2,2,2,2] row_mask:0xf bank_mask:0xf
	v_fmac_f32_dpp v117, -v151, v39 quad_perm:[2,2,2,2] row_mask:0xf bank_mask:0xf
	v_fmac_f32_dpp v118, -v150, v40 quad_perm:[3,3,3,3] row_mask:0xf bank_mask:0xf
	v_fmac_f32_dpp v119, -v151, v41 quad_perm:[3,3,3,3] row_mask:0xf bank_mask:0xf
	v_add_f32_e32 v121, v117, v116
	v_add_f32_e32 v122, v118, v119
	v_add_f32_e32 v42, v122, v121
	s_waitcnt lgkmcnt(14)
; #define GDN_LOADROW(buf, rr_, i_) do { _Pragma("unroll") for (int j4 = 0; j4 < ((i_) + 3) / 4; ++j4) buf[j4] = *(const f32x4*)(Lm + (i_) * GP_LSTR + 4 * j4); rr_ = bf2f(*(const bf16*)(xsrc + (i_) * GP_STR * 2)) * scl[i_]; } while (0)
; template <int STRIP> __device__ __forceinline__ void ph_gdn_prep_fast(const bf16* __restrict__ proj, const float* __restrict__ small, const float* __restrict__ conv_w, const float* __restrict__ a_log, const float* __restrict__ dt_bias, ...
;     ...
; #pragma unroll
;             for (int i = 0; i < 64; i += 2) {
;                 GDN_LOADROW(bB, rB, i + 1);
;                 GDN_ROW(bA, rA, i);
;                 if (i + 2 < 64) GDN_LOADROW(bA, rA, i + 2);
;                 GDN_ROW(bB, rB, i + 1);
	v_mul_f32_dpp v120, v152, v4 quad_perm:[0,0,0,0] row_mask:0xf bank_mask:0xf
	v_fma_f32 v116, v215, v253, -v120
	v_mul_f32_dpp v117, -v153, v5 quad_perm:[0,0,0,0] row_mask:0xf bank_mask:0xf
	v_mul_f32_dpp v118, -v152, v6 quad_perm:[1,1,1,1] row_mask:0xf bank_mask:0xf
	v_mul_f32_dpp v119, -v153, v12 quad_perm:[1,1,1,1] row_mask:0xf bank_mask:0xf
	ds_read_b64 v[188:189], v125 offset:9792
	v_fmac_f32_dpp v116, -v152, v7 quad_perm:[2,2,2,2] row_mask:0xf bank_mask:0xf
	v_fmac_f32_dpp v117, -v153, v13 quad_perm:[2,2,2,2] row_mask:0xf bank_mask:0xf
	v_fmac_f32_dpp v118, -v152, v14 quad_perm:[3,3,3,3] row_mask:0xf bank_mask:0xf
	ds_read_b64 v[190:191], v125 offset:9824
	v_fmac_f32_dpp v119, -v153, v15 quad_perm:[3,3,3,3] row_mask:0xf bank_mask:0xf
	v_fmac_f32_dpp v116, -v154, v16 quad_perm:[0,0,0,0] row_mask:0xf bank_mask:0xf
	v_fmac_f32_dpp v117, -v155, v17 quad_perm:[0,0,0,0] row_mask:0xf bank_mask:0xf
	ds_read_b64 v[192:193], v125 offset:9856
	v_fmac_f32_dpp v118, -v154, v19 quad_perm:[1,1,1,1] row_mask:0xf bank_mask:0xf
	v_fmac_f32_dpp v119, -v155, v20 quad_perm:[1,1,1,1] row_mask:0xf bank_mask:0xf
	v_fmac_f32_dpp v116, -v154, v21 quad_perm:[2,2,2,2] row_mask:0xf bank_mask:0xf
	ds_read_b64 v[194:195], v125 offset:9888
	v_fmac_f32_dpp v117, -v155, v22 quad_perm:[2,2,2,2] row_mask:0xf bank_mask:0xf
	v_fmac_f32_dpp v118, -v154, v23 quad_perm:[3,3,3,3] row_mask:0xf bank_mask:0xf
	v_fmac_f32_dpp v119, -v155, v24 quad_perm:[3,3,3,3] row_mask:0xf bank_mask:0xf
	ds_read_b64 v[196:197], v125 offset:9920
	v_fmac_f32_dpp v116, -v156, v25 quad_perm:[0,0,0,0] row_mask:0xf bank_mask:0xf
	v_fmac_f32_dpp v117, -v157, v27 quad_perm:[0,0,0,0] row_mask:0xf bank_mask:0xf
	v_fmac_f32_dpp v118, -v156, v28 quad_perm:[1,1,1,1] row_mask:0xf bank_mask:0xf
	ds_read_b32 v218, v124 offset:144
	v_fmac_f32_dpp v119, -v157, v29 quad_perm:[1,1,1,1] row_mask:0xf bank_mask:0xf
	v_fmac_f32_dpp v116, -v156, v30 quad_perm:[2,2,2,2] row_mask:0xf bank_mask:0xf
	v_fmac_f32_dpp v117, -v157, v31 quad_perm:[2,2,2,2] row_mask:0xf bank_mask:0xf
	ds_read_u16_d16_hi v244, v123 offset:9792
	v_fmac_f32_dpp v118, -v156, v32 quad_perm:[3,3,3,3] row_mask:0xf bank_mask:0xf
	v_fmac_f32_dpp v119, -v157, v33 quad_perm:[3,3,3,3] row_mask:0xf bank_mask:0xf
	v_fmac_f32_dpp v116, -v158, v34 quad_perm:[0,0,0,0] row_mask:0xf bank_mask:0xf
	v_fmac_f32_dpp v117, -v159, v35 quad_perm:[0,0,0,0] row_mask:0xf bank_mask:0xf
	v_fmac_f32_dpp v118, -v158, v36 quad_perm:[1,1,1,1] row_mask:0xf bank_mask:0xf
	v_fmac_f32_dpp v119, -v159, v37 quad_perm:[1,1,1,1] row_mask:0xf bank_mask:0xf
	v_fmac_f32_dpp v116, -v158, v38 quad_perm:[2,2,2,2] row_mask:0xf bank_mask:0xf
	v_fmac_f32_dpp v117, -v159, v39 quad_perm:[2,2,2,2] row_mask:0xf bank_mask:0xf
	v_fmac_f32_dpp v118, -v158, v40 quad_perm:[3,3,3,3] row_mask:0xf bank_mask:0xf
	v_fmac_f32_dpp v119, -v159, v41 quad_perm:[3,3,3,3] row_mask:0xf bank_mask:0xf
	v_fmac_f32_dpp v116, -v160, v42 quad_perm:[0,0,0,0] row_mask:0xf bank_mask:0xf
	v_add_f32_e32 v121, v117, v116
	v_add_f32_e32 v122, v118, v119
	v_add_f32_e32 v43, v122, v121
	s_waitcnt lgkmcnt(14)
	v_mul_f32_dpp v120, v162, v4 quad_perm:[0,0,0,0] row_mask:0xf bank_mask:0xf
	v_fma_f32 v116, v216, v126, -v120
	v_mul_f32_dpp v117, -v163, v5 quad_perm:[0,0,0,0] row_mask:0xf bank_mask:0xf
	v_mul_f32_dpp v118, -v162, v6 quad_perm:[1,1,1,1] row_mask:0xf bank_mask:0xf
	v_mul_f32_dpp v119, -v163, v12 quad_perm:[1,1,1,1] row_mask:0xf bank_mask:0xf
	ds_read_b64 v[198:199], v125 offset:10064
	v_fmac_f32_dpp v116, -v162, v7 quad_perm:[2,2,2,2] row_mask:0xf bank_mask:0xf
	v_fmac_f32_dpp v117, -v163, v13 quad_perm:[2,2,2,2] row_mask:0xf bank_mask:0xf
	v_fmac_f32_dpp v118, -v162, v14 quad_perm:[3,3,3,3] row_mask:0xf bank_mask:0xf
	ds_read_b64 v[200:201], v125 offset:10096
	v_fmac_f32_dpp v119, -v163, v15 quad_perm:[3,3,3,3] row_mask:0xf bank_mask:0xf
	v_fmac_f32_dpp v116, -v164, v16 quad_perm:[0,0,0,0] row_mask:0xf bank_mask:0xf
	v_fmac_f32_dpp v117, -v165, v17 quad_perm:[0,0,0,0] row_mask:0xf bank_mask:0xf
	ds_read_b64 v[202:203], v125 offset:10128
	v_fmac_f32_dpp v118, -v164, v19 quad_perm:[1,1,1,1] row_mask:0xf bank_mask:0xf
	v_fmac_f32_dpp v119, -v165, v20 quad_perm:[1,1,1,1] row_mask:0xf bank_mask:0xf
	v_fmac_f32_dpp v116, -v164, v21 quad_perm:[2,2,2,2] row_mask:0xf bank_mask:0xf
	ds_read_b64 v[204:205], v125 offset:10160
	v_fmac_f32_dpp v117, -v165, v22 quad_perm:[2,2,2,2] row_mask:0xf bank_mask:0xf
	v_fmac_f32_dpp v118, -v164, v23 quad_perm:[3,3,3,3] row_mask:0xf bank_mask:0xf
	v_fmac_f32_dpp v119, -v165, v24 quad_perm:[3,3,3,3] row_mask:0xf bank_mask:0xf
	ds_read_b64 v[206:207], v125 offset:10192
	v_fmac_f32_dpp v116, -v166, v25 quad_perm:[0,0,0,0] row_mask:0xf bank_mask:0xf
	v_fmac_f32_dpp v117, -v167, v27 quad_perm:[0,0,0,0] row_mask:0xf bank_mask:0xf
	v_fmac_f32_dpp v118, -v166, v28 quad_perm:[1,1,1,1] row_mask:0xf bank_mask:0xf
	ds_read_b32 v219, v124 offset:148
	v_fmac_f32_dpp v119, -v167, v29 quad_perm:[1,1,1,1] row_mask:0xf bank_mask:0xf
	v_fmac_f32_dpp v116, -v166, v30 quad_perm:[2,2,2,2] row_mask:0xf bank_mask:0xf
	v_fmac_f32_dpp v117, -v167, v31 quad_perm:[2,2,2,2] row_mask:0xf bank_mask:0xf
	ds_read_u16_d16_hi v245, v123 offset:10064
	v_fmac_f32_dpp v118, -v166, v32 quad_perm:[3,3,3,3] row_mask:0xf bank_mask:0xf
	v_fmac_f32_dpp v119, -v167, v33 quad_perm:[3,3,3,3] row_mask:0xf bank_mask:0xf
	v_fmac_f32_dpp v116, -v168, v34 quad_perm:[0,0,0,0] row_mask:0xf bank_mask:0xf
	v_fmac_f32_dpp v117, -v169, v35 quad_perm:[0,0,0,0] row_mask:0xf bank_mask:0xf
	v_fmac_f32_dpp v118, -v168, v36 quad_perm:[1,1,1,1] row_mask:0xf bank_mask:0xf
	v_fmac_f32_dpp v119, -v169, v37 quad_perm:[1,1,1,1] row_mask:0xf bank_mask:0xf
	v_fmac_f32_dpp v116, -v168, v38 quad_perm:[2,2,2,2] row_mask:0xf bank_mask:0xf
	v_fmac_f32_dpp v117, -v169, v39 quad_perm:[2,2,2,2] row_mask:0xf bank_mask:0xf
	v_fmac_f32_dpp v118, -v168, v40 quad_perm:[3,3,3,3] row_mask:0xf bank_mask:0xf
	v_fmac_f32_dpp v119, -v169, v41 quad_perm:[3,3,3,3] row_mask:0xf bank_mask:0xf
	v_fmac_f32_dpp v116, -v170, v42 quad_perm:[0,0,0,0] row_mask:0xf bank_mask:0xf
	v_fmac_f32_dpp v117, -v171, v43 quad_perm:[0,0,0,0] row_mask:0xf bank_mask:0xf
	v_add_f32_e32 v121, v117, v116
	v_add_f32_e32 v122, v118, v119
	v_add_f32_e32 v44, v122, v121
	s_waitcnt lgkmcnt(14)
; #define GDN_LOADROW(buf, rr_, i_) do { _Pragma("unroll") for (int j4 = 0; j4 < ((i_) + 3) / 4; ++j4) buf[j4] = *(const f32x4*)(Lm + (i_) * GP_LSTR + 4 * j4); rr_ = bf2f(*(const bf16*)(xsrc + (i_) * GP_STR * 2)) * scl[i_]; } while (0)
; template <int STRIP> __device__ __forceinline__ void ph_gdn_prep_fast(const bf16* __restrict__ proj, const float* __restrict__ small, const float* __restrict__ conv_w, const float* __restrict__ a_log, const float* __restrict__ dt_bias, ...
;     ...
; #pragma unroll
;             for (int i = 0; i < 64; i += 2) {
;                 GDN_LOADROW(bB, rB, i + 1);
;                 GDN_ROW(bA, rA, i);
;                 if (i + 2 < 64) GDN_LOADROW(bA, rA, i + 2);
;                 GDN_ROW(bB, rB, i + 1);
	v_mul_f32_dpp v120, v172, v4 quad_perm:[0,0,0,0] row_mask:0xf bank_mask:0xf
	v_fma_f32 v116, v217, v127, -v120
	v_mul_f32_dpp v117, -v173, v5 quad_perm:[0,0,0,0] row_mask:0xf bank_mask:0xf
	v_mul_f32_dpp v118, -v172, v6 quad_perm:[1,1,1,1] row_mask:0xf bank_mask:0xf
	v_mul_f32_dpp v119, -v173, v12 quad_perm:[1,1,1,1] row_mask:0xf bank_mask:0xf
	ds_read_b64 v[132:133], v125 offset:10336
	v_fmac_f32_dpp v116, -v172, v7 quad_perm:[2,2,2,2] row_mask:0xf bank_mask:0xf
	v_fmac_f32_dpp v117, -v173, v13 quad_perm:[2,2,2,2] row_mask:0xf bank_mask:0xf
	v_fmac_f32_dpp v118, -v172, v14 quad_perm:[3,3,3,3] row_mask:0xf bank_mask:0xf
	ds_read_b64 v[134:135], v125 offset:10368
	v_fmac_f32_dpp v119, -v173, v15 quad_perm:[3,3,3,3] row_mask:0xf bank_mask:0xf
	v_fmac_f32_dpp v116, -v174, v16 quad_perm:[0,0,0,0] row_mask:0xf bank_mask:0xf
	v_fmac_f32_dpp v117, -v175, v17 quad_perm:[0,0,0,0] row_mask:0xf bank_mask:0xf
	ds_read_b64 v[136:137], v125 offset:10400
	v_fmac_f32_dpp v118, -v174, v19 quad_perm:[1,1,1,1] row_mask:0xf bank_mask:0xf
	v_fmac_f32_dpp v119, -v175, v20 quad_perm:[1,1,1,1] row_mask:0xf bank_mask:0xf
	v_fmac_f32_dpp v116, -v174, v21 quad_perm:[2,2,2,2] row_mask:0xf bank_mask:0xf
	ds_read_b64 v[138:139], v125 offset:10432
	v_fmac_f32_dpp v117, -v175, v22 quad_perm:[2,2,2,2] row_mask:0xf bank_mask:0xf
	v_fmac_f32_dpp v118, -v174, v23 quad_perm:[3,3,3,3] row_mask:0xf bank_mask:0xf
	v_fmac_f32_dpp v119, -v175, v24 quad_perm:[3,3,3,3] row_mask:0xf bank_mask:0xf
	ds_read_b64 v[140:141], v125 offset:10464
	v_fmac_f32_dpp v116, -v176, v25 quad_perm:[0,0,0,0] row_mask:0xf bank_mask:0xf
	v_fmac_f32_dpp v117, -v177, v27 quad_perm:[0,0,0,0] row_mask:0xf bank_mask:0xf
	v_fmac_f32_dpp v118, -v176, v28 quad_perm:[1,1,1,1] row_mask:0xf bank_mask:0xf
	ds_read_b32 v220, v124 offset:152
	v_fmac_f32_dpp v119, -v177, v29 quad_perm:[1,1,1,1] row_mask:0xf bank_mask:0xf
	v_fmac_f32_dpp v116, -v176, v30 quad_perm:[2,2,2,2] row_mask:0xf bank_mask:0xf
	v_fmac_f32_dpp v117, -v177, v31 quad_perm:[2,2,2,2] row_mask:0xf bank_mask:0xf
	ds_read_u16_d16_hi v246, v123 offset:10336
	v_fmac_f32_dpp v118, -v176, v32 quad_perm:[3,3,3,3] row_mask:0xf bank_mask:0xf
	v_fmac_f32_dpp v119, -v177, v33 quad_perm:[3,3,3,3] row_mask:0xf bank_mask:0xf
	v_fmac_f32_dpp v116, -v178, v34 quad_perm:[0,0,0,0] row_mask:0xf bank_mask:0xf
	v_fmac_f32_dpp v117, -v179, v35 quad_perm:[0,0,0,0] row_mask:0xf bank_mask:0xf
	v_fmac_f32_dpp v118, -v178, v36 quad_perm:[1,1,1,1] row_mask:0xf bank_mask:0xf
	v_fmac_f32_dpp v119, -v179, v37 quad_perm:[1,1,1,1] row_mask:0xf bank_mask:0xf
	v_fmac_f32_dpp v116, -v178, v38 quad_perm:[2,2,2,2] row_mask:0xf bank_mask:0xf
	v_fmac_f32_dpp v117, -v179, v39 quad_perm:[2,2,2,2] row_mask:0xf bank_mask:0xf
	v_fmac_f32_dpp v118, -v178, v40 quad_perm:[3,3,3,3] row_mask:0xf bank_mask:0xf
	v_fmac_f32_dpp v119, -v179, v41 quad_perm:[3,3,3,3] row_mask:0xf bank_mask:0xf
	v_fmac_f32_dpp v116, -v186, v42 quad_perm:[0,0,0,0] row_mask:0xf bank_mask:0xf
	v_fmac_f32_dpp v117, -v187, v43 quad_perm:[0,0,0,0] row_mask:0xf bank_mask:0xf
	v_fmac_f32_dpp v118, -v186, v44 quad_perm:[1,1,1,1] row_mask:0xf bank_mask:0xf
	v_add_f32_e32 v121, v117, v116
	v_add_f32_e32 v122, v118, v119
	v_add_f32_e32 v45, v122, v121
	s_waitcnt lgkmcnt(14)
	v_mul_f32_dpp v120, v188, v4 quad_perm:[0,0,0,0] row_mask:0xf bank_mask:0xf
	v_fma_f32 v116, v218, v244, -v120
	v_mul_f32_dpp v117, -v189, v5 quad_perm:[0,0,0,0] row_mask:0xf bank_mask:0xf
	v_mul_f32_dpp v118, -v188, v6 quad_perm:[1,1,1,1] row_mask:0xf bank_mask:0xf
	v_mul_f32_dpp v119, -v189, v12 quad_perm:[1,1,1,1] row_mask:0xf bank_mask:0xf
	ds_read_b64 v[142:143], v125 offset:10608
	v_fmac_f32_dpp v116, -v188, v7 quad_perm:[2,2,2,2] row_mask:0xf bank_mask:0xf
	v_fmac_f32_dpp v117, -v189, v13 quad_perm:[2,2,2,2] row_mask:0xf bank_mask:0xf
	v_fmac_f32_dpp v118, -v188, v14 quad_perm:[3,3,3,3] row_mask:0xf bank_mask:0xf
	ds_read_b64 v[144:145], v125 offset:10640
	v_fmac_f32_dpp v119, -v189, v15 quad_perm:[3,3,3,3] row_mask:0xf bank_mask:0xf
	v_fmac_f32_dpp v116, -v190, v16 quad_perm:[0,0,0,0] row_mask:0xf bank_mask:0xf
	v_fmac_f32_dpp v117, -v191, v17 quad_perm:[0,0,0,0] row_mask:0xf bank_mask:0xf
	ds_read_b64 v[146:147], v125 offset:10672
	v_fmac_f32_dpp v118, -v190, v19 quad_perm:[1,1,1,1] row_mask:0xf bank_mask:0xf
	v_fmac_f32_dpp v119, -v191, v20 quad_perm:[1,1,1,1] row_mask:0xf bank_mask:0xf
	v_fmac_f32_dpp v116, -v190, v21 quad_perm:[2,2,2,2] row_mask:0xf bank_mask:0xf
	ds_read_b64 v[148:149], v125 offset:10704
	v_fmac_f32_dpp v117, -v191, v22 quad_perm:[2,2,2,2] row_mask:0xf bank_mask:0xf
	v_fmac_f32_dpp v118, -v190, v23 quad_perm:[3,3,3,3] row_mask:0xf bank_mask:0xf
	v_fmac_f32_dpp v119, -v191, v24 quad_perm:[3,3,3,3] row_mask:0xf bank_mask:0xf
	ds_read_b64 v[150:151], v125 offset:10736
	v_fmac_f32_dpp v116, -v192, v25 quad_perm:[0,0,0,0] row_mask:0xf bank_mask:0xf
	v_fmac_f32_dpp v117, -v193, v27 quad_perm:[0,0,0,0] row_mask:0xf bank_mask:0xf
	v_fmac_f32_dpp v118, -v192, v28 quad_perm:[1,1,1,1] row_mask:0xf bank_mask:0xf
	ds_read_b32 v221, v124 offset:156
	v_fmac_f32_dpp v119, -v193, v29 quad_perm:[1,1,1,1] row_mask:0xf bank_mask:0xf
	v_fmac_f32_dpp v116, -v192, v30 quad_perm:[2,2,2,2] row_mask:0xf bank_mask:0xf
	v_fmac_f32_dpp v117, -v193, v31 quad_perm:[2,2,2,2] row_mask:0xf bank_mask:0xf
	ds_read_u16_d16_hi v247, v123 offset:10608
	v_fmac_f32_dpp v118, -v192, v32 quad_perm:[3,3,3,3] row_mask:0xf bank_mask:0xf
	v_fmac_f32_dpp v119, -v193, v33 quad_perm:[3,3,3,3] row_mask:0xf bank_mask:0xf
	v_fmac_f32_dpp v116, -v194, v34 quad_perm:[0,0,0,0] row_mask:0xf bank_mask:0xf
	v_fmac_f32_dpp v117, -v195, v35 quad_perm:[0,0,0,0] row_mask:0xf bank_mask:0xf
	v_fmac_f32_dpp v118, -v194, v36 quad_perm:[1,1,1,1] row_mask:0xf bank_mask:0xf
	v_fmac_f32_dpp v119, -v195, v37 quad_perm:[1,1,1,1] row_mask:0xf bank_mask:0xf
	v_fmac_f32_dpp v116, -v194, v38 quad_perm:[2,2,2,2] row_mask:0xf bank_mask:0xf
	v_fmac_f32_dpp v117, -v195, v39 quad_perm:[2,2,2,2] row_mask:0xf bank_mask:0xf
	v_fmac_f32_dpp v118, -v194, v40 quad_perm:[3,3,3,3] row_mask:0xf bank_mask:0xf
	v_fmac_f32_dpp v119, -v195, v41 quad_perm:[3,3,3,3] row_mask:0xf bank_mask:0xf
	v_fmac_f32_dpp v116, -v196, v42 quad_perm:[0,0,0,0] row_mask:0xf bank_mask:0xf
	v_fmac_f32_dpp v117, -v197, v43 quad_perm:[0,0,0,0] row_mask:0xf bank_mask:0xf
	v_fmac_f32_dpp v118, -v196, v44 quad_perm:[1,1,1,1] row_mask:0xf bank_mask:0xf
	v_fmac_f32_dpp v119, -v197, v45 quad_perm:[1,1,1,1] row_mask:0xf bank_mask:0xf
	v_add_f32_e32 v121, v117, v116
	v_add_f32_e32 v122, v118, v119
	v_add_f32_e32 v46, v122, v121
	s_waitcnt lgkmcnt(14)
; #define GDN_LOADROW(buf, rr_, i_) do { _Pragma("unroll") for (int j4 = 0; j4 < ((i_) + 3) / 4; ++j4) buf[j4] = *(const f32x4*)(Lm + (i_) * GP_LSTR + 4 * j4); rr_ = bf2f(*(const bf16*)(xsrc + (i_) * GP_STR * 2)) * scl[i_]; } while (0)
; template <int STRIP> __device__ __forceinline__ void ph_gdn_prep_fast(const bf16* __restrict__ proj, const float* __restrict__ small, const float* __restrict__ conv_w, const float* __restrict__ a_log, const float* __restrict__ dt_bias, ...
;     ...
; #pragma unroll
;             for (int i = 0; i < 64; i += 2) {
;                 GDN_LOADROW(bB, rB, i + 1);
;                 GDN_ROW(bA, rA, i);
;                 if (i + 2 < 64) GDN_LOADROW(bA, rA, i + 2);
;                 GDN_ROW(bB, rB, i + 1);
	v_mul_f32_dpp v120, v198, v4 quad_perm:[0,0,0,0] row_mask:0xf bank_mask:0xf
	v_fma_f32 v116, v219, v245, -v120
	v_mul_f32_dpp v117, -v199, v5 quad_perm:[0,0,0,0] row_mask:0xf bank_mask:0xf
	v_mul_f32_dpp v118, -v198, v6 quad_perm:[1,1,1,1] row_mask:0xf bank_mask:0xf
	v_mul_f32_dpp v119, -v199, v12 quad_perm:[1,1,1,1] row_mask:0xf bank_mask:0xf
	ds_read_b64 v[152:153], v125 offset:10880
	v_fmac_f32_dpp v116, -v198, v7 quad_perm:[2,2,2,2] row_mask:0xf bank_mask:0xf
	v_fmac_f32_dpp v117, -v199, v13 quad_perm:[2,2,2,2] row_mask:0xf bank_mask:0xf
	v_fmac_f32_dpp v118, -v198, v14 quad_perm:[3,3,3,3] row_mask:0xf bank_mask:0xf
	ds_read_b64 v[154:155], v125 offset:10912
	v_fmac_f32_dpp v119, -v199, v15 quad_perm:[3,3,3,3] row_mask:0xf bank_mask:0xf
	v_fmac_f32_dpp v116, -v200, v16 quad_perm:[0,0,0,0] row_mask:0xf bank_mask:0xf
	v_fmac_f32_dpp v117, -v201, v17 quad_perm:[0,0,0,0] row_mask:0xf bank_mask:0xf
	ds_read_b64 v[156:157], v125 offset:10944
	v_fmac_f32_dpp v118, -v200, v19 quad_perm:[1,1,1,1] row_mask:0xf bank_mask:0xf
	v_fmac_f32_dpp v119, -v201, v20 quad_perm:[1,1,1,1] row_mask:0xf bank_mask:0xf
	v_fmac_f32_dpp v116, -v200, v21 quad_perm:[2,2,2,2] row_mask:0xf bank_mask:0xf
	ds_read_b64 v[158:159], v125 offset:10976
	v_fmac_f32_dpp v117, -v201, v22 quad_perm:[2,2,2,2] row_mask:0xf bank_mask:0xf
	v_fmac_f32_dpp v118, -v200, v23 quad_perm:[3,3,3,3] row_mask:0xf bank_mask:0xf
	v_fmac_f32_dpp v119, -v201, v24 quad_perm:[3,3,3,3] row_mask:0xf bank_mask:0xf
	ds_read_b64 v[160:161], v125 offset:11008
	v_fmac_f32_dpp v116, -v202, v25 quad_perm:[0,0,0,0] row_mask:0xf bank_mask:0xf
	v_fmac_f32_dpp v117, -v203, v27 quad_perm:[0,0,0,0] row_mask:0xf bank_mask:0xf
	v_fmac_f32_dpp v118, -v202, v28 quad_perm:[1,1,1,1] row_mask:0xf bank_mask:0xf
	ds_read_b32 v222, v124 offset:160
	v_fmac_f32_dpp v119, -v203, v29 quad_perm:[1,1,1,1] row_mask:0xf bank_mask:0xf
	v_fmac_f32_dpp v116, -v202, v30 quad_perm:[2,2,2,2] row_mask:0xf bank_mask:0xf
	v_fmac_f32_dpp v117, -v203, v31 quad_perm:[2,2,2,2] row_mask:0xf bank_mask:0xf
	ds_read_u16_d16_hi v248, v123 offset:10880
	v_fmac_f32_dpp v118, -v202, v32 quad_perm:[3,3,3,3] row_mask:0xf bank_mask:0xf
	v_fmac_f32_dpp v119, -v203, v33 quad_perm:[3,3,3,3] row_mask:0xf bank_mask:0xf
	v_fmac_f32_dpp v116, -v204, v34 quad_perm:[0,0,0,0] row_mask:0xf bank_mask:0xf
	v_fmac_f32_dpp v117, -v205, v35 quad_perm:[0,0,0,0] row_mask:0xf bank_mask:0xf
	v_fmac_f32_dpp v118, -v204, v36 quad_perm:[1,1,1,1] row_mask:0xf bank_mask:0xf
	v_fmac_f32_dpp v119, -v205, v37 quad_perm:[1,1,1,1] row_mask:0xf bank_mask:0xf
	v_fmac_f32_dpp v116, -v204, v38 quad_perm:[2,2,2,2] row_mask:0xf bank_mask:0xf
	v_fmac_f32_dpp v117, -v205, v39 quad_perm:[2,2,2,2] row_mask:0xf bank_mask:0xf
	v_fmac_f32_dpp v118, -v204, v40 quad_perm:[3,3,3,3] row_mask:0xf bank_mask:0xf
	v_fmac_f32_dpp v119, -v205, v41 quad_perm:[3,3,3,3] row_mask:0xf bank_mask:0xf
	v_fmac_f32_dpp v116, -v206, v42 quad_perm:[0,0,0,0] row_mask:0xf bank_mask:0xf
	v_fmac_f32_dpp v117, -v207, v43 quad_perm:[0,0,0,0] row_mask:0xf bank_mask:0xf
	v_fmac_f32_dpp v118, -v206, v44 quad_perm:[1,1,1,1] row_mask:0xf bank_mask:0xf
	v_fmac_f32_dpp v119, -v207, v45 quad_perm:[1,1,1,1] row_mask:0xf bank_mask:0xf
	v_fmac_f32_dpp v116, -v206, v46 quad_perm:[2,2,2,2] row_mask:0xf bank_mask:0xf
	v_add_f32_e32 v121, v117, v116
	v_add_f32_e32 v122, v118, v119
	v_add_f32_e32 v47, v122, v121
	s_waitcnt lgkmcnt(14)
	v_mul_f32_dpp v120, v132, v4 quad_perm:[0,0,0,0] row_mask:0xf bank_mask:0xf
	v_fma_f32 v116, v220, v246, -v120
	v_mul_f32_dpp v117, -v133, v5 quad_perm:[0,0,0,0] row_mask:0xf bank_mask:0xf
	v_mul_f32_dpp v118, -v132, v6 quad_perm:[1,1,1,1] row_mask:0xf bank_mask:0xf
	v_mul_f32_dpp v119, -v133, v12 quad_perm:[1,1,1,1] row_mask:0xf bank_mask:0xf
	ds_read_b64 v[162:163], v125 offset:11152
	v_fmac_f32_dpp v116, -v132, v7 quad_perm:[2,2,2,2] row_mask:0xf bank_mask:0xf
	v_fmac_f32_dpp v117, -v133, v13 quad_perm:[2,2,2,2] row_mask:0xf bank_mask:0xf
	v_fmac_f32_dpp v118, -v132, v14 quad_perm:[3,3,3,3] row_mask:0xf bank_mask:0xf
	ds_read_b64 v[164:165], v125 offset:11184
	v_fmac_f32_dpp v119, -v133, v15 quad_perm:[3,3,3,3] row_mask:0xf bank_mask:0xf
	v_fmac_f32_dpp v116, -v134, v16 quad_perm:[0,0,0,0] row_mask:0xf bank_mask:0xf
	v_fmac_f32_dpp v117, -v135, v17 quad_perm:[0,0,0,0] row_mask:0xf bank_mask:0xf
	ds_read_b64 v[166:167], v125 offset:11216
	v_fmac_f32_dpp v118, -v134, v19 quad_perm:[1,1,1,1] row_mask:0xf bank_mask:0xf
	v_fmac_f32_dpp v119, -v135, v20 quad_perm:[1,1,1,1] row_mask:0xf bank_mask:0xf
	v_fmac_f32_dpp v116, -v134, v21 quad_perm:[2,2,2,2] row_mask:0xf bank_mask:0xf
	ds_read_b64 v[168:169], v125 offset:11248
	v_fmac_f32_dpp v117, -v135, v22 quad_perm:[2,2,2,2] row_mask:0xf bank_mask:0xf
	v_fmac_f32_dpp v118, -v134, v23 quad_perm:[3,3,3,3] row_mask:0xf bank_mask:0xf
	v_fmac_f32_dpp v119, -v135, v24 quad_perm:[3,3,3,3] row_mask:0xf bank_mask:0xf
	ds_read_b64 v[170:171], v125 offset:11280
	v_fmac_f32_dpp v116, -v136, v25 quad_perm:[0,0,0,0] row_mask:0xf bank_mask:0xf
	v_fmac_f32_dpp v117, -v137, v27 quad_perm:[0,0,0,0] row_mask:0xf bank_mask:0xf
	v_fmac_f32_dpp v118, -v136, v28 quad_perm:[1,1,1,1] row_mask:0xf bank_mask:0xf
	ds_read_b64 v[172:173], v125 offset:11312
	v_fmac_f32_dpp v119, -v137, v29 quad_perm:[1,1,1,1] row_mask:0xf bank_mask:0xf
	v_fmac_f32_dpp v116, -v136, v30 quad_perm:[2,2,2,2] row_mask:0xf bank_mask:0xf
	v_fmac_f32_dpp v117, -v137, v31 quad_perm:[2,2,2,2] row_mask:0xf bank_mask:0xf
	ds_read_b32 v223, v124 offset:164
	v_fmac_f32_dpp v118, -v136, v32 quad_perm:[3,3,3,3] row_mask:0xf bank_mask:0xf
	v_fmac_f32_dpp v119, -v137, v33 quad_perm:[3,3,3,3] row_mask:0xf bank_mask:0xf
	v_fmac_f32_dpp v116, -v138, v34 quad_perm:[0,0,0,0] row_mask:0xf bank_mask:0xf
	ds_read_u16_d16_hi v249, v123 offset:11152
	v_fmac_f32_dpp v117, -v139, v35 quad_perm:[0,0,0,0] row_mask:0xf bank_mask:0xf
	v_fmac_f32_dpp v118, -v138, v36 quad_perm:[1,1,1,1] row_mask:0xf bank_mask:0xf
	v_fmac_f32_dpp v119, -v139, v37 quad_perm:[1,1,1,1] row_mask:0xf bank_mask:0xf
	v_fmac_f32_dpp v116, -v138, v38 quad_perm:[2,2,2,2] row_mask:0xf bank_mask:0xf
	v_fmac_f32_dpp v117, -v139, v39 quad_perm:[2,2,2,2] row_mask:0xf bank_mask:0xf
	v_fmac_f32_dpp v118, -v138, v40 quad_perm:[3,3,3,3] row_mask:0xf bank_mask:0xf
	v_fmac_f32_dpp v119, -v139, v41 quad_perm:[3,3,3,3] row_mask:0xf bank_mask:0xf
	v_fmac_f32_dpp v116, -v140, v42 quad_perm:[0,0,0,0] row_mask:0xf bank_mask:0xf
	v_fmac_f32_dpp v117, -v141, v43 quad_perm:[0,0,0,0] row_mask:0xf bank_mask:0xf
	v_fmac_f32_dpp v118, -v140, v44 quad_perm:[1,1,1,1] row_mask:0xf bank_mask:0xf
	v_fmac_f32_dpp v119, -v141, v45 quad_perm:[1,1,1,1] row_mask:0xf bank_mask:0xf
	v_fmac_f32_dpp v116, -v140, v46 quad_perm:[2,2,2,2] row_mask:0xf bank_mask:0xf
	v_fmac_f32_dpp v117, -v141, v47 quad_perm:[2,2,2,2] row_mask:0xf bank_mask:0xf
	v_add_f32_e32 v121, v117, v116
	v_add_f32_e32 v122, v118, v119
	v_add_f32_e32 v48, v122, v121
	s_waitcnt lgkmcnt(15)
; #define GDN_LOADROW(buf, rr_, i_) do { _Pragma("unroll") for (int j4 = 0; j4 < ((i_) + 3) / 4; ++j4) buf[j4] = *(const f32x4*)(Lm + (i_) * GP_LSTR + 4 * j4); rr_ = bf2f(*(const bf16*)(xsrc + (i_) * GP_STR * 2)) * scl[i_]; } while (0)
; template <int STRIP> __device__ __forceinline__ void ph_gdn_prep_fast(const bf16* __restrict__ proj, const float* __restrict__ small, const float* __restrict__ conv_w, const float* __restrict__ a_log, const float* __restrict__ dt_bias, ...
;     ...
; #pragma unroll
;             for (int i = 0; i < 64; i += 2) {
;                 GDN_LOADROW(bB, rB, i + 1);
;                 GDN_ROW(bA, rA, i);
;                 if (i + 2 < 64) GDN_LOADROW(bA, rA, i + 2);
;                 GDN_ROW(bB, rB, i + 1);
	v_mul_f32_dpp v120, v142, v4 quad_perm:[0,0,0,0] row_mask:0xf bank_mask:0xf
	v_fma_f32 v116, v221, v247, -v120
	v_mul_f32_dpp v117, -v143, v5 quad_perm:[0,0,0,0] row_mask:0xf bank_mask:0xf
	v_mul_f32_dpp v118, -v142, v6 quad_perm:[1,1,1,1] row_mask:0xf bank_mask:0xf
	v_mul_f32_dpp v119, -v143, v12 quad_perm:[1,1,1,1] row_mask:0xf bank_mask:0xf
	ds_read_b64 v[174:175], v125 offset:11424
	v_fmac_f32_dpp v116, -v142, v7 quad_perm:[2,2,2,2] row_mask:0xf bank_mask:0xf
	v_fmac_f32_dpp v117, -v143, v13 quad_perm:[2,2,2,2] row_mask:0xf bank_mask:0xf
	v_fmac_f32_dpp v118, -v142, v14 quad_perm:[3,3,3,3] row_mask:0xf bank_mask:0xf
	ds_read_b64 v[176:177], v125 offset:11456
	v_fmac_f32_dpp v119, -v143, v15 quad_perm:[3,3,3,3] row_mask:0xf bank_mask:0xf
	v_fmac_f32_dpp v116, -v144, v16 quad_perm:[0,0,0,0] row_mask:0xf bank_mask:0xf
	v_fmac_f32_dpp v117, -v145, v17 quad_perm:[0,0,0,0] row_mask:0xf bank_mask:0xf
	ds_read_b64 v[178:179], v125 offset:11488
	v_fmac_f32_dpp v118, -v144, v19 quad_perm:[1,1,1,1] row_mask:0xf bank_mask:0xf
	v_fmac_f32_dpp v119, -v145, v20 quad_perm:[1,1,1,1] row_mask:0xf bank_mask:0xf
	v_fmac_f32_dpp v116, -v144, v21 quad_perm:[2,2,2,2] row_mask:0xf bank_mask:0xf
	ds_read_b64 v[186:187], v125 offset:11520
	v_fmac_f32_dpp v117, -v145, v22 quad_perm:[2,2,2,2] row_mask:0xf bank_mask:0xf
	v_fmac_f32_dpp v118, -v144, v23 quad_perm:[3,3,3,3] row_mask:0xf bank_mask:0xf
	v_fmac_f32_dpp v119, -v145, v24 quad_perm:[3,3,3,3] row_mask:0xf bank_mask:0xf
	ds_read_b64 v[188:189], v125 offset:11552
	v_fmac_f32_dpp v116, -v146, v25 quad_perm:[0,0,0,0] row_mask:0xf bank_mask:0xf
	v_fmac_f32_dpp v117, -v147, v27 quad_perm:[0,0,0,0] row_mask:0xf bank_mask:0xf
	v_fmac_f32_dpp v118, -v146, v28 quad_perm:[1,1,1,1] row_mask:0xf bank_mask:0xf
	ds_read_b64 v[190:191], v125 offset:11584
	v_fmac_f32_dpp v119, -v147, v29 quad_perm:[1,1,1,1] row_mask:0xf bank_mask:0xf
	v_fmac_f32_dpp v116, -v146, v30 quad_perm:[2,2,2,2] row_mask:0xf bank_mask:0xf
	v_fmac_f32_dpp v117, -v147, v31 quad_perm:[2,2,2,2] row_mask:0xf bank_mask:0xf
	ds_read_b32 v224, v124 offset:168
	v_fmac_f32_dpp v118, -v146, v32 quad_perm:[3,3,3,3] row_mask:0xf bank_mask:0xf
	v_fmac_f32_dpp v119, -v147, v33 quad_perm:[3,3,3,3] row_mask:0xf bank_mask:0xf
	v_fmac_f32_dpp v116, -v148, v34 quad_perm:[0,0,0,0] row_mask:0xf bank_mask:0xf
	ds_read_u16_d16_hi v250, v123 offset:11424
	v_fmac_f32_dpp v117, -v149, v35 quad_perm:[0,0,0,0] row_mask:0xf bank_mask:0xf
	v_fmac_f32_dpp v118, -v148, v36 quad_perm:[1,1,1,1] row_mask:0xf bank_mask:0xf
	v_fmac_f32_dpp v119, -v149, v37 quad_perm:[1,1,1,1] row_mask:0xf bank_mask:0xf
	v_fmac_f32_dpp v116, -v148, v38 quad_perm:[2,2,2,2] row_mask:0xf bank_mask:0xf
	v_fmac_f32_dpp v117, -v149, v39 quad_perm:[2,2,2,2] row_mask:0xf bank_mask:0xf
	v_fmac_f32_dpp v118, -v148, v40 quad_perm:[3,3,3,3] row_mask:0xf bank_mask:0xf
	v_fmac_f32_dpp v119, -v149, v41 quad_perm:[3,3,3,3] row_mask:0xf bank_mask:0xf
	v_fmac_f32_dpp v116, -v150, v42 quad_perm:[0,0,0,0] row_mask:0xf bank_mask:0xf
	v_fmac_f32_dpp v117, -v151, v43 quad_perm:[0,0,0,0] row_mask:0xf bank_mask:0xf
	v_fmac_f32_dpp v118, -v150, v44 quad_perm:[1,1,1,1] row_mask:0xf bank_mask:0xf
	v_fmac_f32_dpp v119, -v151, v45 quad_perm:[1,1,1,1] row_mask:0xf bank_mask:0xf
	v_fmac_f32_dpp v116, -v150, v46 quad_perm:[2,2,2,2] row_mask:0xf bank_mask:0xf
	v_fmac_f32_dpp v117, -v151, v47 quad_perm:[2,2,2,2] row_mask:0xf bank_mask:0xf
	v_fmac_f32_dpp v118, -v150, v48 quad_perm:[3,3,3,3] row_mask:0xf bank_mask:0xf
	v_add_f32_e32 v121, v117, v116
	v_add_f32_e32 v122, v118, v119
	v_add_f32_e32 v49, v122, v121
	s_waitcnt lgkmcnt(15)
	v_mul_f32_dpp v120, v152, v4 quad_perm:[0,0,0,0] row_mask:0xf bank_mask:0xf
	v_fma_f32 v116, v222, v248, -v120
	v_mul_f32_dpp v117, -v153, v5 quad_perm:[0,0,0,0] row_mask:0xf bank_mask:0xf
	v_mul_f32_dpp v118, -v152, v6 quad_perm:[1,1,1,1] row_mask:0xf bank_mask:0xf
	v_mul_f32_dpp v119, -v153, v12 quad_perm:[1,1,1,1] row_mask:0xf bank_mask:0xf
	ds_read_b64 v[192:193], v125 offset:11696
	v_fmac_f32_dpp v116, -v152, v7 quad_perm:[2,2,2,2] row_mask:0xf bank_mask:0xf
	v_fmac_f32_dpp v117, -v153, v13 quad_perm:[2,2,2,2] row_mask:0xf bank_mask:0xf
	v_fmac_f32_dpp v118, -v152, v14 quad_perm:[3,3,3,3] row_mask:0xf bank_mask:0xf
	ds_read_b64 v[194:195], v125 offset:11728
	v_fmac_f32_dpp v119, -v153, v15 quad_perm:[3,3,3,3] row_mask:0xf bank_mask:0xf
	v_fmac_f32_dpp v116, -v154, v16 quad_perm:[0,0,0,0] row_mask:0xf bank_mask:0xf
	v_fmac_f32_dpp v117, -v155, v17 quad_perm:[0,0,0,0] row_mask:0xf bank_mask:0xf
	ds_read_b64 v[196:197], v125 offset:11760
	v_fmac_f32_dpp v118, -v154, v19 quad_perm:[1,1,1,1] row_mask:0xf bank_mask:0xf
	v_fmac_f32_dpp v119, -v155, v20 quad_perm:[1,1,1,1] row_mask:0xf bank_mask:0xf
	v_fmac_f32_dpp v116, -v154, v21 quad_perm:[2,2,2,2] row_mask:0xf bank_mask:0xf
	ds_read_b64 v[198:199], v125 offset:11792
	v_fmac_f32_dpp v117, -v155, v22 quad_perm:[2,2,2,2] row_mask:0xf bank_mask:0xf
	v_fmac_f32_dpp v118, -v154, v23 quad_perm:[3,3,3,3] row_mask:0xf bank_mask:0xf
	v_fmac_f32_dpp v119, -v155, v24 quad_perm:[3,3,3,3] row_mask:0xf bank_mask:0xf
	ds_read_b64 v[200:201], v125 offset:11824
	v_fmac_f32_dpp v116, -v156, v25 quad_perm:[0,0,0,0] row_mask:0xf bank_mask:0xf
	v_fmac_f32_dpp v117, -v157, v27 quad_perm:[0,0,0,0] row_mask:0xf bank_mask:0xf
	v_fmac_f32_dpp v118, -v156, v28 quad_perm:[1,1,1,1] row_mask:0xf bank_mask:0xf
	ds_read_b64 v[202:203], v125 offset:11856
	v_fmac_f32_dpp v119, -v157, v29 quad_perm:[1,1,1,1] row_mask:0xf bank_mask:0xf
	v_fmac_f32_dpp v116, -v156, v30 quad_perm:[2,2,2,2] row_mask:0xf bank_mask:0xf
	v_fmac_f32_dpp v117, -v157, v31 quad_perm:[2,2,2,2] row_mask:0xf bank_mask:0xf
; #define GDN_LOADROW(buf, rr_, i_) do { _Pragma("unroll") for (int j4 = 0; j4 < ((i_) + 3) / 4; ++j4) buf[j4] = *(const f32x4*)(Lm + (i_) * GP_LSTR + 4 * j4); rr_ = bf2f(*(const bf16*)(xsrc + (i_) * GP_STR * 2)) * scl[i_]; } while (0)
; template <int STRIP> __device__ __forceinline__ void ph_gdn_prep_fast(const bf16* __restrict__ proj, const float* __restrict__ small, const float* __restrict__ conv_w, const float* __restrict__ a_log, const float* __restrict__ dt_bias, ...
;     ...
; #pragma unroll
;             for (int i = 0; i < 64; i += 2) {
;                 GDN_LOADROW(bB, rB, i + 1);
;                 GDN_ROW(bA, rA, i);
;                 if (i + 2 < 64) GDN_LOADROW(bA, rA, i + 2);
;                 GDN_ROW(bB, rB, i + 1);
	ds_read_b32 v225, v124 offset:172
	v_fmac_f32_dpp v118, -v156, v32 quad_perm:[3,3,3,3] row_mask:0xf bank_mask:0xf
	v_fmac_f32_dpp v119, -v157, v33 quad_perm:[3,3,3,3] row_mask:0xf bank_mask:0xf
	v_fmac_f32_dpp v116, -v158, v34 quad_perm:[0,0,0,0] row_mask:0xf bank_mask:0xf
	ds_read_u16_d16_hi v251, v123 offset:11696
	v_fmac_f32_dpp v117, -v159, v35 quad_perm:[0,0,0,0] row_mask:0xf bank_mask:0xf
	v_fmac_f32_dpp v118, -v158, v36 quad_perm:[1,1,1,1] row_mask:0xf bank_mask:0xf
	v_fmac_f32_dpp v119, -v159, v37 quad_perm:[1,1,1,1] row_mask:0xf bank_mask:0xf
	v_fmac_f32_dpp v116, -v158, v38 quad_perm:[2,2,2,2] row_mask:0xf bank_mask:0xf
	v_fmac_f32_dpp v117, -v159, v39 quad_perm:[2,2,2,2] row_mask:0xf bank_mask:0xf
	v_fmac_f32_dpp v118, -v158, v40 quad_perm:[3,3,3,3] row_mask:0xf bank_mask:0xf
	v_fmac_f32_dpp v119, -v159, v41 quad_perm:[3,3,3,3] row_mask:0xf bank_mask:0xf
	v_fmac_f32_dpp v116, -v160, v42 quad_perm:[0,0,0,0] row_mask:0xf bank_mask:0xf
	v_fmac_f32_dpp v117, -v161, v43 quad_perm:[0,0,0,0] row_mask:0xf bank_mask:0xf
	v_fmac_f32_dpp v118, -v160, v44 quad_perm:[1,1,1,1] row_mask:0xf bank_mask:0xf
	v_fmac_f32_dpp v119, -v161, v45 quad_perm:[1,1,1,1] row_mask:0xf bank_mask:0xf
	v_fmac_f32_dpp v116, -v160, v46 quad_perm:[2,2,2,2] row_mask:0xf bank_mask:0xf
	v_fmac_f32_dpp v117, -v161, v47 quad_perm:[2,2,2,2] row_mask:0xf bank_mask:0xf
	v_fmac_f32_dpp v118, -v160, v48 quad_perm:[3,3,3,3] row_mask:0xf bank_mask:0xf
	v_fmac_f32_dpp v119, -v161, v49 quad_perm:[3,3,3,3] row_mask:0xf bank_mask:0xf
	v_add_f32_e32 v121, v117, v116
	v_add_f32_e32 v122, v118, v119
	v_add_f32_e32 v50, v122, v121
	s_waitcnt lgkmcnt(15)
	v_mul_f32_dpp v120, v162, v4 quad_perm:[0,0,0,0] row_mask:0xf bank_mask:0xf
	v_fma_f32 v116, v223, v249, -v120
	v_mul_f32_dpp v117, -v163, v5 quad_perm:[0,0,0,0] row_mask:0xf bank_mask:0xf
	v_mul_f32_dpp v118, -v162, v6 quad_perm:[1,1,1,1] row_mask:0xf bank_mask:0xf
	v_mul_f32_dpp v119, -v163, v12 quad_perm:[1,1,1,1] row_mask:0xf bank_mask:0xf
	ds_read_b64 v[204:205], v125 offset:11968
	v_fmac_f32_dpp v116, -v162, v7 quad_perm:[2,2,2,2] row_mask:0xf bank_mask:0xf
	v_fmac_f32_dpp v117, -v163, v13 quad_perm:[2,2,2,2] row_mask:0xf bank_mask:0xf
	v_fmac_f32_dpp v118, -v162, v14 quad_perm:[3,3,3,3] row_mask:0xf bank_mask:0xf
	ds_read_b64 v[206:207], v125 offset:12000
	v_fmac_f32_dpp v119, -v163, v15 quad_perm:[3,3,3,3] row_mask:0xf bank_mask:0xf
	v_fmac_f32_dpp v116, -v164, v16 quad_perm:[0,0,0,0] row_mask:0xf bank_mask:0xf
	v_fmac_f32_dpp v117, -v165, v17 quad_perm:[0,0,0,0] row_mask:0xf bank_mask:0xf
	ds_read_b64 v[132:133], v125 offset:12032
	v_fmac_f32_dpp v118, -v164, v19 quad_perm:[1,1,1,1] row_mask:0xf bank_mask:0xf
	v_fmac_f32_dpp v119, -v165, v20 quad_perm:[1,1,1,1] row_mask:0xf bank_mask:0xf
	v_fmac_f32_dpp v116, -v164, v21 quad_perm:[2,2,2,2] row_mask:0xf bank_mask:0xf
	ds_read_b64 v[134:135], v125 offset:12064
	v_fmac_f32_dpp v117, -v165, v22 quad_perm:[2,2,2,2] row_mask:0xf bank_mask:0xf
	v_fmac_f32_dpp v118, -v164, v23 quad_perm:[3,3,3,3] row_mask:0xf bank_mask:0xf
	v_fmac_f32_dpp v119, -v165, v24 quad_perm:[3,3,3,3] row_mask:0xf bank_mask:0xf
	ds_read_b64 v[136:137], v125 offset:12096
	v_fmac_f32_dpp v116, -v166, v25 quad_perm:[0,0,0,0] row_mask:0xf bank_mask:0xf
	v_fmac_f32_dpp v117, -v167, v27 quad_perm:[0,0,0,0] row_mask:0xf bank_mask:0xf
	v_fmac_f32_dpp v118, -v166, v28 quad_perm:[1,1,1,1] row_mask:0xf bank_mask:0xf
	ds_read_b64 v[138:139], v125 offset:12128
	v_fmac_f32_dpp v119, -v167, v29 quad_perm:[1,1,1,1] row_mask:0xf bank_mask:0xf
	v_fmac_f32_dpp v116, -v166, v30 quad_perm:[2,2,2,2] row_mask:0xf bank_mask:0xf
	v_fmac_f32_dpp v117, -v167, v31 quad_perm:[2,2,2,2] row_mask:0xf bank_mask:0xf
	ds_read_b32 v226, v124 offset:176
	v_fmac_f32_dpp v118, -v166, v32 quad_perm:[3,3,3,3] row_mask:0xf bank_mask:0xf
	v_fmac_f32_dpp v119, -v167, v33 quad_perm:[3,3,3,3] row_mask:0xf bank_mask:0xf
	v_fmac_f32_dpp v116, -v168, v34 quad_perm:[0,0,0,0] row_mask:0xf bank_mask:0xf
	ds_read_u16_d16_hi v252, v123 offset:11968
	v_fmac_f32_dpp v117, -v169, v35 quad_perm:[0,0,0,0] row_mask:0xf bank_mask:0xf
	v_fmac_f32_dpp v118, -v168, v36 quad_perm:[1,1,1,1] row_mask:0xf bank_mask:0xf
	v_fmac_f32_dpp v119, -v169, v37 quad_perm:[1,1,1,1] row_mask:0xf bank_mask:0xf
	v_fmac_f32_dpp v116, -v168, v38 quad_perm:[2,2,2,2] row_mask:0xf bank_mask:0xf
	v_fmac_f32_dpp v117, -v169, v39 quad_perm:[2,2,2,2] row_mask:0xf bank_mask:0xf
	v_fmac_f32_dpp v118, -v168, v40 quad_perm:[3,3,3,3] row_mask:0xf bank_mask:0xf
	v_fmac_f32_dpp v119, -v169, v41 quad_perm:[3,3,3,3] row_mask:0xf bank_mask:0xf
	v_fmac_f32_dpp v116, -v170, v42 quad_perm:[0,0,0,0] row_mask:0xf bank_mask:0xf
	v_fmac_f32_dpp v117, -v171, v43 quad_perm:[0,0,0,0] row_mask:0xf bank_mask:0xf
	v_fmac_f32_dpp v118, -v170, v44 quad_perm:[1,1,1,1] row_mask:0xf bank_mask:0xf
	v_fmac_f32_dpp v119, -v171, v45 quad_perm:[1,1,1,1] row_mask:0xf bank_mask:0xf
	v_fmac_f32_dpp v116, -v170, v46 quad_perm:[2,2,2,2] row_mask:0xf bank_mask:0xf
	v_fmac_f32_dpp v117, -v171, v47 quad_perm:[2,2,2,2] row_mask:0xf bank_mask:0xf
	v_fmac_f32_dpp v118, -v170, v48 quad_perm:[3,3,3,3] row_mask:0xf bank_mask:0xf
	v_fmac_f32_dpp v119, -v171, v49 quad_perm:[3,3,3,3] row_mask:0xf bank_mask:0xf
	v_fmac_f32_dpp v116, -v172, v50 quad_perm:[0,0,0,0] row_mask:0xf bank_mask:0xf
	v_add_f32_e32 v121, v117, v116
	v_add_f32_e32 v122, v118, v119
	v_add_f32_e32 v51, v122, v121
	s_waitcnt lgkmcnt(15)
; #define GDN_LOADROW(buf, rr_, i_) do { _Pragma("unroll") for (int j4 = 0; j4 < ((i_) + 3) / 4; ++j4) buf[j4] = *(const f32x4*)(Lm + (i_) * GP_LSTR + 4 * j4); rr_ = bf2f(*(const bf16*)(xsrc + (i_) * GP_STR * 2)) * scl[i_]; } while (0)
; template <int STRIP> __device__ __forceinline__ void ph_gdn_prep_fast(const bf16* __restrict__ proj, const float* __restrict__ small, const float* __restrict__ conv_w, const float* __restrict__ a_log, const float* __restrict__ dt_bias, ...
;     ...
; #pragma unroll
;             for (int i = 0; i < 64; i += 2) {
;                 GDN_LOADROW(bB, rB, i + 1);
;                 GDN_ROW(bA, rA, i);
;                 if (i + 2 < 64) GDN_LOADROW(bA, rA, i + 2);
;                 GDN_ROW(bB, rB, i + 1);
	v_mul_f32_dpp v120, v174, v4 quad_perm:[0,0,0,0] row_mask:0xf bank_mask:0xf
	v_fma_f32 v116, v224, v250, -v120
	v_mul_f32_dpp v117, -v175, v5 quad_perm:[0,0,0,0] row_mask:0xf bank_mask:0xf
	v_mul_f32_dpp v118, -v174, v6 quad_perm:[1,1,1,1] row_mask:0xf bank_mask:0xf
	v_mul_f32_dpp v119, -v175, v12 quad_perm:[1,1,1,1] row_mask:0xf bank_mask:0xf
	ds_read_b64 v[140:141], v125 offset:12240
	v_fmac_f32_dpp v116, -v174, v7 quad_perm:[2,2,2,2] row_mask:0xf bank_mask:0xf
	v_fmac_f32_dpp v117, -v175, v13 quad_perm:[2,2,2,2] row_mask:0xf bank_mask:0xf
	v_fmac_f32_dpp v118, -v174, v14 quad_perm:[3,3,3,3] row_mask:0xf bank_mask:0xf
	ds_read_b64 v[142:143], v125 offset:12272
	v_fmac_f32_dpp v119, -v175, v15 quad_perm:[3,3,3,3] row_mask:0xf bank_mask:0xf
	v_fmac_f32_dpp v116, -v176, v16 quad_perm:[0,0,0,0] row_mask:0xf bank_mask:0xf
	v_fmac_f32_dpp v117, -v177, v17 quad_perm:[0,0,0,0] row_mask:0xf bank_mask:0xf
	ds_read_b64 v[144:145], v125 offset:12304
	v_fmac_f32_dpp v118, -v176, v19 quad_perm:[1,1,1,1] row_mask:0xf bank_mask:0xf
	v_fmac_f32_dpp v119, -v177, v20 quad_perm:[1,1,1,1] row_mask:0xf bank_mask:0xf
	v_fmac_f32_dpp v116, -v176, v21 quad_perm:[2,2,2,2] row_mask:0xf bank_mask:0xf
	ds_read_b64 v[146:147], v125 offset:12336
	v_fmac_f32_dpp v117, -v177, v22 quad_perm:[2,2,2,2] row_mask:0xf bank_mask:0xf
	v_fmac_f32_dpp v118, -v176, v23 quad_perm:[3,3,3,3] row_mask:0xf bank_mask:0xf
	v_fmac_f32_dpp v119, -v177, v24 quad_perm:[3,3,3,3] row_mask:0xf bank_mask:0xf
	ds_read_b64 v[148:149], v125 offset:12368
	v_fmac_f32_dpp v116, -v178, v25 quad_perm:[0,0,0,0] row_mask:0xf bank_mask:0xf
	v_fmac_f32_dpp v117, -v179, v27 quad_perm:[0,0,0,0] row_mask:0xf bank_mask:0xf
	v_fmac_f32_dpp v118, -v178, v28 quad_perm:[1,1,1,1] row_mask:0xf bank_mask:0xf
	ds_read_b64 v[150:151], v125 offset:12400
	v_fmac_f32_dpp v119, -v179, v29 quad_perm:[1,1,1,1] row_mask:0xf bank_mask:0xf
	v_fmac_f32_dpp v116, -v178, v30 quad_perm:[2,2,2,2] row_mask:0xf bank_mask:0xf
	v_fmac_f32_dpp v117, -v179, v31 quad_perm:[2,2,2,2] row_mask:0xf bank_mask:0xf
	ds_read_b32 v227, v124 offset:180
	v_fmac_f32_dpp v118, -v178, v32 quad_perm:[3,3,3,3] row_mask:0xf bank_mask:0xf
	v_fmac_f32_dpp v119, -v179, v33 quad_perm:[3,3,3,3] row_mask:0xf bank_mask:0xf
	v_fmac_f32_dpp v116, -v186, v34 quad_perm:[0,0,0,0] row_mask:0xf bank_mask:0xf
	ds_read_u16_d16_hi v253, v123 offset:12240
	v_fmac_f32_dpp v117, -v187, v35 quad_perm:[0,0,0,0] row_mask:0xf bank_mask:0xf
	v_fmac_f32_dpp v118, -v186, v36 quad_perm:[1,1,1,1] row_mask:0xf bank_mask:0xf
	v_fmac_f32_dpp v119, -v187, v37 quad_perm:[1,1,1,1] row_mask:0xf bank_mask:0xf
	v_fmac_f32_dpp v116, -v186, v38 quad_perm:[2,2,2,2] row_mask:0xf bank_mask:0xf
	v_fmac_f32_dpp v117, -v187, v39 quad_perm:[2,2,2,2] row_mask:0xf bank_mask:0xf
	v_fmac_f32_dpp v118, -v186, v40 quad_perm:[3,3,3,3] row_mask:0xf bank_mask:0xf
	v_fmac_f32_dpp v119, -v187, v41 quad_perm:[3,3,3,3] row_mask:0xf bank_mask:0xf
	v_fmac_f32_dpp v116, -v188, v42 quad_perm:[0,0,0,0] row_mask:0xf bank_mask:0xf
	v_fmac_f32_dpp v117, -v189, v43 quad_perm:[0,0,0,0] row_mask:0xf bank_mask:0xf
	v_fmac_f32_dpp v118, -v188, v44 quad_perm:[1,1,1,1] row_mask:0xf bank_mask:0xf
	v_fmac_f32_dpp v119, -v189, v45 quad_perm:[1,1,1,1] row_mask:0xf bank_mask:0xf
	v_fmac_f32_dpp v116, -v188, v46 quad_perm:[2,2,2,2] row_mask:0xf bank_mask:0xf
	v_fmac_f32_dpp v117, -v189, v47 quad_perm:[2,2,2,2] row_mask:0xf bank_mask:0xf
	v_fmac_f32_dpp v118, -v188, v48 quad_perm:[3,3,3,3] row_mask:0xf bank_mask:0xf
	v_fmac_f32_dpp v119, -v189, v49 quad_perm:[3,3,3,3] row_mask:0xf bank_mask:0xf
	v_fmac_f32_dpp v116, -v190, v50 quad_perm:[0,0,0,0] row_mask:0xf bank_mask:0xf
	v_fmac_f32_dpp v117, -v191, v51 quad_perm:[0,0,0,0] row_mask:0xf bank_mask:0xf
	v_add_f32_e32 v121, v117, v116
	v_add_f32_e32 v122, v118, v119
	v_add_f32_e32 v52, v122, v121
	s_waitcnt lgkmcnt(15)
	v_mul_f32_dpp v120, v192, v4 quad_perm:[0,0,0,0] row_mask:0xf bank_mask:0xf
	v_fma_f32 v116, v225, v251, -v120
	v_mul_f32_dpp v117, -v193, v5 quad_perm:[0,0,0,0] row_mask:0xf bank_mask:0xf
	v_mul_f32_dpp v118, -v192, v6 quad_perm:[1,1,1,1] row_mask:0xf bank_mask:0xf
	v_mul_f32_dpp v119, -v193, v12 quad_perm:[1,1,1,1] row_mask:0xf bank_mask:0xf
	ds_read_b64 v[152:153], v125 offset:12512
	v_fmac_f32_dpp v116, -v192, v7 quad_perm:[2,2,2,2] row_mask:0xf bank_mask:0xf
	v_fmac_f32_dpp v117, -v193, v13 quad_perm:[2,2,2,2] row_mask:0xf bank_mask:0xf
	v_fmac_f32_dpp v118, -v192, v14 quad_perm:[3,3,3,3] row_mask:0xf bank_mask:0xf
	ds_read_b64 v[154:155], v125 offset:12544
	v_fmac_f32_dpp v119, -v193, v15 quad_perm:[3,3,3,3] row_mask:0xf bank_mask:0xf
	v_fmac_f32_dpp v116, -v194, v16 quad_perm:[0,0,0,0] row_mask:0xf bank_mask:0xf
	v_fmac_f32_dpp v117, -v195, v17 quad_perm:[0,0,0,0] row_mask:0xf bank_mask:0xf
	ds_read_b64 v[156:157], v125 offset:12576
	v_fmac_f32_dpp v118, -v194, v19 quad_perm:[1,1,1,1] row_mask:0xf bank_mask:0xf
	v_fmac_f32_dpp v119, -v195, v20 quad_perm:[1,1,1,1] row_mask:0xf bank_mask:0xf
	v_fmac_f32_dpp v116, -v194, v21 quad_perm:[2,2,2,2] row_mask:0xf bank_mask:0xf
	ds_read_b64 v[158:159], v125 offset:12608
	v_fmac_f32_dpp v117, -v195, v22 quad_perm:[2,2,2,2] row_mask:0xf bank_mask:0xf
	v_fmac_f32_dpp v118, -v194, v23 quad_perm:[3,3,3,3] row_mask:0xf bank_mask:0xf
	v_fmac_f32_dpp v119, -v195, v24 quad_perm:[3,3,3,3] row_mask:0xf bank_mask:0xf
	ds_read_b64 v[160:161], v125 offset:12640
	v_fmac_f32_dpp v116, -v196, v25 quad_perm:[0,0,0,0] row_mask:0xf bank_mask:0xf
	v_fmac_f32_dpp v117, -v197, v27 quad_perm:[0,0,0,0] row_mask:0xf bank_mask:0xf
	v_fmac_f32_dpp v118, -v196, v28 quad_perm:[1,1,1,1] row_mask:0xf bank_mask:0xf
	ds_read_b64 v[162:163], v125 offset:12672
; #define GDN_LOADROW(buf, rr_, i_) do { _Pragma("unroll") for (int j4 = 0; j4 < ((i_) + 3) / 4; ++j4) buf[j4] = *(const f32x4*)(Lm + (i_) * GP_LSTR + 4 * j4); rr_ = bf2f(*(const bf16*)(xsrc + (i_) * GP_STR * 2)) * scl[i_]; } while (0)
; template <int STRIP> __device__ __forceinline__ void ph_gdn_prep_fast(const bf16* __restrict__ proj, const float* __restrict__ small, const float* __restrict__ conv_w, const float* __restrict__ a_log, const float* __restrict__ dt_bias, ...
;     ...
; #pragma unroll
;             for (int i = 0; i < 64; i += 2) {
;                 GDN_LOADROW(bB, rB, i + 1);
;                 GDN_ROW(bA, rA, i);
;                 if (i + 2 < 64) GDN_LOADROW(bA, rA, i + 2);
;                 GDN_ROW(bB, rB, i + 1);
	v_fmac_f32_dpp v119, -v197, v29 quad_perm:[1,1,1,1] row_mask:0xf bank_mask:0xf
	v_fmac_f32_dpp v116, -v196, v30 quad_perm:[2,2,2,2] row_mask:0xf bank_mask:0xf
	v_fmac_f32_dpp v117, -v197, v31 quad_perm:[2,2,2,2] row_mask:0xf bank_mask:0xf
	ds_read_b32 v228, v124 offset:184
	v_fmac_f32_dpp v118, -v196, v32 quad_perm:[3,3,3,3] row_mask:0xf bank_mask:0xf
	v_fmac_f32_dpp v119, -v197, v33 quad_perm:[3,3,3,3] row_mask:0xf bank_mask:0xf
	v_fmac_f32_dpp v116, -v198, v34 quad_perm:[0,0,0,0] row_mask:0xf bank_mask:0xf
	ds_read_u16_d16_hi v126, v123 offset:12512
	v_fmac_f32_dpp v117, -v199, v35 quad_perm:[0,0,0,0] row_mask:0xf bank_mask:0xf
	v_fmac_f32_dpp v118, -v198, v36 quad_perm:[1,1,1,1] row_mask:0xf bank_mask:0xf
	v_fmac_f32_dpp v119, -v199, v37 quad_perm:[1,1,1,1] row_mask:0xf bank_mask:0xf
	v_fmac_f32_dpp v116, -v198, v38 quad_perm:[2,2,2,2] row_mask:0xf bank_mask:0xf
	v_fmac_f32_dpp v117, -v199, v39 quad_perm:[2,2,2,2] row_mask:0xf bank_mask:0xf
	v_fmac_f32_dpp v118, -v198, v40 quad_perm:[3,3,3,3] row_mask:0xf bank_mask:0xf
	v_fmac_f32_dpp v119, -v199, v41 quad_perm:[3,3,3,3] row_mask:0xf bank_mask:0xf
	v_fmac_f32_dpp v116, -v200, v42 quad_perm:[0,0,0,0] row_mask:0xf bank_mask:0xf
	v_fmac_f32_dpp v117, -v201, v43 quad_perm:[0,0,0,0] row_mask:0xf bank_mask:0xf
	v_fmac_f32_dpp v118, -v200, v44 quad_perm:[1,1,1,1] row_mask:0xf bank_mask:0xf
	v_fmac_f32_dpp v119, -v201, v45 quad_perm:[1,1,1,1] row_mask:0xf bank_mask:0xf
	v_fmac_f32_dpp v116, -v200, v46 quad_perm:[2,2,2,2] row_mask:0xf bank_mask:0xf
	v_fmac_f32_dpp v117, -v201, v47 quad_perm:[2,2,2,2] row_mask:0xf bank_mask:0xf
	v_fmac_f32_dpp v118, -v200, v48 quad_perm:[3,3,3,3] row_mask:0xf bank_mask:0xf
	v_fmac_f32_dpp v119, -v201, v49 quad_perm:[3,3,3,3] row_mask:0xf bank_mask:0xf
	v_fmac_f32_dpp v116, -v202, v50 quad_perm:[0,0,0,0] row_mask:0xf bank_mask:0xf
	v_fmac_f32_dpp v117, -v203, v51 quad_perm:[0,0,0,0] row_mask:0xf bank_mask:0xf
	v_fmac_f32_dpp v118, -v202, v52 quad_perm:[1,1,1,1] row_mask:0xf bank_mask:0xf
	v_add_f32_e32 v121, v117, v116
	v_add_f32_e32 v122, v118, v119
	v_add_f32_e32 v53, v122, v121
	s_waitcnt lgkmcnt(15)
	v_mul_f32_dpp v120, v204, v4 quad_perm:[0,0,0,0] row_mask:0xf bank_mask:0xf
	v_fma_f32 v116, v226, v252, -v120
	v_mul_f32_dpp v117, -v205, v5 quad_perm:[0,0,0,0] row_mask:0xf bank_mask:0xf
	v_mul_f32_dpp v118, -v204, v6 quad_perm:[1,1,1,1] row_mask:0xf bank_mask:0xf
	v_mul_f32_dpp v119, -v205, v12 quad_perm:[1,1,1,1] row_mask:0xf bank_mask:0xf
	ds_read_b64 v[164:165], v125 offset:12784
	v_fmac_f32_dpp v116, -v204, v7 quad_perm:[2,2,2,2] row_mask:0xf bank_mask:0xf
	v_fmac_f32_dpp v117, -v205, v13 quad_perm:[2,2,2,2] row_mask:0xf bank_mask:0xf
	v_fmac_f32_dpp v118, -v204, v14 quad_perm:[3,3,3,3] row_mask:0xf bank_mask:0xf
	ds_read_b64 v[166:167], v125 offset:12816
	v_fmac_f32_dpp v119, -v205, v15 quad_perm:[3,3,3,3] row_mask:0xf bank_mask:0xf
	v_fmac_f32_dpp v116, -v206, v16 quad_perm:[0,0,0,0] row_mask:0xf bank_mask:0xf
	v_fmac_f32_dpp v117, -v207, v17 quad_perm:[0,0,0,0] row_mask:0xf bank_mask:0xf
	ds_read_b64 v[168:169], v125 offset:12848
	v_fmac_f32_dpp v118, -v206, v19 quad_perm:[1,1,1,1] row_mask:0xf bank_mask:0xf
	v_fmac_f32_dpp v119, -v207, v20 quad_perm:[1,1,1,1] row_mask:0xf bank_mask:0xf
	v_fmac_f32_dpp v116, -v206, v21 quad_perm:[2,2,2,2] row_mask:0xf bank_mask:0xf
	ds_read_b64 v[170:171], v125 offset:12880
	v_fmac_f32_dpp v117, -v207, v22 quad_perm:[2,2,2,2] row_mask:0xf bank_mask:0xf
	v_fmac_f32_dpp v118, -v206, v23 quad_perm:[3,3,3,3] row_mask:0xf bank_mask:0xf
	v_fmac_f32_dpp v119, -v207, v24 quad_perm:[3,3,3,3] row_mask:0xf bank_mask:0xf
	ds_read_b64 v[172:173], v125 offset:12912
	v_fmac_f32_dpp v116, -v132, v25 quad_perm:[0,0,0,0] row_mask:0xf bank_mask:0xf
	v_fmac_f32_dpp v117, -v133, v27 quad_perm:[0,0,0,0] row_mask:0xf bank_mask:0xf
	v_fmac_f32_dpp v118, -v132, v28 quad_perm:[1,1,1,1] row_mask:0xf bank_mask:0xf
	ds_read_b64 v[174:175], v125 offset:12944
	v_fmac_f32_dpp v119, -v133, v29 quad_perm:[1,1,1,1] row_mask:0xf bank_mask:0xf
	v_fmac_f32_dpp v116, -v132, v30 quad_perm:[2,2,2,2] row_mask:0xf bank_mask:0xf
	v_fmac_f32_dpp v117, -v133, v31 quad_perm:[2,2,2,2] row_mask:0xf bank_mask:0xf
	ds_read_b32 v229, v124 offset:188
	v_fmac_f32_dpp v118, -v132, v32 quad_perm:[3,3,3,3] row_mask:0xf bank_mask:0xf
	v_fmac_f32_dpp v119, -v133, v33 quad_perm:[3,3,3,3] row_mask:0xf bank_mask:0xf
	v_fmac_f32_dpp v116, -v134, v34 quad_perm:[0,0,0,0] row_mask:0xf bank_mask:0xf
	ds_read_u16_d16_hi v127, v123 offset:12784
	v_fmac_f32_dpp v117, -v135, v35 quad_perm:[0,0,0,0] row_mask:0xf bank_mask:0xf
	v_fmac_f32_dpp v118, -v134, v36 quad_perm:[1,1,1,1] row_mask:0xf bank_mask:0xf
	v_fmac_f32_dpp v119, -v135, v37 quad_perm:[1,1,1,1] row_mask:0xf bank_mask:0xf
	v_fmac_f32_dpp v116, -v134, v38 quad_perm:[2,2,2,2] row_mask:0xf bank_mask:0xf
	v_fmac_f32_dpp v117, -v135, v39 quad_perm:[2,2,2,2] row_mask:0xf bank_mask:0xf
	v_fmac_f32_dpp v118, -v134, v40 quad_perm:[3,3,3,3] row_mask:0xf bank_mask:0xf
	v_fmac_f32_dpp v119, -v135, v41 quad_perm:[3,3,3,3] row_mask:0xf bank_mask:0xf
	v_fmac_f32_dpp v116, -v136, v42 quad_perm:[0,0,0,0] row_mask:0xf bank_mask:0xf
	v_fmac_f32_dpp v117, -v137, v43 quad_perm:[0,0,0,0] row_mask:0xf bank_mask:0xf
	v_fmac_f32_dpp v118, -v136, v44 quad_perm:[1,1,1,1] row_mask:0xf bank_mask:0xf
	v_fmac_f32_dpp v119, -v137, v45 quad_perm:[1,1,1,1] row_mask:0xf bank_mask:0xf
	v_fmac_f32_dpp v116, -v136, v46 quad_perm:[2,2,2,2] row_mask:0xf bank_mask:0xf
	v_fmac_f32_dpp v117, -v137, v47 quad_perm:[2,2,2,2] row_mask:0xf bank_mask:0xf
	v_fmac_f32_dpp v118, -v136, v48 quad_perm:[3,3,3,3] row_mask:0xf bank_mask:0xf
	v_fmac_f32_dpp v119, -v137, v49 quad_perm:[3,3,3,3] row_mask:0xf bank_mask:0xf
	v_fmac_f32_dpp v116, -v138, v50 quad_perm:[0,0,0,0] row_mask:0xf bank_mask:0xf
	v_fmac_f32_dpp v117, -v139, v51 quad_perm:[0,0,0,0] row_mask:0xf bank_mask:0xf
	v_fmac_f32_dpp v118, -v138, v52 quad_perm:[1,1,1,1] row_mask:0xf bank_mask:0xf
	v_fmac_f32_dpp v119, -v139, v53 quad_perm:[1,1,1,1] row_mask:0xf bank_mask:0xf
	v_add_f32_e32 v121, v117, v116
	v_add_f32_e32 v122, v118, v119
	v_add_f32_e32 v54, v122, v121
	s_waitcnt lgkmcnt(15)
; #define GDN_LOADROW(buf, rr_, i_) do { _Pragma("unroll") for (int j4 = 0; j4 < ((i_) + 3) / 4; ++j4) buf[j4] = *(const f32x4*)(Lm + (i_) * GP_LSTR + 4 * j4); rr_ = bf2f(*(const bf16*)(xsrc + (i_) * GP_STR * 2)) * scl[i_]; } while (0)
; template <int STRIP> __device__ __forceinline__ void ph_gdn_prep_fast(const bf16* __restrict__ proj, const float* __restrict__ small, const float* __restrict__ conv_w, const float* __restrict__ a_log, const float* __restrict__ dt_bias, ...
;     ...
; #pragma unroll
;             for (int i = 0; i < 64; i += 2) {
;                 GDN_LOADROW(bB, rB, i + 1);
;                 GDN_ROW(bA, rA, i);
;                 if (i + 2 < 64) GDN_LOADROW(bA, rA, i + 2);
;                 GDN_ROW(bB, rB, i + 1);
	v_mul_f32_dpp v120, v140, v4 quad_perm:[0,0,0,0] row_mask:0xf bank_mask:0xf
	v_fma_f32 v116, v227, v253, -v120
	v_mul_f32_dpp v117, -v141, v5 quad_perm:[0,0,0,0] row_mask:0xf bank_mask:0xf
	v_mul_f32_dpp v118, -v140, v6 quad_perm:[1,1,1,1] row_mask:0xf bank_mask:0xf
	v_mul_f32_dpp v119, -v141, v12 quad_perm:[1,1,1,1] row_mask:0xf bank_mask:0xf
	ds_read_b64 v[176:177], v125 offset:13056
	v_fmac_f32_dpp v116, -v140, v7 quad_perm:[2,2,2,2] row_mask:0xf bank_mask:0xf
	v_fmac_f32_dpp v117, -v141, v13 quad_perm:[2,2,2,2] row_mask:0xf bank_mask:0xf
	v_fmac_f32_dpp v118, -v140, v14 quad_perm:[3,3,3,3] row_mask:0xf bank_mask:0xf
	ds_read_b64 v[178:179], v125 offset:13088
	v_fmac_f32_dpp v119, -v141, v15 quad_perm:[3,3,3,3] row_mask:0xf bank_mask:0xf
	v_fmac_f32_dpp v116, -v142, v16 quad_perm:[0,0,0,0] row_mask:0xf bank_mask:0xf
	v_fmac_f32_dpp v117, -v143, v17 quad_perm:[0,0,0,0] row_mask:0xf bank_mask:0xf
	ds_read_b64 v[186:187], v125 offset:13120
	v_fmac_f32_dpp v118, -v142, v19 quad_perm:[1,1,1,1] row_mask:0xf bank_mask:0xf
	v_fmac_f32_dpp v119, -v143, v20 quad_perm:[1,1,1,1] row_mask:0xf bank_mask:0xf
	v_fmac_f32_dpp v116, -v142, v21 quad_perm:[2,2,2,2] row_mask:0xf bank_mask:0xf
	ds_read_b64 v[188:189], v125 offset:13152
	v_fmac_f32_dpp v117, -v143, v22 quad_perm:[2,2,2,2] row_mask:0xf bank_mask:0xf
	v_fmac_f32_dpp v118, -v142, v23 quad_perm:[3,3,3,3] row_mask:0xf bank_mask:0xf
	v_fmac_f32_dpp v119, -v143, v24 quad_perm:[3,3,3,3] row_mask:0xf bank_mask:0xf
	ds_read_b64 v[190:191], v125 offset:13184
	v_fmac_f32_dpp v116, -v144, v25 quad_perm:[0,0,0,0] row_mask:0xf bank_mask:0xf
	v_fmac_f32_dpp v117, -v145, v27 quad_perm:[0,0,0,0] row_mask:0xf bank_mask:0xf
	v_fmac_f32_dpp v118, -v144, v28 quad_perm:[1,1,1,1] row_mask:0xf bank_mask:0xf
	ds_read_b64 v[192:193], v125 offset:13216
	v_fmac_f32_dpp v119, -v145, v29 quad_perm:[1,1,1,1] row_mask:0xf bank_mask:0xf
	v_fmac_f32_dpp v116, -v144, v30 quad_perm:[2,2,2,2] row_mask:0xf bank_mask:0xf
	v_fmac_f32_dpp v117, -v145, v31 quad_perm:[2,2,2,2] row_mask:0xf bank_mask:0xf
	ds_read_b32 v181, v124 offset:192
	v_fmac_f32_dpp v118, -v144, v32 quad_perm:[3,3,3,3] row_mask:0xf bank_mask:0xf
	v_fmac_f32_dpp v119, -v145, v33 quad_perm:[3,3,3,3] row_mask:0xf bank_mask:0xf
	v_fmac_f32_dpp v116, -v146, v34 quad_perm:[0,0,0,0] row_mask:0xf bank_mask:0xf
	ds_read_u16_d16_hi v244, v123 offset:13056
	v_fmac_f32_dpp v117, -v147, v35 quad_perm:[0,0,0,0] row_mask:0xf bank_mask:0xf
	v_fmac_f32_dpp v118, -v146, v36 quad_perm:[1,1,1,1] row_mask:0xf bank_mask:0xf
	v_fmac_f32_dpp v119, -v147, v37 quad_perm:[1,1,1,1] row_mask:0xf bank_mask:0xf
	v_fmac_f32_dpp v116, -v146, v38 quad_perm:[2,2,2,2] row_mask:0xf bank_mask:0xf
	v_fmac_f32_dpp v117, -v147, v39 quad_perm:[2,2,2,2] row_mask:0xf bank_mask:0xf
	v_fmac_f32_dpp v118, -v146, v40 quad_perm:[3,3,3,3] row_mask:0xf bank_mask:0xf
	v_fmac_f32_dpp v119, -v147, v41 quad_perm:[3,3,3,3] row_mask:0xf bank_mask:0xf
	v_fmac_f32_dpp v116, -v148, v42 quad_perm:[0,0,0,0] row_mask:0xf bank_mask:0xf
	v_fmac_f32_dpp v117, -v149, v43 quad_perm:[0,0,0,0] row_mask:0xf bank_mask:0xf
	v_fmac_f32_dpp v118, -v148, v44 quad_perm:[1,1,1,1] row_mask:0xf bank_mask:0xf
	v_fmac_f32_dpp v119, -v149, v45 quad_perm:[1,1,1,1] row_mask:0xf bank_mask:0xf
	v_fmac_f32_dpp v116, -v148, v46 quad_perm:[2,2,2,2] row_mask:0xf bank_mask:0xf
	v_fmac_f32_dpp v117, -v149, v47 quad_perm:[2,2,2,2] row_mask:0xf bank_mask:0xf
	v_fmac_f32_dpp v118, -v148, v48 quad_perm:[3,3,3,3] row_mask:0xf bank_mask:0xf
	v_fmac_f32_dpp v119, -v149, v49 quad_perm:[3,3,3,3] row_mask:0xf bank_mask:0xf
	v_fmac_f32_dpp v116, -v150, v50 quad_perm:[0,0,0,0] row_mask:0xf bank_mask:0xf
	v_fmac_f32_dpp v117, -v151, v51 quad_perm:[0,0,0,0] row_mask:0xf bank_mask:0xf
	v_fmac_f32_dpp v118, -v150, v52 quad_perm:[1,1,1,1] row_mask:0xf bank_mask:0xf
	v_fmac_f32_dpp v119, -v151, v53 quad_perm:[1,1,1,1] row_mask:0xf bank_mask:0xf
	v_fmac_f32_dpp v116, -v150, v54 quad_perm:[2,2,2,2] row_mask:0xf bank_mask:0xf
	v_add_f32_e32 v121, v117, v116
	v_add_f32_e32 v122, v118, v119
	v_add_f32_e32 v55, v122, v121
	s_waitcnt lgkmcnt(15)
	v_mul_f32_dpp v120, v152, v4 quad_perm:[0,0,0,0] row_mask:0xf bank_mask:0xf
	v_fma_f32 v116, v228, v126, -v120
	v_mul_f32_dpp v117, -v153, v5 quad_perm:[0,0,0,0] row_mask:0xf bank_mask:0xf
	v_mul_f32_dpp v118, -v152, v6 quad_perm:[1,1,1,1] row_mask:0xf bank_mask:0xf
	v_mul_f32_dpp v119, -v153, v12 quad_perm:[1,1,1,1] row_mask:0xf bank_mask:0xf
	ds_read_b64 v[194:195], v125 offset:13328
	v_fmac_f32_dpp v116, -v152, v7 quad_perm:[2,2,2,2] row_mask:0xf bank_mask:0xf
	v_fmac_f32_dpp v117, -v153, v13 quad_perm:[2,2,2,2] row_mask:0xf bank_mask:0xf
	v_fmac_f32_dpp v118, -v152, v14 quad_perm:[3,3,3,3] row_mask:0xf bank_mask:0xf
	ds_read_b64 v[196:197], v125 offset:13360
	v_fmac_f32_dpp v119, -v153, v15 quad_perm:[3,3,3,3] row_mask:0xf bank_mask:0xf
	v_fmac_f32_dpp v116, -v154, v16 quad_perm:[0,0,0,0] row_mask:0xf bank_mask:0xf
	v_fmac_f32_dpp v117, -v155, v17 quad_perm:[0,0,0,0] row_mask:0xf bank_mask:0xf
	ds_read_b64 v[198:199], v125 offset:13392
	v_fmac_f32_dpp v118, -v154, v19 quad_perm:[1,1,1,1] row_mask:0xf bank_mask:0xf
	v_fmac_f32_dpp v119, -v155, v20 quad_perm:[1,1,1,1] row_mask:0xf bank_mask:0xf
	v_fmac_f32_dpp v116, -v154, v21 quad_perm:[2,2,2,2] row_mask:0xf bank_mask:0xf
	ds_read_b64 v[200:201], v125 offset:13424
	v_fmac_f32_dpp v117, -v155, v22 quad_perm:[2,2,2,2] row_mask:0xf bank_mask:0xf
	v_fmac_f32_dpp v118, -v154, v23 quad_perm:[3,3,3,3] row_mask:0xf bank_mask:0xf
	v_fmac_f32_dpp v119, -v155, v24 quad_perm:[3,3,3,3] row_mask:0xf bank_mask:0xf
	ds_read_b64 v[202:203], v125 offset:13456
; #define GDN_LOADROW(buf, rr_, i_) do { _Pragma("unroll") for (int j4 = 0; j4 < ((i_) + 3) / 4; ++j4) buf[j4] = *(const f32x4*)(Lm + (i_) * GP_LSTR + 4 * j4); rr_ = bf2f(*(const bf16*)(xsrc + (i_) * GP_STR * 2)) * scl[i_]; } while (0)
; template <int STRIP> __device__ __forceinline__ void ph_gdn_prep_fast(const bf16* __restrict__ proj, const float* __restrict__ small, const float* __restrict__ conv_w, const float* __restrict__ a_log, const float* __restrict__ dt_bias, ...
;     ...
; #pragma unroll
;             for (int i = 0; i < 64; i += 2) {
;                 GDN_LOADROW(bB, rB, i + 1);
;                 GDN_ROW(bA, rA, i);
;                 if (i + 2 < 64) GDN_LOADROW(bA, rA, i + 2);
;                 GDN_ROW(bB, rB, i + 1);
	v_fmac_f32_dpp v116, -v156, v25 quad_perm:[0,0,0,0] row_mask:0xf bank_mask:0xf
	v_fmac_f32_dpp v117, -v157, v27 quad_perm:[0,0,0,0] row_mask:0xf bank_mask:0xf
	v_fmac_f32_dpp v118, -v156, v28 quad_perm:[1,1,1,1] row_mask:0xf bank_mask:0xf
	ds_read_b64 v[204:205], v125 offset:13488
	v_fmac_f32_dpp v119, -v157, v29 quad_perm:[1,1,1,1] row_mask:0xf bank_mask:0xf
	v_fmac_f32_dpp v116, -v156, v30 quad_perm:[2,2,2,2] row_mask:0xf bank_mask:0xf
	v_fmac_f32_dpp v117, -v157, v31 quad_perm:[2,2,2,2] row_mask:0xf bank_mask:0xf
	ds_read_b64 v[206:207], v125 offset:13520
	v_fmac_f32_dpp v118, -v156, v32 quad_perm:[3,3,3,3] row_mask:0xf bank_mask:0xf
	v_fmac_f32_dpp v119, -v157, v33 quad_perm:[3,3,3,3] row_mask:0xf bank_mask:0xf
	v_fmac_f32_dpp v116, -v158, v34 quad_perm:[0,0,0,0] row_mask:0xf bank_mask:0xf
	ds_read_b32 v182, v124 offset:196
	v_fmac_f32_dpp v117, -v159, v35 quad_perm:[0,0,0,0] row_mask:0xf bank_mask:0xf
	v_fmac_f32_dpp v118, -v158, v36 quad_perm:[1,1,1,1] row_mask:0xf bank_mask:0xf
	v_fmac_f32_dpp v119, -v159, v37 quad_perm:[1,1,1,1] row_mask:0xf bank_mask:0xf
	ds_read_u16_d16_hi v245, v123 offset:13328
	v_fmac_f32_dpp v116, -v158, v38 quad_perm:[2,2,2,2] row_mask:0xf bank_mask:0xf
	v_fmac_f32_dpp v117, -v159, v39 quad_perm:[2,2,2,2] row_mask:0xf bank_mask:0xf
	v_fmac_f32_dpp v118, -v158, v40 quad_perm:[3,3,3,3] row_mask:0xf bank_mask:0xf
	v_fmac_f32_dpp v119, -v159, v41 quad_perm:[3,3,3,3] row_mask:0xf bank_mask:0xf
	v_fmac_f32_dpp v116, -v160, v42 quad_perm:[0,0,0,0] row_mask:0xf bank_mask:0xf
	v_fmac_f32_dpp v117, -v161, v43 quad_perm:[0,0,0,0] row_mask:0xf bank_mask:0xf
	v_fmac_f32_dpp v118, -v160, v44 quad_perm:[1,1,1,1] row_mask:0xf bank_mask:0xf
	v_fmac_f32_dpp v119, -v161, v45 quad_perm:[1,1,1,1] row_mask:0xf bank_mask:0xf
	v_fmac_f32_dpp v116, -v160, v46 quad_perm:[2,2,2,2] row_mask:0xf bank_mask:0xf
	v_fmac_f32_dpp v117, -v161, v47 quad_perm:[2,2,2,2] row_mask:0xf bank_mask:0xf
	v_fmac_f32_dpp v118, -v160, v48 quad_perm:[3,3,3,3] row_mask:0xf bank_mask:0xf
	v_fmac_f32_dpp v119, -v161, v49 quad_perm:[3,3,3,3] row_mask:0xf bank_mask:0xf
	v_fmac_f32_dpp v116, -v162, v50 quad_perm:[0,0,0,0] row_mask:0xf bank_mask:0xf
	v_fmac_f32_dpp v117, -v163, v51 quad_perm:[0,0,0,0] row_mask:0xf bank_mask:0xf
	v_fmac_f32_dpp v118, -v162, v52 quad_perm:[1,1,1,1] row_mask:0xf bank_mask:0xf
	v_fmac_f32_dpp v119, -v163, v53 quad_perm:[1,1,1,1] row_mask:0xf bank_mask:0xf
	v_fmac_f32_dpp v116, -v162, v54 quad_perm:[2,2,2,2] row_mask:0xf bank_mask:0xf
	v_fmac_f32_dpp v117, -v163, v55 quad_perm:[2,2,2,2] row_mask:0xf bank_mask:0xf
	v_add_f32_e32 v121, v117, v116
	v_add_f32_e32 v122, v118, v119
	v_add_f32_e32 v56, v122, v121
	s_waitcnt lgkmcnt(15)
	v_mul_f32_dpp v120, v164, v4 quad_perm:[0,0,0,0] row_mask:0xf bank_mask:0xf
	v_fma_f32 v116, v229, v127, -v120
	v_mul_f32_dpp v117, -v165, v5 quad_perm:[0,0,0,0] row_mask:0xf bank_mask:0xf
	v_mul_f32_dpp v118, -v164, v6 quad_perm:[1,1,1,1] row_mask:0xf bank_mask:0xf
	v_mul_f32_dpp v119, -v165, v12 quad_perm:[1,1,1,1] row_mask:0xf bank_mask:0xf
	ds_read_b64 v[132:133], v125 offset:13600
	v_fmac_f32_dpp v116, -v164, v7 quad_perm:[2,2,2,2] row_mask:0xf bank_mask:0xf
	v_fmac_f32_dpp v117, -v165, v13 quad_perm:[2,2,2,2] row_mask:0xf bank_mask:0xf
	v_fmac_f32_dpp v118, -v164, v14 quad_perm:[3,3,3,3] row_mask:0xf bank_mask:0xf
	ds_read_b64 v[134:135], v125 offset:13632
	v_fmac_f32_dpp v119, -v165, v15 quad_perm:[3,3,3,3] row_mask:0xf bank_mask:0xf
	v_fmac_f32_dpp v116, -v166, v16 quad_perm:[0,0,0,0] row_mask:0xf bank_mask:0xf
	v_fmac_f32_dpp v117, -v167, v17 quad_perm:[0,0,0,0] row_mask:0xf bank_mask:0xf
	ds_read_b64 v[136:137], v125 offset:13664
	v_fmac_f32_dpp v118, -v166, v19 quad_perm:[1,1,1,1] row_mask:0xf bank_mask:0xf
	v_fmac_f32_dpp v119, -v167, v20 quad_perm:[1,1,1,1] row_mask:0xf bank_mask:0xf
	v_fmac_f32_dpp v116, -v166, v21 quad_perm:[2,2,2,2] row_mask:0xf bank_mask:0xf
	ds_read_b64 v[138:139], v125 offset:13696
	v_fmac_f32_dpp v117, -v167, v22 quad_perm:[2,2,2,2] row_mask:0xf bank_mask:0xf
	v_fmac_f32_dpp v118, -v166, v23 quad_perm:[3,3,3,3] row_mask:0xf bank_mask:0xf
	v_fmac_f32_dpp v119, -v167, v24 quad_perm:[3,3,3,3] row_mask:0xf bank_mask:0xf
	ds_read_b64 v[140:141], v125 offset:13728
	v_fmac_f32_dpp v116, -v168, v25 quad_perm:[0,0,0,0] row_mask:0xf bank_mask:0xf
	v_fmac_f32_dpp v117, -v169, v27 quad_perm:[0,0,0,0] row_mask:0xf bank_mask:0xf
	v_fmac_f32_dpp v118, -v168, v28 quad_perm:[1,1,1,1] row_mask:0xf bank_mask:0xf
	ds_read_b64 v[142:143], v125 offset:13760
	v_fmac_f32_dpp v119, -v169, v29 quad_perm:[1,1,1,1] row_mask:0xf bank_mask:0xf
	v_fmac_f32_dpp v116, -v168, v30 quad_perm:[2,2,2,2] row_mask:0xf bank_mask:0xf
	v_fmac_f32_dpp v117, -v169, v31 quad_perm:[2,2,2,2] row_mask:0xf bank_mask:0xf
	ds_read_b64 v[144:145], v125 offset:13792
	v_fmac_f32_dpp v118, -v168, v32 quad_perm:[3,3,3,3] row_mask:0xf bank_mask:0xf
	v_fmac_f32_dpp v119, -v169, v33 quad_perm:[3,3,3,3] row_mask:0xf bank_mask:0xf
	v_fmac_f32_dpp v116, -v170, v34 quad_perm:[0,0,0,0] row_mask:0xf bank_mask:0xf
	ds_read_b32 v183, v124 offset:200
	v_fmac_f32_dpp v117, -v171, v35 quad_perm:[0,0,0,0] row_mask:0xf bank_mask:0xf
	v_fmac_f32_dpp v118, -v170, v36 quad_perm:[1,1,1,1] row_mask:0xf bank_mask:0xf
	v_fmac_f32_dpp v119, -v171, v37 quad_perm:[1,1,1,1] row_mask:0xf bank_mask:0xf
	ds_read_u16_d16_hi v246, v123 offset:13600
	v_fmac_f32_dpp v116, -v170, v38 quad_perm:[2,2,2,2] row_mask:0xf bank_mask:0xf
	v_fmac_f32_dpp v117, -v171, v39 quad_perm:[2,2,2,2] row_mask:0xf bank_mask:0xf
	v_fmac_f32_dpp v118, -v170, v40 quad_perm:[3,3,3,3] row_mask:0xf bank_mask:0xf
	v_fmac_f32_dpp v119, -v171, v41 quad_perm:[3,3,3,3] row_mask:0xf bank_mask:0xf
	v_fmac_f32_dpp v116, -v172, v42 quad_perm:[0,0,0,0] row_mask:0xf bank_mask:0xf
	v_fmac_f32_dpp v117, -v173, v43 quad_perm:[0,0,0,0] row_mask:0xf bank_mask:0xf
	v_fmac_f32_dpp v118, -v172, v44 quad_perm:[1,1,1,1] row_mask:0xf bank_mask:0xf
	v_fmac_f32_dpp v119, -v173, v45 quad_perm:[1,1,1,1] row_mask:0xf bank_mask:0xf
	v_fmac_f32_dpp v116, -v172, v46 quad_perm:[2,2,2,2] row_mask:0xf bank_mask:0xf
	v_fmac_f32_dpp v117, -v173, v47 quad_perm:[2,2,2,2] row_mask:0xf bank_mask:0xf
	v_fmac_f32_dpp v118, -v172, v48 quad_perm:[3,3,3,3] row_mask:0xf bank_mask:0xf
	v_fmac_f32_dpp v119, -v173, v49 quad_perm:[3,3,3,3] row_mask:0xf bank_mask:0xf
	v_fmac_f32_dpp v116, -v174, v50 quad_perm:[0,0,0,0] row_mask:0xf bank_mask:0xf
	v_fmac_f32_dpp v117, -v175, v51 quad_perm:[0,0,0,0] row_mask:0xf bank_mask:0xf
	v_fmac_f32_dpp v118, -v174, v52 quad_perm:[1,1,1,1] row_mask:0xf bank_mask:0xf
	v_fmac_f32_dpp v119, -v175, v53 quad_perm:[1,1,1,1] row_mask:0xf bank_mask:0xf
	v_fmac_f32_dpp v116, -v174, v54 quad_perm:[2,2,2,2] row_mask:0xf bank_mask:0xf
	v_fmac_f32_dpp v117, -v175, v55 quad_perm:[2,2,2,2] row_mask:0xf bank_mask:0xf
	v_fmac_f32_dpp v118, -v174, v56 quad_perm:[3,3,3,3] row_mask:0xf bank_mask:0xf
	v_add_f32_e32 v121, v117, v116
	v_add_f32_e32 v122, v118, v119
	v_add_f32_e32 v57, v122, v121
	s_waitcnt lgkmcnt(15)
; #define GDN_LOADROW(buf, rr_, i_) do { _Pragma("unroll") for (int j4 = 0; j4 < ((i_) + 3) / 4; ++j4) buf[j4] = *(const f32x4*)(Lm + (i_) * GP_LSTR + 4 * j4); rr_ = bf2f(*(const bf16*)(xsrc + (i_) * GP_STR * 2)) * scl[i_]; } while (0)
; template <int STRIP> __device__ __forceinline__ void ph_gdn_prep_fast(const bf16* __restrict__ proj, const float* __restrict__ small, const float* __restrict__ conv_w, const float* __restrict__ a_log, const float* __restrict__ dt_bias, ...
;     ...
; #pragma unroll
;             for (int i = 0; i < 64; i += 2) {
;                 GDN_LOADROW(bB, rB, i + 1);
;                 GDN_ROW(bA, rA, i);
;                 if (i + 2 < 64) GDN_LOADROW(bA, rA, i + 2);
;                 GDN_ROW(bB, rB, i + 1);
	v_mul_f32_dpp v120, v176, v4 quad_perm:[0,0,0,0] row_mask:0xf bank_mask:0xf
	v_fma_f32 v116, v181, v244, -v120
	v_mul_f32_dpp v117, -v177, v5 quad_perm:[0,0,0,0] row_mask:0xf bank_mask:0xf
	v_mul_f32_dpp v118, -v176, v6 quad_perm:[1,1,1,1] row_mask:0xf bank_mask:0xf
	v_mul_f32_dpp v119, -v177, v12 quad_perm:[1,1,1,1] row_mask:0xf bank_mask:0xf
	v_fmac_f32_dpp v116, -v176, v7 quad_perm:[2,2,2,2] row_mask:0xf bank_mask:0xf
	v_fmac_f32_dpp v117, -v177, v13 quad_perm:[2,2,2,2] row_mask:0xf bank_mask:0xf
	v_fmac_f32_dpp v118, -v176, v14 quad_perm:[3,3,3,3] row_mask:0xf bank_mask:0xf
	v_fmac_f32_dpp v119, -v177, v15 quad_perm:[3,3,3,3] row_mask:0xf bank_mask:0xf
	v_fmac_f32_dpp v116, -v178, v16 quad_perm:[0,0,0,0] row_mask:0xf bank_mask:0xf
	v_fmac_f32_dpp v117, -v179, v17 quad_perm:[0,0,0,0] row_mask:0xf bank_mask:0xf
	v_fmac_f32_dpp v118, -v178, v19 quad_perm:[1,1,1,1] row_mask:0xf bank_mask:0xf
	v_fmac_f32_dpp v119, -v179, v20 quad_perm:[1,1,1,1] row_mask:0xf bank_mask:0xf
	v_fmac_f32_dpp v116, -v178, v21 quad_perm:[2,2,2,2] row_mask:0xf bank_mask:0xf
	v_fmac_f32_dpp v117, -v179, v22 quad_perm:[2,2,2,2] row_mask:0xf bank_mask:0xf
	v_fmac_f32_dpp v118, -v178, v23 quad_perm:[3,3,3,3] row_mask:0xf bank_mask:0xf
	v_fmac_f32_dpp v119, -v179, v24 quad_perm:[3,3,3,3] row_mask:0xf bank_mask:0xf
	v_fmac_f32_dpp v116, -v186, v25 quad_perm:[0,0,0,0] row_mask:0xf bank_mask:0xf
	v_fmac_f32_dpp v117, -v187, v27 quad_perm:[0,0,0,0] row_mask:0xf bank_mask:0xf
	v_fmac_f32_dpp v118, -v186, v28 quad_perm:[1,1,1,1] row_mask:0xf bank_mask:0xf
	v_fmac_f32_dpp v119, -v187, v29 quad_perm:[1,1,1,1] row_mask:0xf bank_mask:0xf
	v_fmac_f32_dpp v116, -v186, v30 quad_perm:[2,2,2,2] row_mask:0xf bank_mask:0xf
	v_fmac_f32_dpp v117, -v187, v31 quad_perm:[2,2,2,2] row_mask:0xf bank_mask:0xf
	v_fmac_f32_dpp v118, -v186, v32 quad_perm:[3,3,3,3] row_mask:0xf bank_mask:0xf
	v_fmac_f32_dpp v119, -v187, v33 quad_perm:[3,3,3,3] row_mask:0xf bank_mask:0xf
	v_fmac_f32_dpp v116, -v188, v34 quad_perm:[0,0,0,0] row_mask:0xf bank_mask:0xf
	v_fmac_f32_dpp v117, -v189, v35 quad_perm:[0,0,0,0] row_mask:0xf bank_mask:0xf
	v_fmac_f32_dpp v118, -v188, v36 quad_perm:[1,1,1,1] row_mask:0xf bank_mask:0xf
	v_fmac_f32_dpp v119, -v189, v37 quad_perm:[1,1,1,1] row_mask:0xf bank_mask:0xf
	v_fmac_f32_dpp v116, -v188, v38 quad_perm:[2,2,2,2] row_mask:0xf bank_mask:0xf
	v_fmac_f32_dpp v117, -v189, v39 quad_perm:[2,2,2,2] row_mask:0xf bank_mask:0xf
	v_fmac_f32_dpp v118, -v188, v40 quad_perm:[3,3,3,3] row_mask:0xf bank_mask:0xf
	v_fmac_f32_dpp v119, -v189, v41 quad_perm:[3,3,3,3] row_mask:0xf bank_mask:0xf
	v_fmac_f32_dpp v116, -v190, v42 quad_perm:[0,0,0,0] row_mask:0xf bank_mask:0xf
	v_fmac_f32_dpp v117, -v191, v43 quad_perm:[0,0,0,0] row_mask:0xf bank_mask:0xf
	v_fmac_f32_dpp v118, -v190, v44 quad_perm:[1,1,1,1] row_mask:0xf bank_mask:0xf
	v_fmac_f32_dpp v119, -v191, v45 quad_perm:[1,1,1,1] row_mask:0xf bank_mask:0xf
	v_fmac_f32_dpp v116, -v190, v46 quad_perm:[2,2,2,2] row_mask:0xf bank_mask:0xf
	v_fmac_f32_dpp v117, -v191, v47 quad_perm:[2,2,2,2] row_mask:0xf bank_mask:0xf
	v_fmac_f32_dpp v118, -v190, v48 quad_perm:[3,3,3,3] row_mask:0xf bank_mask:0xf
	v_fmac_f32_dpp v119, -v191, v49 quad_perm:[3,3,3,3] row_mask:0xf bank_mask:0xf
	v_fmac_f32_dpp v116, -v192, v50 quad_perm:[0,0,0,0] row_mask:0xf bank_mask:0xf
	v_fmac_f32_dpp v117, -v193, v51 quad_perm:[0,0,0,0] row_mask:0xf bank_mask:0xf
	v_fmac_f32_dpp v118, -v192, v52 quad_perm:[1,1,1,1] row_mask:0xf bank_mask:0xf
	v_fmac_f32_dpp v119, -v193, v53 quad_perm:[1,1,1,1] row_mask:0xf bank_mask:0xf
	v_fmac_f32_dpp v116, -v192, v54 quad_perm:[2,2,2,2] row_mask:0xf bank_mask:0xf
	v_fmac_f32_dpp v117, -v193, v55 quad_perm:[2,2,2,2] row_mask:0xf bank_mask:0xf
	v_fmac_f32_dpp v118, -v192, v56 quad_perm:[3,3,3,3] row_mask:0xf bank_mask:0xf
	v_fmac_f32_dpp v119, -v193, v57 quad_perm:[3,3,3,3] row_mask:0xf bank_mask:0xf
	v_add_f32_e32 v121, v117, v116
	v_add_f32_e32 v122, v118, v119
	v_add_f32_e32 v58, v122, v121
	s_waitcnt lgkmcnt(9)
	v_mul_f32_dpp v120, v194, v4 quad_perm:[0,0,0,0] row_mask:0xf bank_mask:0xf
	v_fma_f32 v116, v182, v245, -v120
	v_mul_f32_dpp v117, -v195, v5 quad_perm:[0,0,0,0] row_mask:0xf bank_mask:0xf
	v_mul_f32_dpp v118, -v194, v6 quad_perm:[1,1,1,1] row_mask:0xf bank_mask:0xf
	v_mul_f32_dpp v119, -v195, v12 quad_perm:[1,1,1,1] row_mask:0xf bank_mask:0xf
	ds_read_b64 v[146:147], v125 offset:13872
	v_fmac_f32_dpp v116, -v194, v7 quad_perm:[2,2,2,2] row_mask:0xf bank_mask:0xf
	v_fmac_f32_dpp v117, -v195, v13 quad_perm:[2,2,2,2] row_mask:0xf bank_mask:0xf
	v_fmac_f32_dpp v118, -v194, v14 quad_perm:[3,3,3,3] row_mask:0xf bank_mask:0xf
	ds_read_b64 v[148:149], v125 offset:13904
	v_fmac_f32_dpp v119, -v195, v15 quad_perm:[3,3,3,3] row_mask:0xf bank_mask:0xf
	v_fmac_f32_dpp v116, -v196, v16 quad_perm:[0,0,0,0] row_mask:0xf bank_mask:0xf
	v_fmac_f32_dpp v117, -v197, v17 quad_perm:[0,0,0,0] row_mask:0xf bank_mask:0xf
	ds_read_b64 v[150:151], v125 offset:13936
	v_fmac_f32_dpp v118, -v196, v19 quad_perm:[1,1,1,1] row_mask:0xf bank_mask:0xf
	v_fmac_f32_dpp v119, -v197, v20 quad_perm:[1,1,1,1] row_mask:0xf bank_mask:0xf
	v_fmac_f32_dpp v116, -v196, v21 quad_perm:[2,2,2,2] row_mask:0xf bank_mask:0xf
	ds_read_b64 v[152:153], v125 offset:13968
	v_fmac_f32_dpp v117, -v197, v22 quad_perm:[2,2,2,2] row_mask:0xf bank_mask:0xf
	v_fmac_f32_dpp v118, -v196, v23 quad_perm:[3,3,3,3] row_mask:0xf bank_mask:0xf
	v_fmac_f32_dpp v119, -v197, v24 quad_perm:[3,3,3,3] row_mask:0xf bank_mask:0xf
	ds_read_b64 v[154:155], v125 offset:14000
	v_fmac_f32_dpp v116, -v198, v25 quad_perm:[0,0,0,0] row_mask:0xf bank_mask:0xf
	v_fmac_f32_dpp v117, -v199, v27 quad_perm:[0,0,0,0] row_mask:0xf bank_mask:0xf
; #define GDN_LOADROW(buf, rr_, i_) do { _Pragma("unroll") for (int j4 = 0; j4 < ((i_) + 3) / 4; ++j4) buf[j4] = *(const f32x4*)(Lm + (i_) * GP_LSTR + 4 * j4); rr_ = bf2f(*(const bf16*)(xsrc + (i_) * GP_STR * 2)) * scl[i_]; } while (0)
; template <int STRIP> __device__ __forceinline__ void ph_gdn_prep_fast(const bf16* __restrict__ proj, const float* __restrict__ small, const float* __restrict__ conv_w, const float* __restrict__ a_log, const float* __restrict__ dt_bias, ...
;     ...
; #pragma unroll
;             for (int i = 0; i < 64; i += 2) {
;                 GDN_LOADROW(bB, rB, i + 1);
;                 GDN_ROW(bA, rA, i);
;                 if (i + 2 < 64) GDN_LOADROW(bA, rA, i + 2);
;                 GDN_ROW(bB, rB, i + 1);
	v_fmac_f32_dpp v118, -v198, v28 quad_perm:[1,1,1,1] row_mask:0xf bank_mask:0xf
	ds_read_b64 v[156:157], v125 offset:14032
	v_fmac_f32_dpp v119, -v199, v29 quad_perm:[1,1,1,1] row_mask:0xf bank_mask:0xf
	v_fmac_f32_dpp v116, -v198, v30 quad_perm:[2,2,2,2] row_mask:0xf bank_mask:0xf
	v_fmac_f32_dpp v117, -v199, v31 quad_perm:[2,2,2,2] row_mask:0xf bank_mask:0xf
	ds_read_b64 v[158:159], v125 offset:14064
	v_fmac_f32_dpp v118, -v198, v32 quad_perm:[3,3,3,3] row_mask:0xf bank_mask:0xf
	v_fmac_f32_dpp v119, -v199, v33 quad_perm:[3,3,3,3] row_mask:0xf bank_mask:0xf
	v_fmac_f32_dpp v116, -v200, v34 quad_perm:[0,0,0,0] row_mask:0xf bank_mask:0xf
	ds_read_b32 v185, v124 offset:204
	v_fmac_f32_dpp v117, -v201, v35 quad_perm:[0,0,0,0] row_mask:0xf bank_mask:0xf
	v_fmac_f32_dpp v118, -v200, v36 quad_perm:[1,1,1,1] row_mask:0xf bank_mask:0xf
	v_fmac_f32_dpp v119, -v201, v37 quad_perm:[1,1,1,1] row_mask:0xf bank_mask:0xf
	ds_read_u16_d16_hi v247, v123 offset:13872
	v_fmac_f32_dpp v116, -v200, v38 quad_perm:[2,2,2,2] row_mask:0xf bank_mask:0xf
	v_fmac_f32_dpp v117, -v201, v39 quad_perm:[2,2,2,2] row_mask:0xf bank_mask:0xf
	v_fmac_f32_dpp v118, -v200, v40 quad_perm:[3,3,3,3] row_mask:0xf bank_mask:0xf
	v_fmac_f32_dpp v119, -v201, v41 quad_perm:[3,3,3,3] row_mask:0xf bank_mask:0xf
	v_fmac_f32_dpp v116, -v202, v42 quad_perm:[0,0,0,0] row_mask:0xf bank_mask:0xf
	v_fmac_f32_dpp v117, -v203, v43 quad_perm:[0,0,0,0] row_mask:0xf bank_mask:0xf
	v_fmac_f32_dpp v118, -v202, v44 quad_perm:[1,1,1,1] row_mask:0xf bank_mask:0xf
	v_fmac_f32_dpp v119, -v203, v45 quad_perm:[1,1,1,1] row_mask:0xf bank_mask:0xf
	v_fmac_f32_dpp v116, -v202, v46 quad_perm:[2,2,2,2] row_mask:0xf bank_mask:0xf
	v_fmac_f32_dpp v117, -v203, v47 quad_perm:[2,2,2,2] row_mask:0xf bank_mask:0xf
	v_fmac_f32_dpp v118, -v202, v48 quad_perm:[3,3,3,3] row_mask:0xf bank_mask:0xf
	v_fmac_f32_dpp v119, -v203, v49 quad_perm:[3,3,3,3] row_mask:0xf bank_mask:0xf
	v_fmac_f32_dpp v116, -v204, v50 quad_perm:[0,0,0,0] row_mask:0xf bank_mask:0xf
	v_fmac_f32_dpp v117, -v205, v51 quad_perm:[0,0,0,0] row_mask:0xf bank_mask:0xf
	v_fmac_f32_dpp v118, -v204, v52 quad_perm:[1,1,1,1] row_mask:0xf bank_mask:0xf
	v_fmac_f32_dpp v119, -v205, v53 quad_perm:[1,1,1,1] row_mask:0xf bank_mask:0xf
	v_fmac_f32_dpp v116, -v204, v54 quad_perm:[2,2,2,2] row_mask:0xf bank_mask:0xf
	v_fmac_f32_dpp v117, -v205, v55 quad_perm:[2,2,2,2] row_mask:0xf bank_mask:0xf
	v_fmac_f32_dpp v118, -v204, v56 quad_perm:[3,3,3,3] row_mask:0xf bank_mask:0xf
	v_fmac_f32_dpp v119, -v205, v57 quad_perm:[3,3,3,3] row_mask:0xf bank_mask:0xf
	v_fmac_f32_dpp v116, -v206, v58 quad_perm:[0,0,0,0] row_mask:0xf bank_mask:0xf
	v_add_f32_e32 v121, v117, v116
	v_add_f32_e32 v122, v118, v119
	v_add_f32_e32 v59, v122, v121
	s_waitcnt lgkmcnt(9)
	v_mul_f32_dpp v120, v132, v4 quad_perm:[0,0,0,0] row_mask:0xf bank_mask:0xf
	v_fma_f32 v116, v183, v246, -v120
	v_mul_f32_dpp v117, -v133, v5 quad_perm:[0,0,0,0] row_mask:0xf bank_mask:0xf
	v_mul_f32_dpp v118, -v132, v6 quad_perm:[1,1,1,1] row_mask:0xf bank_mask:0xf
	v_mul_f32_dpp v119, -v133, v12 quad_perm:[1,1,1,1] row_mask:0xf bank_mask:0xf
	ds_read_b64 v[160:161], v125 offset:14144
	v_fmac_f32_dpp v116, -v132, v7 quad_perm:[2,2,2,2] row_mask:0xf bank_mask:0xf
	v_fmac_f32_dpp v117, -v133, v13 quad_perm:[2,2,2,2] row_mask:0xf bank_mask:0xf
	v_fmac_f32_dpp v118, -v132, v14 quad_perm:[3,3,3,3] row_mask:0xf bank_mask:0xf
	ds_read_b64 v[162:163], v125 offset:14176
	v_fmac_f32_dpp v119, -v133, v15 quad_perm:[3,3,3,3] row_mask:0xf bank_mask:0xf
	v_fmac_f32_dpp v116, -v134, v16 quad_perm:[0,0,0,0] row_mask:0xf bank_mask:0xf
	v_fmac_f32_dpp v117, -v135, v17 quad_perm:[0,0,0,0] row_mask:0xf bank_mask:0xf
	ds_read_b64 v[164:165], v125 offset:14208
	v_fmac_f32_dpp v118, -v134, v19 quad_perm:[1,1,1,1] row_mask:0xf bank_mask:0xf
	v_fmac_f32_dpp v119, -v135, v20 quad_perm:[1,1,1,1] row_mask:0xf bank_mask:0xf
	v_fmac_f32_dpp v116, -v134, v21 quad_perm:[2,2,2,2] row_mask:0xf bank_mask:0xf
	ds_read_b64 v[166:167], v125 offset:14240
	v_fmac_f32_dpp v117, -v135, v22 quad_perm:[2,2,2,2] row_mask:0xf bank_mask:0xf
	v_fmac_f32_dpp v118, -v134, v23 quad_perm:[3,3,3,3] row_mask:0xf bank_mask:0xf
	v_fmac_f32_dpp v119, -v135, v24 quad_perm:[3,3,3,3] row_mask:0xf bank_mask:0xf
	ds_read_b64 v[168:169], v125 offset:14272
	v_fmac_f32_dpp v116, -v136, v25 quad_perm:[0,0,0,0] row_mask:0xf bank_mask:0xf
	v_fmac_f32_dpp v117, -v137, v27 quad_perm:[0,0,0,0] row_mask:0xf bank_mask:0xf
	v_fmac_f32_dpp v118, -v136, v28 quad_perm:[1,1,1,1] row_mask:0xf bank_mask:0xf
	ds_read_b64 v[170:171], v125 offset:14304
	v_fmac_f32_dpp v119, -v137, v29 quad_perm:[1,1,1,1] row_mask:0xf bank_mask:0xf
	v_fmac_f32_dpp v116, -v136, v30 quad_perm:[2,2,2,2] row_mask:0xf bank_mask:0xf
	v_fmac_f32_dpp v117, -v137, v31 quad_perm:[2,2,2,2] row_mask:0xf bank_mask:0xf
	ds_read_b64 v[172:173], v125 offset:14336
	v_fmac_f32_dpp v118, -v136, v32 quad_perm:[3,3,3,3] row_mask:0xf bank_mask:0xf
	v_fmac_f32_dpp v119, -v137, v33 quad_perm:[3,3,3,3] row_mask:0xf bank_mask:0xf
	v_fmac_f32_dpp v116, -v138, v34 quad_perm:[0,0,0,0] row_mask:0xf bank_mask:0xf
	ds_read_b32 v208, v124 offset:208
	v_fmac_f32_dpp v117, -v139, v35 quad_perm:[0,0,0,0] row_mask:0xf bank_mask:0xf
	v_fmac_f32_dpp v118, -v138, v36 quad_perm:[1,1,1,1] row_mask:0xf bank_mask:0xf
	v_fmac_f32_dpp v119, -v139, v37 quad_perm:[1,1,1,1] row_mask:0xf bank_mask:0xf
	ds_read_u16_d16_hi v248, v123 offset:14144
	v_fmac_f32_dpp v116, -v138, v38 quad_perm:[2,2,2,2] row_mask:0xf bank_mask:0xf
	v_fmac_f32_dpp v117, -v139, v39 quad_perm:[2,2,2,2] row_mask:0xf bank_mask:0xf
	v_fmac_f32_dpp v118, -v138, v40 quad_perm:[3,3,3,3] row_mask:0xf bank_mask:0xf
; #define GDN_LOADROW(buf, rr_, i_) do { _Pragma("unroll") for (int j4 = 0; j4 < ((i_) + 3) / 4; ++j4) buf[j4] = *(const f32x4*)(Lm + (i_) * GP_LSTR + 4 * j4); rr_ = bf2f(*(const bf16*)(xsrc + (i_) * GP_STR * 2)) * scl[i_]; } while (0)
; template <int STRIP> __device__ __forceinline__ void ph_gdn_prep_fast(const bf16* __restrict__ proj, const float* __restrict__ small, const float* __restrict__ conv_w, const float* __restrict__ a_log, const float* __restrict__ dt_bias, ...
;     ...
; #pragma unroll
;             for (int i = 0; i < 64; i += 2) {
;                 GDN_LOADROW(bB, rB, i + 1);
;                 GDN_ROW(bA, rA, i);
;                 if (i + 2 < 64) GDN_LOADROW(bA, rA, i + 2);
;                 GDN_ROW(bB, rB, i + 1);
	v_fmac_f32_dpp v119, -v139, v41 quad_perm:[3,3,3,3] row_mask:0xf bank_mask:0xf
	v_fmac_f32_dpp v116, -v140, v42 quad_perm:[0,0,0,0] row_mask:0xf bank_mask:0xf
	v_fmac_f32_dpp v117, -v141, v43 quad_perm:[0,0,0,0] row_mask:0xf bank_mask:0xf
	v_fmac_f32_dpp v118, -v140, v44 quad_perm:[1,1,1,1] row_mask:0xf bank_mask:0xf
	v_fmac_f32_dpp v119, -v141, v45 quad_perm:[1,1,1,1] row_mask:0xf bank_mask:0xf
	v_fmac_f32_dpp v116, -v140, v46 quad_perm:[2,2,2,2] row_mask:0xf bank_mask:0xf
	v_fmac_f32_dpp v117, -v141, v47 quad_perm:[2,2,2,2] row_mask:0xf bank_mask:0xf
	v_fmac_f32_dpp v118, -v140, v48 quad_perm:[3,3,3,3] row_mask:0xf bank_mask:0xf
	v_fmac_f32_dpp v119, -v141, v49 quad_perm:[3,3,3,3] row_mask:0xf bank_mask:0xf
	v_fmac_f32_dpp v116, -v142, v50 quad_perm:[0,0,0,0] row_mask:0xf bank_mask:0xf
	v_fmac_f32_dpp v117, -v143, v51 quad_perm:[0,0,0,0] row_mask:0xf bank_mask:0xf
	v_fmac_f32_dpp v118, -v142, v52 quad_perm:[1,1,1,1] row_mask:0xf bank_mask:0xf
	v_fmac_f32_dpp v119, -v143, v53 quad_perm:[1,1,1,1] row_mask:0xf bank_mask:0xf
	v_fmac_f32_dpp v116, -v142, v54 quad_perm:[2,2,2,2] row_mask:0xf bank_mask:0xf
	v_fmac_f32_dpp v117, -v143, v55 quad_perm:[2,2,2,2] row_mask:0xf bank_mask:0xf
	v_fmac_f32_dpp v118, -v142, v56 quad_perm:[3,3,3,3] row_mask:0xf bank_mask:0xf
	v_fmac_f32_dpp v119, -v143, v57 quad_perm:[3,3,3,3] row_mask:0xf bank_mask:0xf
	v_fmac_f32_dpp v116, -v144, v58 quad_perm:[0,0,0,0] row_mask:0xf bank_mask:0xf
	v_fmac_f32_dpp v117, -v145, v59 quad_perm:[0,0,0,0] row_mask:0xf bank_mask:0xf
	v_add_f32_e32 v121, v117, v116
	v_add_f32_e32 v122, v118, v119
	v_add_f32_e32 v60, v122, v121
	s_waitcnt lgkmcnt(9)
	v_mul_f32_dpp v120, v146, v4 quad_perm:[0,0,0,0] row_mask:0xf bank_mask:0xf
	v_fma_f32 v116, v185, v247, -v120
	v_mul_f32_dpp v117, -v147, v5 quad_perm:[0,0,0,0] row_mask:0xf bank_mask:0xf
	v_mul_f32_dpp v118, -v146, v6 quad_perm:[1,1,1,1] row_mask:0xf bank_mask:0xf
	v_mul_f32_dpp v119, -v147, v12 quad_perm:[1,1,1,1] row_mask:0xf bank_mask:0xf
	ds_read_b64 v[174:175], v125 offset:14416
	v_fmac_f32_dpp v116, -v146, v7 quad_perm:[2,2,2,2] row_mask:0xf bank_mask:0xf
	v_fmac_f32_dpp v117, -v147, v13 quad_perm:[2,2,2,2] row_mask:0xf bank_mask:0xf
	v_fmac_f32_dpp v118, -v146, v14 quad_perm:[3,3,3,3] row_mask:0xf bank_mask:0xf
	ds_read_b64 v[176:177], v125 offset:14448
	v_fmac_f32_dpp v119, -v147, v15 quad_perm:[3,3,3,3] row_mask:0xf bank_mask:0xf
	v_fmac_f32_dpp v116, -v148, v16 quad_perm:[0,0,0,0] row_mask:0xf bank_mask:0xf
	v_fmac_f32_dpp v117, -v149, v17 quad_perm:[0,0,0,0] row_mask:0xf bank_mask:0xf
	ds_read_b64 v[178:179], v125 offset:14480
	v_fmac_f32_dpp v118, -v148, v19 quad_perm:[1,1,1,1] row_mask:0xf bank_mask:0xf
	v_fmac_f32_dpp v119, -v149, v20 quad_perm:[1,1,1,1] row_mask:0xf bank_mask:0xf
	v_fmac_f32_dpp v116, -v148, v21 quad_perm:[2,2,2,2] row_mask:0xf bank_mask:0xf
	ds_read_b64 v[186:187], v125 offset:14512
	v_fmac_f32_dpp v117, -v149, v22 quad_perm:[2,2,2,2] row_mask:0xf bank_mask:0xf
	v_fmac_f32_dpp v118, -v148, v23 quad_perm:[3,3,3,3] row_mask:0xf bank_mask:0xf
	v_fmac_f32_dpp v119, -v149, v24 quad_perm:[3,3,3,3] row_mask:0xf bank_mask:0xf
	ds_read_b64 v[188:189], v125 offset:14544
	v_fmac_f32_dpp v116, -v150, v25 quad_perm:[0,0,0,0] row_mask:0xf bank_mask:0xf
	v_fmac_f32_dpp v117, -v151, v27 quad_perm:[0,0,0,0] row_mask:0xf bank_mask:0xf
	v_fmac_f32_dpp v118, -v150, v28 quad_perm:[1,1,1,1] row_mask:0xf bank_mask:0xf
	ds_read_b64 v[190:191], v125 offset:14576
	v_fmac_f32_dpp v119, -v151, v29 quad_perm:[1,1,1,1] row_mask:0xf bank_mask:0xf
	v_fmac_f32_dpp v116, -v150, v30 quad_perm:[2,2,2,2] row_mask:0xf bank_mask:0xf
	v_fmac_f32_dpp v117, -v151, v31 quad_perm:[2,2,2,2] row_mask:0xf bank_mask:0xf
	ds_read_b64 v[192:193], v125 offset:14608
	v_fmac_f32_dpp v118, -v150, v32 quad_perm:[3,3,3,3] row_mask:0xf bank_mask:0xf
	v_fmac_f32_dpp v119, -v151, v33 quad_perm:[3,3,3,3] row_mask:0xf bank_mask:0xf
	v_fmac_f32_dpp v116, -v152, v34 quad_perm:[0,0,0,0] row_mask:0xf bank_mask:0xf
	ds_read_b32 v209, v124 offset:212
	v_fmac_f32_dpp v117, -v153, v35 quad_perm:[0,0,0,0] row_mask:0xf bank_mask:0xf
	v_fmac_f32_dpp v118, -v152, v36 quad_perm:[1,1,1,1] row_mask:0xf bank_mask:0xf
	v_fmac_f32_dpp v119, -v153, v37 quad_perm:[1,1,1,1] row_mask:0xf bank_mask:0xf
	ds_read_u16_d16_hi v249, v123 offset:14416
	v_fmac_f32_dpp v116, -v152, v38 quad_perm:[2,2,2,2] row_mask:0xf bank_mask:0xf
	v_fmac_f32_dpp v117, -v153, v39 quad_perm:[2,2,2,2] row_mask:0xf bank_mask:0xf
	v_fmac_f32_dpp v118, -v152, v40 quad_perm:[3,3,3,3] row_mask:0xf bank_mask:0xf
	v_fmac_f32_dpp v119, -v153, v41 quad_perm:[3,3,3,3] row_mask:0xf bank_mask:0xf
	v_fmac_f32_dpp v116, -v154, v42 quad_perm:[0,0,0,0] row_mask:0xf bank_mask:0xf
	v_fmac_f32_dpp v117, -v155, v43 quad_perm:[0,0,0,0] row_mask:0xf bank_mask:0xf
	v_fmac_f32_dpp v118, -v154, v44 quad_perm:[1,1,1,1] row_mask:0xf bank_mask:0xf
	v_fmac_f32_dpp v119, -v155, v45 quad_perm:[1,1,1,1] row_mask:0xf bank_mask:0xf
	v_fmac_f32_dpp v116, -v154, v46 quad_perm:[2,2,2,2] row_mask:0xf bank_mask:0xf
	v_fmac_f32_dpp v117, -v155, v47 quad_perm:[2,2,2,2] row_mask:0xf bank_mask:0xf
	v_fmac_f32_dpp v118, -v154, v48 quad_perm:[3,3,3,3] row_mask:0xf bank_mask:0xf
	v_fmac_f32_dpp v119, -v155, v49 quad_perm:[3,3,3,3] row_mask:0xf bank_mask:0xf
	v_fmac_f32_dpp v116, -v156, v50 quad_perm:[0,0,0,0] row_mask:0xf bank_mask:0xf
	v_fmac_f32_dpp v117, -v157, v51 quad_perm:[0,0,0,0] row_mask:0xf bank_mask:0xf
	v_fmac_f32_dpp v118, -v156, v52 quad_perm:[1,1,1,1] row_mask:0xf bank_mask:0xf
	v_fmac_f32_dpp v119, -v157, v53 quad_perm:[1,1,1,1] row_mask:0xf bank_mask:0xf
	v_fmac_f32_dpp v116, -v156, v54 quad_perm:[2,2,2,2] row_mask:0xf bank_mask:0xf
	v_fmac_f32_dpp v117, -v157, v55 quad_perm:[2,2,2,2] row_mask:0xf bank_mask:0xf
	v_fmac_f32_dpp v118, -v156, v56 quad_perm:[3,3,3,3] row_mask:0xf bank_mask:0xf
	v_fmac_f32_dpp v119, -v157, v57 quad_perm:[3,3,3,3] row_mask:0xf bank_mask:0xf
	v_fmac_f32_dpp v116, -v158, v58 quad_perm:[0,0,0,0] row_mask:0xf bank_mask:0xf
	v_fmac_f32_dpp v117, -v159, v59 quad_perm:[0,0,0,0] row_mask:0xf bank_mask:0xf
	v_fmac_f32_dpp v118, -v158, v60 quad_perm:[1,1,1,1] row_mask:0xf bank_mask:0xf
	v_add_f32_e32 v121, v117, v116
	v_add_f32_e32 v122, v118, v119
	v_add_f32_e32 v61, v122, v121
	s_waitcnt lgkmcnt(9)
; #define GDN_LOADROW(buf, rr_, i_) do { _Pragma("unroll") for (int j4 = 0; j4 < ((i_) + 3) / 4; ++j4) buf[j4] = *(const f32x4*)(Lm + (i_) * GP_LSTR + 4 * j4); rr_ = bf2f(*(const bf16*)(xsrc + (i_) * GP_STR * 2)) * scl[i_]; } while (0)
; template <int STRIP> __device__ __forceinline__ void ph_gdn_prep_fast(const bf16* __restrict__ proj, const float* __restrict__ small, const float* __restrict__ conv_w, const float* __restrict__ a_log, const float* __restrict__ dt_bias, ...
;     ...
; #pragma unroll
;             for (int i = 0; i < 64; i += 2) {
;                 GDN_LOADROW(bB, rB, i + 1);
;                 GDN_ROW(bA, rA, i);
;                 if (i + 2 < 64) GDN_LOADROW(bA, rA, i + 2);
;                 GDN_ROW(bB, rB, i + 1);
	v_mul_f32_dpp v120, v160, v4 quad_perm:[0,0,0,0] row_mask:0xf bank_mask:0xf
	v_fma_f32 v116, v208, v248, -v120
	v_mul_f32_dpp v117, -v161, v5 quad_perm:[0,0,0,0] row_mask:0xf bank_mask:0xf
	v_mul_f32_dpp v118, -v160, v6 quad_perm:[1,1,1,1] row_mask:0xf bank_mask:0xf
	v_mul_f32_dpp v119, -v161, v12 quad_perm:[1,1,1,1] row_mask:0xf bank_mask:0xf
	ds_read_b64 v[194:195], v125 offset:14688
	v_fmac_f32_dpp v116, -v160, v7 quad_perm:[2,2,2,2] row_mask:0xf bank_mask:0xf
	v_fmac_f32_dpp v117, -v161, v13 quad_perm:[2,2,2,2] row_mask:0xf bank_mask:0xf
	v_fmac_f32_dpp v118, -v160, v14 quad_perm:[3,3,3,3] row_mask:0xf bank_mask:0xf
	ds_read_b64 v[196:197], v125 offset:14720
	v_fmac_f32_dpp v119, -v161, v15 quad_perm:[3,3,3,3] row_mask:0xf bank_mask:0xf
	v_fmac_f32_dpp v116, -v162, v16 quad_perm:[0,0,0,0] row_mask:0xf bank_mask:0xf
	v_fmac_f32_dpp v117, -v163, v17 quad_perm:[0,0,0,0] row_mask:0xf bank_mask:0xf
	ds_read_b64 v[198:199], v125 offset:14752
	v_fmac_f32_dpp v118, -v162, v19 quad_perm:[1,1,1,1] row_mask:0xf bank_mask:0xf
	v_fmac_f32_dpp v119, -v163, v20 quad_perm:[1,1,1,1] row_mask:0xf bank_mask:0xf
	v_fmac_f32_dpp v116, -v162, v21 quad_perm:[2,2,2,2] row_mask:0xf bank_mask:0xf
	ds_read_b64 v[200:201], v125 offset:14784
	v_fmac_f32_dpp v117, -v163, v22 quad_perm:[2,2,2,2] row_mask:0xf bank_mask:0xf
	v_fmac_f32_dpp v118, -v162, v23 quad_perm:[3,3,3,3] row_mask:0xf bank_mask:0xf
	v_fmac_f32_dpp v119, -v163, v24 quad_perm:[3,3,3,3] row_mask:0xf bank_mask:0xf
	ds_read_b64 v[202:203], v125 offset:14816
	v_fmac_f32_dpp v116, -v164, v25 quad_perm:[0,0,0,0] row_mask:0xf bank_mask:0xf
	v_fmac_f32_dpp v117, -v165, v27 quad_perm:[0,0,0,0] row_mask:0xf bank_mask:0xf
	v_fmac_f32_dpp v118, -v164, v28 quad_perm:[1,1,1,1] row_mask:0xf bank_mask:0xf
	ds_read_b64 v[204:205], v125 offset:14848
	v_fmac_f32_dpp v119, -v165, v29 quad_perm:[1,1,1,1] row_mask:0xf bank_mask:0xf
	v_fmac_f32_dpp v116, -v164, v30 quad_perm:[2,2,2,2] row_mask:0xf bank_mask:0xf
	v_fmac_f32_dpp v117, -v165, v31 quad_perm:[2,2,2,2] row_mask:0xf bank_mask:0xf
	ds_read_b64 v[206:207], v125 offset:14880
	v_fmac_f32_dpp v118, -v164, v32 quad_perm:[3,3,3,3] row_mask:0xf bank_mask:0xf
	v_fmac_f32_dpp v119, -v165, v33 quad_perm:[3,3,3,3] row_mask:0xf bank_mask:0xf
	v_fmac_f32_dpp v116, -v166, v34 quad_perm:[0,0,0,0] row_mask:0xf bank_mask:0xf
	ds_read_b32 v210, v124 offset:216
	v_fmac_f32_dpp v117, -v167, v35 quad_perm:[0,0,0,0] row_mask:0xf bank_mask:0xf
	v_fmac_f32_dpp v118, -v166, v36 quad_perm:[1,1,1,1] row_mask:0xf bank_mask:0xf
	v_fmac_f32_dpp v119, -v167, v37 quad_perm:[1,1,1,1] row_mask:0xf bank_mask:0xf
	ds_read_u16_d16_hi v250, v123 offset:14688
	v_fmac_f32_dpp v116, -v166, v38 quad_perm:[2,2,2,2] row_mask:0xf bank_mask:0xf
	v_fmac_f32_dpp v117, -v167, v39 quad_perm:[2,2,2,2] row_mask:0xf bank_mask:0xf
	v_fmac_f32_dpp v118, -v166, v40 quad_perm:[3,3,3,3] row_mask:0xf bank_mask:0xf
	v_fmac_f32_dpp v119, -v167, v41 quad_perm:[3,3,3,3] row_mask:0xf bank_mask:0xf
	v_fmac_f32_dpp v116, -v168, v42 quad_perm:[0,0,0,0] row_mask:0xf bank_mask:0xf
	v_fmac_f32_dpp v117, -v169, v43 quad_perm:[0,0,0,0] row_mask:0xf bank_mask:0xf
	v_fmac_f32_dpp v118, -v168, v44 quad_perm:[1,1,1,1] row_mask:0xf bank_mask:0xf
	v_fmac_f32_dpp v119, -v169, v45 quad_perm:[1,1,1,1] row_mask:0xf bank_mask:0xf
	v_fmac_f32_dpp v116, -v168, v46 quad_perm:[2,2,2,2] row_mask:0xf bank_mask:0xf
	v_fmac_f32_dpp v117, -v169, v47 quad_perm:[2,2,2,2] row_mask:0xf bank_mask:0xf
	v_fmac_f32_dpp v118, -v168, v48 quad_perm:[3,3,3,3] row_mask:0xf bank_mask:0xf
	v_fmac_f32_dpp v119, -v169, v49 quad_perm:[3,3,3,3] row_mask:0xf bank_mask:0xf
	v_fmac_f32_dpp v116, -v170, v50 quad_perm:[0,0,0,0] row_mask:0xf bank_mask:0xf
	v_fmac_f32_dpp v117, -v171, v51 quad_perm:[0,0,0,0] row_mask:0xf bank_mask:0xf
	v_fmac_f32_dpp v118, -v170, v52 quad_perm:[1,1,1,1] row_mask:0xf bank_mask:0xf
	v_fmac_f32_dpp v119, -v171, v53 quad_perm:[1,1,1,1] row_mask:0xf bank_mask:0xf
	v_fmac_f32_dpp v116, -v170, v54 quad_perm:[2,2,2,2] row_mask:0xf bank_mask:0xf
	v_fmac_f32_dpp v117, -v171, v55 quad_perm:[2,2,2,2] row_mask:0xf bank_mask:0xf
	v_fmac_f32_dpp v118, -v170, v56 quad_perm:[3,3,3,3] row_mask:0xf bank_mask:0xf
	v_fmac_f32_dpp v119, -v171, v57 quad_perm:[3,3,3,3] row_mask:0xf bank_mask:0xf
	v_fmac_f32_dpp v116, -v172, v58 quad_perm:[0,0,0,0] row_mask:0xf bank_mask:0xf
	v_fmac_f32_dpp v117, -v173, v59 quad_perm:[0,0,0,0] row_mask:0xf bank_mask:0xf
	v_fmac_f32_dpp v118, -v172, v60 quad_perm:[1,1,1,1] row_mask:0xf bank_mask:0xf
	v_fmac_f32_dpp v119, -v173, v61 quad_perm:[1,1,1,1] row_mask:0xf bank_mask:0xf
	v_add_f32_e32 v121, v117, v116
	v_add_f32_e32 v122, v118, v119
	v_add_f32_e32 v62, v122, v121
	s_waitcnt lgkmcnt(9)
; #define GDN_LOADROW(buf, rr_, i_) do { _Pragma("unroll") for (int j4 = 0; j4 < ((i_) + 3) / 4; ++j4) buf[j4] = *(const f32x4*)(Lm + (i_) * GP_LSTR + 4 * j4); rr_ = bf2f(*(const bf16*)(xsrc + (i_) * GP_STR * 2)) * scl[i_]; } while (0)
; template <int STRIP> __device__ __forceinline__ void ph_gdn_prep_fast(const bf16* __restrict__ proj, const float* __restrict__ small, const float* __restrict__ conv_w, const float* __restrict__ a_log, const float* __restrict__ dt_bias, ...
;     ...
; #pragma unroll
;             for (int i = 0; i < 64; i += 2) {
;                 GDN_LOADROW(bB, rB, i + 1);
;                 GDN_ROW(bA, rA, i);
;                 if (i + 2 < 64) GDN_LOADROW(bA, rA, i + 2);
;                 GDN_ROW(bB, rB, i + 1);
	v_mul_f32_dpp v120, v174, v4 quad_perm:[0,0,0,0] row_mask:0xf bank_mask:0xf
	v_fma_f32 v116, v209, v249, -v120
	v_mul_f32_dpp v117, -v175, v5 quad_perm:[0,0,0,0] row_mask:0xf bank_mask:0xf
	v_mul_f32_dpp v118, -v174, v6 quad_perm:[1,1,1,1] row_mask:0xf bank_mask:0xf
	v_mul_f32_dpp v119, -v175, v12 quad_perm:[1,1,1,1] row_mask:0xf bank_mask:0xf
	ds_read_b64 v[132:133], v125 offset:14960
	v_fmac_f32_dpp v116, -v174, v7 quad_perm:[2,2,2,2] row_mask:0xf bank_mask:0xf
	v_fmac_f32_dpp v117, -v175, v13 quad_perm:[2,2,2,2] row_mask:0xf bank_mask:0xf
	v_fmac_f32_dpp v118, -v174, v14 quad_perm:[3,3,3,3] row_mask:0xf bank_mask:0xf
	ds_read_b64 v[134:135], v125 offset:14992
	v_fmac_f32_dpp v119, -v175, v15 quad_perm:[3,3,3,3] row_mask:0xf bank_mask:0xf
	v_fmac_f32_dpp v116, -v176, v16 quad_perm:[0,0,0,0] row_mask:0xf bank_mask:0xf
	v_fmac_f32_dpp v117, -v177, v17 quad_perm:[0,0,0,0] row_mask:0xf bank_mask:0xf
	ds_read_b64 v[136:137], v125 offset:15024
	v_fmac_f32_dpp v118, -v176, v19 quad_perm:[1,1,1,1] row_mask:0xf bank_mask:0xf
	v_fmac_f32_dpp v119, -v177, v20 quad_perm:[1,1,1,1] row_mask:0xf bank_mask:0xf
	v_fmac_f32_dpp v116, -v176, v21 quad_perm:[2,2,2,2] row_mask:0xf bank_mask:0xf
	ds_read_b64 v[138:139], v125 offset:15056
	v_fmac_f32_dpp v117, -v177, v22 quad_perm:[2,2,2,2] row_mask:0xf bank_mask:0xf
	v_fmac_f32_dpp v118, -v176, v23 quad_perm:[3,3,3,3] row_mask:0xf bank_mask:0xf
	v_fmac_f32_dpp v119, -v177, v24 quad_perm:[3,3,3,3] row_mask:0xf bank_mask:0xf
	ds_read_b64 v[140:141], v125 offset:15088
	v_fmac_f32_dpp v116, -v178, v25 quad_perm:[0,0,0,0] row_mask:0xf bank_mask:0xf
	v_fmac_f32_dpp v117, -v179, v27 quad_perm:[0,0,0,0] row_mask:0xf bank_mask:0xf
	v_fmac_f32_dpp v118, -v178, v28 quad_perm:[1,1,1,1] row_mask:0xf bank_mask:0xf
	ds_read_b64 v[142:143], v125 offset:15120
	v_fmac_f32_dpp v119, -v179, v29 quad_perm:[1,1,1,1] row_mask:0xf bank_mask:0xf
	v_fmac_f32_dpp v116, -v178, v30 quad_perm:[2,2,2,2] row_mask:0xf bank_mask:0xf
	v_fmac_f32_dpp v117, -v179, v31 quad_perm:[2,2,2,2] row_mask:0xf bank_mask:0xf
	ds_read_b64 v[144:145], v125 offset:15152
	v_fmac_f32_dpp v118, -v178, v32 quad_perm:[3,3,3,3] row_mask:0xf bank_mask:0xf
	v_fmac_f32_dpp v119, -v179, v33 quad_perm:[3,3,3,3] row_mask:0xf bank_mask:0xf
	v_fmac_f32_dpp v116, -v186, v34 quad_perm:[0,0,0,0] row_mask:0xf bank_mask:0xf
	ds_read_b32 v211, v124 offset:220
	v_fmac_f32_dpp v117, -v187, v35 quad_perm:[0,0,0,0] row_mask:0xf bank_mask:0xf
	v_fmac_f32_dpp v118, -v186, v36 quad_perm:[1,1,1,1] row_mask:0xf bank_mask:0xf
	v_fmac_f32_dpp v119, -v187, v37 quad_perm:[1,1,1,1] row_mask:0xf bank_mask:0xf
	ds_read_u16_d16_hi v251, v123 offset:14960
	v_fmac_f32_dpp v116, -v186, v38 quad_perm:[2,2,2,2] row_mask:0xf bank_mask:0xf
	v_fmac_f32_dpp v117, -v187, v39 quad_perm:[2,2,2,2] row_mask:0xf bank_mask:0xf
	v_fmac_f32_dpp v118, -v186, v40 quad_perm:[3,3,3,3] row_mask:0xf bank_mask:0xf
	v_fmac_f32_dpp v119, -v187, v41 quad_perm:[3,3,3,3] row_mask:0xf bank_mask:0xf
	v_fmac_f32_dpp v116, -v188, v42 quad_perm:[0,0,0,0] row_mask:0xf bank_mask:0xf
	v_fmac_f32_dpp v117, -v189, v43 quad_perm:[0,0,0,0] row_mask:0xf bank_mask:0xf
	v_fmac_f32_dpp v118, -v188, v44 quad_perm:[1,1,1,1] row_mask:0xf bank_mask:0xf
	v_fmac_f32_dpp v119, -v189, v45 quad_perm:[1,1,1,1] row_mask:0xf bank_mask:0xf
	v_fmac_f32_dpp v116, -v188, v46 quad_perm:[2,2,2,2] row_mask:0xf bank_mask:0xf
	v_fmac_f32_dpp v117, -v189, v47 quad_perm:[2,2,2,2] row_mask:0xf bank_mask:0xf
	v_fmac_f32_dpp v118, -v188, v48 quad_perm:[3,3,3,3] row_mask:0xf bank_mask:0xf
	v_fmac_f32_dpp v119, -v189, v49 quad_perm:[3,3,3,3] row_mask:0xf bank_mask:0xf
	v_fmac_f32_dpp v116, -v190, v50 quad_perm:[0,0,0,0] row_mask:0xf bank_mask:0xf
	v_fmac_f32_dpp v117, -v191, v51 quad_perm:[0,0,0,0] row_mask:0xf bank_mask:0xf
	v_fmac_f32_dpp v118, -v190, v52 quad_perm:[1,1,1,1] row_mask:0xf bank_mask:0xf
	v_fmac_f32_dpp v119, -v191, v53 quad_perm:[1,1,1,1] row_mask:0xf bank_mask:0xf
	v_fmac_f32_dpp v116, -v190, v54 quad_perm:[2,2,2,2] row_mask:0xf bank_mask:0xf
	v_fmac_f32_dpp v117, -v191, v55 quad_perm:[2,2,2,2] row_mask:0xf bank_mask:0xf
	v_fmac_f32_dpp v118, -v190, v56 quad_perm:[3,3,3,3] row_mask:0xf bank_mask:0xf
	v_fmac_f32_dpp v119, -v191, v57 quad_perm:[3,3,3,3] row_mask:0xf bank_mask:0xf
	v_fmac_f32_dpp v116, -v192, v58 quad_perm:[0,0,0,0] row_mask:0xf bank_mask:0xf
	v_fmac_f32_dpp v117, -v193, v59 quad_perm:[0,0,0,0] row_mask:0xf bank_mask:0xf
	v_fmac_f32_dpp v118, -v192, v60 quad_perm:[1,1,1,1] row_mask:0xf bank_mask:0xf
	v_fmac_f32_dpp v119, -v193, v61 quad_perm:[1,1,1,1] row_mask:0xf bank_mask:0xf
	v_fmac_f32_dpp v116, -v192, v62 quad_perm:[2,2,2,2] row_mask:0xf bank_mask:0xf
	v_add_f32_e32 v121, v117, v116
	v_add_f32_e32 v122, v118, v119
	v_add_f32_e32 v63, v122, v121
	s_waitcnt lgkmcnt(9)
; #define GDN_LOADROW(buf, rr_, i_) do { _Pragma("unroll") for (int j4 = 0; j4 < ((i_) + 3) / 4; ++j4) buf[j4] = *(const f32x4*)(Lm + (i_) * GP_LSTR + 4 * j4); rr_ = bf2f(*(const bf16*)(xsrc + (i_) * GP_STR * 2)) * scl[i_]; } while (0)
; template <int STRIP> __device__ __forceinline__ void ph_gdn_prep_fast(const bf16* __restrict__ proj, const float* __restrict__ small, const float* __restrict__ conv_w, const float* __restrict__ a_log, const float* __restrict__ dt_bias, ...
;     ...
; #pragma unroll
;             for (int i = 0; i < 64; i += 2) {
;                 GDN_LOADROW(bB, rB, i + 1);
;                 GDN_ROW(bA, rA, i);
;                 if (i + 2 < 64) GDN_LOADROW(bA, rA, i + 2);
;                 GDN_ROW(bB, rB, i + 1);
	v_mul_f32_dpp v120, v194, v4 quad_perm:[0,0,0,0] row_mask:0xf bank_mask:0xf
	v_fma_f32 v116, v210, v250, -v120
	v_mul_f32_dpp v117, -v195, v5 quad_perm:[0,0,0,0] row_mask:0xf bank_mask:0xf
	v_mul_f32_dpp v118, -v194, v6 quad_perm:[1,1,1,1] row_mask:0xf bank_mask:0xf
	v_mul_f32_dpp v119, -v195, v12 quad_perm:[1,1,1,1] row_mask:0xf bank_mask:0xf
	ds_read_b64 v[146:147], v125 offset:15232
	v_fmac_f32_dpp v116, -v194, v7 quad_perm:[2,2,2,2] row_mask:0xf bank_mask:0xf
	v_fmac_f32_dpp v117, -v195, v13 quad_perm:[2,2,2,2] row_mask:0xf bank_mask:0xf
	v_fmac_f32_dpp v118, -v194, v14 quad_perm:[3,3,3,3] row_mask:0xf bank_mask:0xf
	ds_read_b64 v[148:149], v125 offset:15264
	v_fmac_f32_dpp v119, -v195, v15 quad_perm:[3,3,3,3] row_mask:0xf bank_mask:0xf
	v_fmac_f32_dpp v116, -v196, v16 quad_perm:[0,0,0,0] row_mask:0xf bank_mask:0xf
	v_fmac_f32_dpp v117, -v197, v17 quad_perm:[0,0,0,0] row_mask:0xf bank_mask:0xf
	ds_read_b64 v[150:151], v125 offset:15296
	v_fmac_f32_dpp v118, -v196, v19 quad_perm:[1,1,1,1] row_mask:0xf bank_mask:0xf
	v_fmac_f32_dpp v119, -v197, v20 quad_perm:[1,1,1,1] row_mask:0xf bank_mask:0xf
	v_fmac_f32_dpp v116, -v196, v21 quad_perm:[2,2,2,2] row_mask:0xf bank_mask:0xf
	ds_read_b64 v[152:153], v125 offset:15328
	v_fmac_f32_dpp v117, -v197, v22 quad_perm:[2,2,2,2] row_mask:0xf bank_mask:0xf
	v_fmac_f32_dpp v118, -v196, v23 quad_perm:[3,3,3,3] row_mask:0xf bank_mask:0xf
	v_fmac_f32_dpp v119, -v197, v24 quad_perm:[3,3,3,3] row_mask:0xf bank_mask:0xf
	ds_read_b64 v[154:155], v125 offset:15360
	v_fmac_f32_dpp v116, -v198, v25 quad_perm:[0,0,0,0] row_mask:0xf bank_mask:0xf
	v_fmac_f32_dpp v117, -v199, v27 quad_perm:[0,0,0,0] row_mask:0xf bank_mask:0xf
	v_fmac_f32_dpp v118, -v198, v28 quad_perm:[1,1,1,1] row_mask:0xf bank_mask:0xf
	ds_read_b64 v[156:157], v125 offset:15392
	v_fmac_f32_dpp v119, -v199, v29 quad_perm:[1,1,1,1] row_mask:0xf bank_mask:0xf
	v_fmac_f32_dpp v116, -v198, v30 quad_perm:[2,2,2,2] row_mask:0xf bank_mask:0xf
	v_fmac_f32_dpp v117, -v199, v31 quad_perm:[2,2,2,2] row_mask:0xf bank_mask:0xf
	ds_read_b64 v[158:159], v125 offset:15424
	v_fmac_f32_dpp v118, -v198, v32 quad_perm:[3,3,3,3] row_mask:0xf bank_mask:0xf
	v_fmac_f32_dpp v119, -v199, v33 quad_perm:[3,3,3,3] row_mask:0xf bank_mask:0xf
	v_fmac_f32_dpp v116, -v200, v34 quad_perm:[0,0,0,0] row_mask:0xf bank_mask:0xf
	ds_read_b32 v212, v124 offset:224
	v_fmac_f32_dpp v117, -v201, v35 quad_perm:[0,0,0,0] row_mask:0xf bank_mask:0xf
	v_fmac_f32_dpp v118, -v200, v36 quad_perm:[1,1,1,1] row_mask:0xf bank_mask:0xf
	v_fmac_f32_dpp v119, -v201, v37 quad_perm:[1,1,1,1] row_mask:0xf bank_mask:0xf
	ds_read_u16_d16_hi v252, v123 offset:15232
	v_fmac_f32_dpp v116, -v200, v38 quad_perm:[2,2,2,2] row_mask:0xf bank_mask:0xf
	v_fmac_f32_dpp v117, -v201, v39 quad_perm:[2,2,2,2] row_mask:0xf bank_mask:0xf
	v_fmac_f32_dpp v118, -v200, v40 quad_perm:[3,3,3,3] row_mask:0xf bank_mask:0xf
	v_fmac_f32_dpp v119, -v201, v41 quad_perm:[3,3,3,3] row_mask:0xf bank_mask:0xf
	v_fmac_f32_dpp v116, -v202, v42 quad_perm:[0,0,0,0] row_mask:0xf bank_mask:0xf
	v_fmac_f32_dpp v117, -v203, v43 quad_perm:[0,0,0,0] row_mask:0xf bank_mask:0xf
	v_fmac_f32_dpp v118, -v202, v44 quad_perm:[1,1,1,1] row_mask:0xf bank_mask:0xf
	v_fmac_f32_dpp v119, -v203, v45 quad_perm:[1,1,1,1] row_mask:0xf bank_mask:0xf
	v_fmac_f32_dpp v116, -v202, v46 quad_perm:[2,2,2,2] row_mask:0xf bank_mask:0xf
	v_fmac_f32_dpp v117, -v203, v47 quad_perm:[2,2,2,2] row_mask:0xf bank_mask:0xf
	v_fmac_f32_dpp v118, -v202, v48 quad_perm:[3,3,3,3] row_mask:0xf bank_mask:0xf
	v_fmac_f32_dpp v119, -v203, v49 quad_perm:[3,3,3,3] row_mask:0xf bank_mask:0xf
	v_fmac_f32_dpp v116, -v204, v50 quad_perm:[0,0,0,0] row_mask:0xf bank_mask:0xf
	v_fmac_f32_dpp v117, -v205, v51 quad_perm:[0,0,0,0] row_mask:0xf bank_mask:0xf
	v_fmac_f32_dpp v118, -v204, v52 quad_perm:[1,1,1,1] row_mask:0xf bank_mask:0xf
	v_fmac_f32_dpp v119, -v205, v53 quad_perm:[1,1,1,1] row_mask:0xf bank_mask:0xf
	v_fmac_f32_dpp v116, -v204, v54 quad_perm:[2,2,2,2] row_mask:0xf bank_mask:0xf
	v_fmac_f32_dpp v117, -v205, v55 quad_perm:[2,2,2,2] row_mask:0xf bank_mask:0xf
	v_fmac_f32_dpp v118, -v204, v56 quad_perm:[3,3,3,3] row_mask:0xf bank_mask:0xf
	v_fmac_f32_dpp v119, -v205, v57 quad_perm:[3,3,3,3] row_mask:0xf bank_mask:0xf
	v_fmac_f32_dpp v116, -v206, v58 quad_perm:[0,0,0,0] row_mask:0xf bank_mask:0xf
	v_fmac_f32_dpp v117, -v207, v59 quad_perm:[0,0,0,0] row_mask:0xf bank_mask:0xf
	v_fmac_f32_dpp v118, -v206, v60 quad_perm:[1,1,1,1] row_mask:0xf bank_mask:0xf
	v_fmac_f32_dpp v119, -v207, v61 quad_perm:[1,1,1,1] row_mask:0xf bank_mask:0xf
	v_fmac_f32_dpp v116, -v206, v62 quad_perm:[2,2,2,2] row_mask:0xf bank_mask:0xf
	v_fmac_f32_dpp v117, -v207, v63 quad_perm:[2,2,2,2] row_mask:0xf bank_mask:0xf
	v_add_f32_e32 v121, v117, v116
	v_add_f32_e32 v122, v118, v119
	v_add_f32_e32 v64, v122, v121
	s_waitcnt lgkmcnt(9)
; #define GDN_LOADROW(buf, rr_, i_) do { _Pragma("unroll") for (int j4 = 0; j4 < ((i_) + 3) / 4; ++j4) buf[j4] = *(const f32x4*)(Lm + (i_) * GP_LSTR + 4 * j4); rr_ = bf2f(*(const bf16*)(xsrc + (i_) * GP_STR * 2)) * scl[i_]; } while (0)
; template <int STRIP> __device__ __forceinline__ void ph_gdn_prep_fast(const bf16* __restrict__ proj, const float* __restrict__ small, const float* __restrict__ conv_w, const float* __restrict__ a_log, const float* __restrict__ dt_bias, ...
;     ...
; #pragma unroll
;             for (int i = 0; i < 64; i += 2) {
;                 GDN_LOADROW(bB, rB, i + 1);
;                 GDN_ROW(bA, rA, i);
;                 if (i + 2 < 64) GDN_LOADROW(bA, rA, i + 2);
;                 GDN_ROW(bB, rB, i + 1);
	v_mul_f32_dpp v120, v132, v4 quad_perm:[0,0,0,0] row_mask:0xf bank_mask:0xf
	v_fma_f32 v116, v211, v251, -v120
	v_mul_f32_dpp v117, -v133, v5 quad_perm:[0,0,0,0] row_mask:0xf bank_mask:0xf
	v_mul_f32_dpp v118, -v132, v6 quad_perm:[1,1,1,1] row_mask:0xf bank_mask:0xf
	v_mul_f32_dpp v119, -v133, v12 quad_perm:[1,1,1,1] row_mask:0xf bank_mask:0xf
	ds_read_b64 v[160:161], v125 offset:15504
	v_fmac_f32_dpp v116, -v132, v7 quad_perm:[2,2,2,2] row_mask:0xf bank_mask:0xf
	v_fmac_f32_dpp v117, -v133, v13 quad_perm:[2,2,2,2] row_mask:0xf bank_mask:0xf
	v_fmac_f32_dpp v118, -v132, v14 quad_perm:[3,3,3,3] row_mask:0xf bank_mask:0xf
	ds_read_b64 v[162:163], v125 offset:15536
	v_fmac_f32_dpp v119, -v133, v15 quad_perm:[3,3,3,3] row_mask:0xf bank_mask:0xf
	v_fmac_f32_dpp v116, -v134, v16 quad_perm:[0,0,0,0] row_mask:0xf bank_mask:0xf
	v_fmac_f32_dpp v117, -v135, v17 quad_perm:[0,0,0,0] row_mask:0xf bank_mask:0xf
	ds_read_b64 v[164:165], v125 offset:15568
	v_fmac_f32_dpp v118, -v134, v19 quad_perm:[1,1,1,1] row_mask:0xf bank_mask:0xf
	v_fmac_f32_dpp v119, -v135, v20 quad_perm:[1,1,1,1] row_mask:0xf bank_mask:0xf
	v_fmac_f32_dpp v116, -v134, v21 quad_perm:[2,2,2,2] row_mask:0xf bank_mask:0xf
	ds_read_b64 v[166:167], v125 offset:15600
	v_fmac_f32_dpp v117, -v135, v22 quad_perm:[2,2,2,2] row_mask:0xf bank_mask:0xf
	v_fmac_f32_dpp v118, -v134, v23 quad_perm:[3,3,3,3] row_mask:0xf bank_mask:0xf
	v_fmac_f32_dpp v119, -v135, v24 quad_perm:[3,3,3,3] row_mask:0xf bank_mask:0xf
	ds_read_b64 v[168:169], v125 offset:15632
	v_fmac_f32_dpp v116, -v136, v25 quad_perm:[0,0,0,0] row_mask:0xf bank_mask:0xf
	v_fmac_f32_dpp v117, -v137, v27 quad_perm:[0,0,0,0] row_mask:0xf bank_mask:0xf
	v_fmac_f32_dpp v118, -v136, v28 quad_perm:[1,1,1,1] row_mask:0xf bank_mask:0xf
	ds_read_b64 v[170:171], v125 offset:15664
	v_fmac_f32_dpp v119, -v137, v29 quad_perm:[1,1,1,1] row_mask:0xf bank_mask:0xf
	v_fmac_f32_dpp v116, -v136, v30 quad_perm:[2,2,2,2] row_mask:0xf bank_mask:0xf
	v_fmac_f32_dpp v117, -v137, v31 quad_perm:[2,2,2,2] row_mask:0xf bank_mask:0xf
	ds_read_b64 v[172:173], v125 offset:15696
	v_fmac_f32_dpp v118, -v136, v32 quad_perm:[3,3,3,3] row_mask:0xf bank_mask:0xf
	v_fmac_f32_dpp v119, -v137, v33 quad_perm:[3,3,3,3] row_mask:0xf bank_mask:0xf
	v_fmac_f32_dpp v116, -v138, v34 quad_perm:[0,0,0,0] row_mask:0xf bank_mask:0xf
	ds_read_b64 v[174:175], v125 offset:15728
	v_fmac_f32_dpp v117, -v139, v35 quad_perm:[0,0,0,0] row_mask:0xf bank_mask:0xf
	v_fmac_f32_dpp v118, -v138, v36 quad_perm:[1,1,1,1] row_mask:0xf bank_mask:0xf
	v_fmac_f32_dpp v119, -v139, v37 quad_perm:[1,1,1,1] row_mask:0xf bank_mask:0xf
	ds_read_b32 v213, v124 offset:228
	v_fmac_f32_dpp v116, -v138, v38 quad_perm:[2,2,2,2] row_mask:0xf bank_mask:0xf
	v_fmac_f32_dpp v117, -v139, v39 quad_perm:[2,2,2,2] row_mask:0xf bank_mask:0xf
	v_fmac_f32_dpp v118, -v138, v40 quad_perm:[3,3,3,3] row_mask:0xf bank_mask:0xf
	ds_read_u16_d16_hi v253, v123 offset:15504
	v_fmac_f32_dpp v119, -v139, v41 quad_perm:[3,3,3,3] row_mask:0xf bank_mask:0xf
	v_fmac_f32_dpp v116, -v140, v42 quad_perm:[0,0,0,0] row_mask:0xf bank_mask:0xf
	v_fmac_f32_dpp v117, -v141, v43 quad_perm:[0,0,0,0] row_mask:0xf bank_mask:0xf
	v_fmac_f32_dpp v118, -v140, v44 quad_perm:[1,1,1,1] row_mask:0xf bank_mask:0xf
	v_fmac_f32_dpp v119, -v141, v45 quad_perm:[1,1,1,1] row_mask:0xf bank_mask:0xf
	v_fmac_f32_dpp v116, -v140, v46 quad_perm:[2,2,2,2] row_mask:0xf bank_mask:0xf
	v_fmac_f32_dpp v117, -v141, v47 quad_perm:[2,2,2,2] row_mask:0xf bank_mask:0xf
	v_fmac_f32_dpp v118, -v140, v48 quad_perm:[3,3,3,3] row_mask:0xf bank_mask:0xf
	v_fmac_f32_dpp v119, -v141, v49 quad_perm:[3,3,3,3] row_mask:0xf bank_mask:0xf
	v_fmac_f32_dpp v116, -v142, v50 quad_perm:[0,0,0,0] row_mask:0xf bank_mask:0xf
	v_fmac_f32_dpp v117, -v143, v51 quad_perm:[0,0,0,0] row_mask:0xf bank_mask:0xf
	v_fmac_f32_dpp v118, -v142, v52 quad_perm:[1,1,1,1] row_mask:0xf bank_mask:0xf
	v_fmac_f32_dpp v119, -v143, v53 quad_perm:[1,1,1,1] row_mask:0xf bank_mask:0xf
	v_fmac_f32_dpp v116, -v142, v54 quad_perm:[2,2,2,2] row_mask:0xf bank_mask:0xf
	v_fmac_f32_dpp v117, -v143, v55 quad_perm:[2,2,2,2] row_mask:0xf bank_mask:0xf
	v_fmac_f32_dpp v118, -v142, v56 quad_perm:[3,3,3,3] row_mask:0xf bank_mask:0xf
	v_fmac_f32_dpp v119, -v143, v57 quad_perm:[3,3,3,3] row_mask:0xf bank_mask:0xf
	v_fmac_f32_dpp v116, -v144, v58 quad_perm:[0,0,0,0] row_mask:0xf bank_mask:0xf
	v_fmac_f32_dpp v117, -v145, v59 quad_perm:[0,0,0,0] row_mask:0xf bank_mask:0xf
	v_fmac_f32_dpp v118, -v144, v60 quad_perm:[1,1,1,1] row_mask:0xf bank_mask:0xf
	v_fmac_f32_dpp v119, -v145, v61 quad_perm:[1,1,1,1] row_mask:0xf bank_mask:0xf
	v_fmac_f32_dpp v116, -v144, v62 quad_perm:[2,2,2,2] row_mask:0xf bank_mask:0xf
	v_fmac_f32_dpp v117, -v145, v63 quad_perm:[2,2,2,2] row_mask:0xf bank_mask:0xf
	v_fmac_f32_dpp v118, -v144, v64 quad_perm:[3,3,3,3] row_mask:0xf bank_mask:0xf
	v_add_f32_e32 v121, v117, v116
	v_add_f32_e32 v122, v118, v119
	v_add_f32_e32 v65, v122, v121
	s_waitcnt lgkmcnt(10)
; #define GDN_LOADROW(buf, rr_, i_) do { _Pragma("unroll") for (int j4 = 0; j4 < ((i_) + 3) / 4; ++j4) buf[j4] = *(const f32x4*)(Lm + (i_) * GP_LSTR + 4 * j4); rr_ = bf2f(*(const bf16*)(xsrc + (i_) * GP_STR * 2)) * scl[i_]; } while (0)
; template <int STRIP> __device__ __forceinline__ void ph_gdn_prep_fast(const bf16* __restrict__ proj, const float* __restrict__ small, const float* __restrict__ conv_w, const float* __restrict__ a_log, const float* __restrict__ dt_bias, ...
;     ...
; #pragma unroll
;             for (int i = 0; i < 64; i += 2) {
;                 GDN_LOADROW(bB, rB, i + 1);
;                 GDN_ROW(bA, rA, i);
;                 if (i + 2 < 64) GDN_LOADROW(bA, rA, i + 2);
;                 GDN_ROW(bB, rB, i + 1);
	v_mul_f32_dpp v120, v146, v4 quad_perm:[0,0,0,0] row_mask:0xf bank_mask:0xf
	v_fma_f32 v116, v212, v252, -v120
	v_mul_f32_dpp v117, -v147, v5 quad_perm:[0,0,0,0] row_mask:0xf bank_mask:0xf
	v_mul_f32_dpp v118, -v146, v6 quad_perm:[1,1,1,1] row_mask:0xf bank_mask:0xf
	v_mul_f32_dpp v119, -v147, v12 quad_perm:[1,1,1,1] row_mask:0xf bank_mask:0xf
	ds_read_b64 v[176:177], v125 offset:15776
	v_fmac_f32_dpp v116, -v146, v7 quad_perm:[2,2,2,2] row_mask:0xf bank_mask:0xf
	v_fmac_f32_dpp v117, -v147, v13 quad_perm:[2,2,2,2] row_mask:0xf bank_mask:0xf
	v_fmac_f32_dpp v118, -v146, v14 quad_perm:[3,3,3,3] row_mask:0xf bank_mask:0xf
	ds_read_b64 v[178:179], v125 offset:15808
	v_fmac_f32_dpp v119, -v147, v15 quad_perm:[3,3,3,3] row_mask:0xf bank_mask:0xf
	v_fmac_f32_dpp v116, -v148, v16 quad_perm:[0,0,0,0] row_mask:0xf bank_mask:0xf
	v_fmac_f32_dpp v117, -v149, v17 quad_perm:[0,0,0,0] row_mask:0xf bank_mask:0xf
	ds_read_b64 v[186:187], v125 offset:15840
	v_fmac_f32_dpp v118, -v148, v19 quad_perm:[1,1,1,1] row_mask:0xf bank_mask:0xf
	v_fmac_f32_dpp v119, -v149, v20 quad_perm:[1,1,1,1] row_mask:0xf bank_mask:0xf
	v_fmac_f32_dpp v116, -v148, v21 quad_perm:[2,2,2,2] row_mask:0xf bank_mask:0xf
	ds_read_b64 v[188:189], v125 offset:15872
	v_fmac_f32_dpp v117, -v149, v22 quad_perm:[2,2,2,2] row_mask:0xf bank_mask:0xf
	v_fmac_f32_dpp v118, -v148, v23 quad_perm:[3,3,3,3] row_mask:0xf bank_mask:0xf
	v_fmac_f32_dpp v119, -v149, v24 quad_perm:[3,3,3,3] row_mask:0xf bank_mask:0xf
	ds_read_b64 v[190:191], v125 offset:15904
	v_fmac_f32_dpp v116, -v150, v25 quad_perm:[0,0,0,0] row_mask:0xf bank_mask:0xf
	v_fmac_f32_dpp v117, -v151, v27 quad_perm:[0,0,0,0] row_mask:0xf bank_mask:0xf
	v_fmac_f32_dpp v118, -v150, v28 quad_perm:[1,1,1,1] row_mask:0xf bank_mask:0xf
	ds_read_b64 v[192:193], v125 offset:15936
	v_fmac_f32_dpp v119, -v151, v29 quad_perm:[1,1,1,1] row_mask:0xf bank_mask:0xf
	v_fmac_f32_dpp v116, -v150, v30 quad_perm:[2,2,2,2] row_mask:0xf bank_mask:0xf
	v_fmac_f32_dpp v117, -v151, v31 quad_perm:[2,2,2,2] row_mask:0xf bank_mask:0xf
	ds_read_b64 v[194:195], v125 offset:15968
	v_fmac_f32_dpp v118, -v150, v32 quad_perm:[3,3,3,3] row_mask:0xf bank_mask:0xf
	v_fmac_f32_dpp v119, -v151, v33 quad_perm:[3,3,3,3] row_mask:0xf bank_mask:0xf
	v_fmac_f32_dpp v116, -v152, v34 quad_perm:[0,0,0,0] row_mask:0xf bank_mask:0xf
	ds_read_b64 v[196:197], v125 offset:16000
	v_fmac_f32_dpp v117, -v153, v35 quad_perm:[0,0,0,0] row_mask:0xf bank_mask:0xf
	v_fmac_f32_dpp v118, -v152, v36 quad_perm:[1,1,1,1] row_mask:0xf bank_mask:0xf
	v_fmac_f32_dpp v119, -v153, v37 quad_perm:[1,1,1,1] row_mask:0xf bank_mask:0xf
	ds_read_b32 v214, v124 offset:232
	v_fmac_f32_dpp v116, -v152, v38 quad_perm:[2,2,2,2] row_mask:0xf bank_mask:0xf
	v_fmac_f32_dpp v117, -v153, v39 quad_perm:[2,2,2,2] row_mask:0xf bank_mask:0xf
	v_fmac_f32_dpp v118, -v152, v40 quad_perm:[3,3,3,3] row_mask:0xf bank_mask:0xf
	ds_read_u16_d16_hi v126, v123 offset:15776
	v_fmac_f32_dpp v119, -v153, v41 quad_perm:[3,3,3,3] row_mask:0xf bank_mask:0xf
	v_fmac_f32_dpp v116, -v154, v42 quad_perm:[0,0,0,0] row_mask:0xf bank_mask:0xf
	v_fmac_f32_dpp v117, -v155, v43 quad_perm:[0,0,0,0] row_mask:0xf bank_mask:0xf
	v_fmac_f32_dpp v118, -v154, v44 quad_perm:[1,1,1,1] row_mask:0xf bank_mask:0xf
	v_fmac_f32_dpp v119, -v155, v45 quad_perm:[1,1,1,1] row_mask:0xf bank_mask:0xf
	v_fmac_f32_dpp v116, -v154, v46 quad_perm:[2,2,2,2] row_mask:0xf bank_mask:0xf
	v_fmac_f32_dpp v117, -v155, v47 quad_perm:[2,2,2,2] row_mask:0xf bank_mask:0xf
	v_fmac_f32_dpp v118, -v154, v48 quad_perm:[3,3,3,3] row_mask:0xf bank_mask:0xf
	v_fmac_f32_dpp v119, -v155, v49 quad_perm:[3,3,3,3] row_mask:0xf bank_mask:0xf
	v_fmac_f32_dpp v116, -v156, v50 quad_perm:[0,0,0,0] row_mask:0xf bank_mask:0xf
	v_fmac_f32_dpp v117, -v157, v51 quad_perm:[0,0,0,0] row_mask:0xf bank_mask:0xf
	v_fmac_f32_dpp v118, -v156, v52 quad_perm:[1,1,1,1] row_mask:0xf bank_mask:0xf
	v_fmac_f32_dpp v119, -v157, v53 quad_perm:[1,1,1,1] row_mask:0xf bank_mask:0xf
	v_fmac_f32_dpp v116, -v156, v54 quad_perm:[2,2,2,2] row_mask:0xf bank_mask:0xf
	v_fmac_f32_dpp v117, -v157, v55 quad_perm:[2,2,2,2] row_mask:0xf bank_mask:0xf
	v_fmac_f32_dpp v118, -v156, v56 quad_perm:[3,3,3,3] row_mask:0xf bank_mask:0xf
	v_fmac_f32_dpp v119, -v157, v57 quad_perm:[3,3,3,3] row_mask:0xf bank_mask:0xf
	v_fmac_f32_dpp v116, -v158, v58 quad_perm:[0,0,0,0] row_mask:0xf bank_mask:0xf
	v_fmac_f32_dpp v117, -v159, v59 quad_perm:[0,0,0,0] row_mask:0xf bank_mask:0xf
	v_fmac_f32_dpp v118, -v158, v60 quad_perm:[1,1,1,1] row_mask:0xf bank_mask:0xf
	v_fmac_f32_dpp v119, -v159, v61 quad_perm:[1,1,1,1] row_mask:0xf bank_mask:0xf
	v_fmac_f32_dpp v116, -v158, v62 quad_perm:[2,2,2,2] row_mask:0xf bank_mask:0xf
	v_fmac_f32_dpp v117, -v159, v63 quad_perm:[2,2,2,2] row_mask:0xf bank_mask:0xf
	v_fmac_f32_dpp v118, -v158, v64 quad_perm:[3,3,3,3] row_mask:0xf bank_mask:0xf
	v_fmac_f32_dpp v119, -v159, v65 quad_perm:[3,3,3,3] row_mask:0xf bank_mask:0xf
	v_add_f32_e32 v121, v117, v116
	v_add_f32_e32 v122, v118, v119
	v_add_f32_e32 v66, v122, v121
	s_waitcnt lgkmcnt(10)
; #define GDN_LOADROW(buf, rr_, i_) do { _Pragma("unroll") for (int j4 = 0; j4 < ((i_) + 3) / 4; ++j4) buf[j4] = *(const f32x4*)(Lm + (i_) * GP_LSTR + 4 * j4); rr_ = bf2f(*(const bf16*)(xsrc + (i_) * GP_STR * 2)) * scl[i_]; } while (0)
; template <int STRIP> __device__ __forceinline__ void ph_gdn_prep_fast(const bf16* __restrict__ proj, const float* __restrict__ small, const float* __restrict__ conv_w, const float* __restrict__ a_log, const float* __restrict__ dt_bias, ...
;     ...
; #pragma unroll
;             for (int i = 0; i < 64; i += 2) {
;                 GDN_LOADROW(bB, rB, i + 1);
;                 GDN_ROW(bA, rA, i);
;                 if (i + 2 < 64) GDN_LOADROW(bA, rA, i + 2);
;                 GDN_ROW(bB, rB, i + 1);
	v_mul_f32_dpp v120, v160, v4 quad_perm:[0,0,0,0] row_mask:0xf bank_mask:0xf
	v_fma_f32 v116, v213, v253, -v120
	v_mul_f32_dpp v117, -v161, v5 quad_perm:[0,0,0,0] row_mask:0xf bank_mask:0xf
	v_mul_f32_dpp v118, -v160, v6 quad_perm:[1,1,1,1] row_mask:0xf bank_mask:0xf
	v_mul_f32_dpp v119, -v161, v12 quad_perm:[1,1,1,1] row_mask:0xf bank_mask:0xf
	ds_read_b64 v[198:199], v125 offset:16048
	v_fmac_f32_dpp v116, -v160, v7 quad_perm:[2,2,2,2] row_mask:0xf bank_mask:0xf
	v_fmac_f32_dpp v117, -v161, v13 quad_perm:[2,2,2,2] row_mask:0xf bank_mask:0xf
	v_fmac_f32_dpp v118, -v160, v14 quad_perm:[3,3,3,3] row_mask:0xf bank_mask:0xf
	ds_read_b64 v[200:201], v125 offset:16080
	v_fmac_f32_dpp v119, -v161, v15 quad_perm:[3,3,3,3] row_mask:0xf bank_mask:0xf
	v_fmac_f32_dpp v116, -v162, v16 quad_perm:[0,0,0,0] row_mask:0xf bank_mask:0xf
	v_fmac_f32_dpp v117, -v163, v17 quad_perm:[0,0,0,0] row_mask:0xf bank_mask:0xf
	ds_read_b64 v[202:203], v125 offset:16112
	v_fmac_f32_dpp v118, -v162, v19 quad_perm:[1,1,1,1] row_mask:0xf bank_mask:0xf
	v_fmac_f32_dpp v119, -v163, v20 quad_perm:[1,1,1,1] row_mask:0xf bank_mask:0xf
	v_fmac_f32_dpp v116, -v162, v21 quad_perm:[2,2,2,2] row_mask:0xf bank_mask:0xf
	ds_read_b64 v[204:205], v125 offset:16144
	v_fmac_f32_dpp v117, -v163, v22 quad_perm:[2,2,2,2] row_mask:0xf bank_mask:0xf
	v_fmac_f32_dpp v118, -v162, v23 quad_perm:[3,3,3,3] row_mask:0xf bank_mask:0xf
	v_fmac_f32_dpp v119, -v163, v24 quad_perm:[3,3,3,3] row_mask:0xf bank_mask:0xf
	ds_read_b64 v[206:207], v125 offset:16176
	v_fmac_f32_dpp v116, -v164, v25 quad_perm:[0,0,0,0] row_mask:0xf bank_mask:0xf
	v_fmac_f32_dpp v117, -v165, v27 quad_perm:[0,0,0,0] row_mask:0xf bank_mask:0xf
	v_fmac_f32_dpp v118, -v164, v28 quad_perm:[1,1,1,1] row_mask:0xf bank_mask:0xf
	ds_read_b64 v[132:133], v125 offset:16208
	v_fmac_f32_dpp v119, -v165, v29 quad_perm:[1,1,1,1] row_mask:0xf bank_mask:0xf
	v_fmac_f32_dpp v116, -v164, v30 quad_perm:[2,2,2,2] row_mask:0xf bank_mask:0xf
	v_fmac_f32_dpp v117, -v165, v31 quad_perm:[2,2,2,2] row_mask:0xf bank_mask:0xf
	ds_read_b64 v[134:135], v125 offset:16240
	v_fmac_f32_dpp v118, -v164, v32 quad_perm:[3,3,3,3] row_mask:0xf bank_mask:0xf
	v_fmac_f32_dpp v119, -v165, v33 quad_perm:[3,3,3,3] row_mask:0xf bank_mask:0xf
	v_fmac_f32_dpp v116, -v166, v34 quad_perm:[0,0,0,0] row_mask:0xf bank_mask:0xf
	ds_read_b64 v[136:137], v125 offset:16272
	v_fmac_f32_dpp v117, -v167, v35 quad_perm:[0,0,0,0] row_mask:0xf bank_mask:0xf
	v_fmac_f32_dpp v118, -v166, v36 quad_perm:[1,1,1,1] row_mask:0xf bank_mask:0xf
	v_fmac_f32_dpp v119, -v167, v37 quad_perm:[1,1,1,1] row_mask:0xf bank_mask:0xf
	ds_read_b32 v215, v124 offset:236
	v_fmac_f32_dpp v116, -v166, v38 quad_perm:[2,2,2,2] row_mask:0xf bank_mask:0xf
	v_fmac_f32_dpp v117, -v167, v39 quad_perm:[2,2,2,2] row_mask:0xf bank_mask:0xf
	v_fmac_f32_dpp v118, -v166, v40 quad_perm:[3,3,3,3] row_mask:0xf bank_mask:0xf
	ds_read_u16_d16_hi v127, v123 offset:16048
	v_fmac_f32_dpp v119, -v167, v41 quad_perm:[3,3,3,3] row_mask:0xf bank_mask:0xf
	v_fmac_f32_dpp v116, -v168, v42 quad_perm:[0,0,0,0] row_mask:0xf bank_mask:0xf
	v_fmac_f32_dpp v117, -v169, v43 quad_perm:[0,0,0,0] row_mask:0xf bank_mask:0xf
	v_fmac_f32_dpp v118, -v168, v44 quad_perm:[1,1,1,1] row_mask:0xf bank_mask:0xf
	v_fmac_f32_dpp v119, -v169, v45 quad_perm:[1,1,1,1] row_mask:0xf bank_mask:0xf
	v_fmac_f32_dpp v116, -v168, v46 quad_perm:[2,2,2,2] row_mask:0xf bank_mask:0xf
	v_fmac_f32_dpp v117, -v169, v47 quad_perm:[2,2,2,2] row_mask:0xf bank_mask:0xf
	v_fmac_f32_dpp v118, -v168, v48 quad_perm:[3,3,3,3] row_mask:0xf bank_mask:0xf
	v_fmac_f32_dpp v119, -v169, v49 quad_perm:[3,3,3,3] row_mask:0xf bank_mask:0xf
	v_fmac_f32_dpp v116, -v170, v50 quad_perm:[0,0,0,0] row_mask:0xf bank_mask:0xf
	v_fmac_f32_dpp v117, -v171, v51 quad_perm:[0,0,0,0] row_mask:0xf bank_mask:0xf
	v_fmac_f32_dpp v118, -v170, v52 quad_perm:[1,1,1,1] row_mask:0xf bank_mask:0xf
	v_fmac_f32_dpp v119, -v171, v53 quad_perm:[1,1,1,1] row_mask:0xf bank_mask:0xf
	v_fmac_f32_dpp v116, -v170, v54 quad_perm:[2,2,2,2] row_mask:0xf bank_mask:0xf
	v_fmac_f32_dpp v117, -v171, v55 quad_perm:[2,2,2,2] row_mask:0xf bank_mask:0xf
	v_fmac_f32_dpp v118, -v170, v56 quad_perm:[3,3,3,3] row_mask:0xf bank_mask:0xf
	v_fmac_f32_dpp v119, -v171, v57 quad_perm:[3,3,3,3] row_mask:0xf bank_mask:0xf
	v_fmac_f32_dpp v116, -v172, v58 quad_perm:[0,0,0,0] row_mask:0xf bank_mask:0xf
	v_fmac_f32_dpp v117, -v173, v59 quad_perm:[0,0,0,0] row_mask:0xf bank_mask:0xf
	v_fmac_f32_dpp v118, -v172, v60 quad_perm:[1,1,1,1] row_mask:0xf bank_mask:0xf
	v_fmac_f32_dpp v119, -v173, v61 quad_perm:[1,1,1,1] row_mask:0xf bank_mask:0xf
	v_fmac_f32_dpp v116, -v172, v62 quad_perm:[2,2,2,2] row_mask:0xf bank_mask:0xf
	v_fmac_f32_dpp v117, -v173, v63 quad_perm:[2,2,2,2] row_mask:0xf bank_mask:0xf
	v_fmac_f32_dpp v118, -v172, v64 quad_perm:[3,3,3,3] row_mask:0xf bank_mask:0xf
	v_fmac_f32_dpp v119, -v173, v65 quad_perm:[3,3,3,3] row_mask:0xf bank_mask:0xf
	v_fmac_f32_dpp v116, -v174, v66 quad_perm:[0,0,0,0] row_mask:0xf bank_mask:0xf
	v_add_f32_e32 v121, v117, v116
	v_add_f32_e32 v122, v118, v119
	v_add_f32_e32 v67, v122, v121
	s_waitcnt lgkmcnt(10)
; #define GDN_LOADROW(buf, rr_, i_) do { _Pragma("unroll") for (int j4 = 0; j4 < ((i_) + 3) / 4; ++j4) buf[j4] = *(const f32x4*)(Lm + (i_) * GP_LSTR + 4 * j4); rr_ = bf2f(*(const bf16*)(xsrc + (i_) * GP_STR * 2)) * scl[i_]; } while (0)
; template <int STRIP> __device__ __forceinline__ void ph_gdn_prep_fast(const bf16* __restrict__ proj, const float* __restrict__ small, const float* __restrict__ conv_w, const float* __restrict__ a_log, const float* __restrict__ dt_bias, ...
;     ...
; #pragma unroll
;             for (int i = 0; i < 64; i += 2) {
;                 GDN_LOADROW(bB, rB, i + 1);
;                 GDN_ROW(bA, rA, i);
;                 if (i + 2 < 64) GDN_LOADROW(bA, rA, i + 2);
;                 GDN_ROW(bB, rB, i + 1);
	v_mul_f32_dpp v120, v176, v4 quad_perm:[0,0,0,0] row_mask:0xf bank_mask:0xf
	v_fma_f32 v116, v214, v126, -v120
	v_mul_f32_dpp v117, -v177, v5 quad_perm:[0,0,0,0] row_mask:0xf bank_mask:0xf
	v_mul_f32_dpp v118, -v176, v6 quad_perm:[1,1,1,1] row_mask:0xf bank_mask:0xf
	v_mul_f32_dpp v119, -v177, v12 quad_perm:[1,1,1,1] row_mask:0xf bank_mask:0xf
	ds_read_b64 v[138:139], v125 offset:16320
	v_fmac_f32_dpp v116, -v176, v7 quad_perm:[2,2,2,2] row_mask:0xf bank_mask:0xf
	v_fmac_f32_dpp v117, -v177, v13 quad_perm:[2,2,2,2] row_mask:0xf bank_mask:0xf
	v_fmac_f32_dpp v118, -v176, v14 quad_perm:[3,3,3,3] row_mask:0xf bank_mask:0xf
	ds_read_b64 v[140:141], v125 offset:16352
	v_fmac_f32_dpp v119, -v177, v15 quad_perm:[3,3,3,3] row_mask:0xf bank_mask:0xf
	v_fmac_f32_dpp v116, -v178, v16 quad_perm:[0,0,0,0] row_mask:0xf bank_mask:0xf
	v_fmac_f32_dpp v117, -v179, v17 quad_perm:[0,0,0,0] row_mask:0xf bank_mask:0xf
	ds_read_b64 v[142:143], v125 offset:16384
	v_fmac_f32_dpp v118, -v178, v19 quad_perm:[1,1,1,1] row_mask:0xf bank_mask:0xf
	v_fmac_f32_dpp v119, -v179, v20 quad_perm:[1,1,1,1] row_mask:0xf bank_mask:0xf
	v_fmac_f32_dpp v116, -v178, v21 quad_perm:[2,2,2,2] row_mask:0xf bank_mask:0xf
	ds_read_b64 v[144:145], v125 offset:16416
	v_fmac_f32_dpp v117, -v179, v22 quad_perm:[2,2,2,2] row_mask:0xf bank_mask:0xf
	v_fmac_f32_dpp v118, -v178, v23 quad_perm:[3,3,3,3] row_mask:0xf bank_mask:0xf
	v_fmac_f32_dpp v119, -v179, v24 quad_perm:[3,3,3,3] row_mask:0xf bank_mask:0xf
	ds_read_b64 v[146:147], v125 offset:16448
	v_fmac_f32_dpp v116, -v186, v25 quad_perm:[0,0,0,0] row_mask:0xf bank_mask:0xf
	v_fmac_f32_dpp v117, -v187, v27 quad_perm:[0,0,0,0] row_mask:0xf bank_mask:0xf
	v_fmac_f32_dpp v118, -v186, v28 quad_perm:[1,1,1,1] row_mask:0xf bank_mask:0xf
	ds_read_b64 v[148:149], v125 offset:16480
	v_fmac_f32_dpp v119, -v187, v29 quad_perm:[1,1,1,1] row_mask:0xf bank_mask:0xf
	v_fmac_f32_dpp v116, -v186, v30 quad_perm:[2,2,2,2] row_mask:0xf bank_mask:0xf
	v_fmac_f32_dpp v117, -v187, v31 quad_perm:[2,2,2,2] row_mask:0xf bank_mask:0xf
	ds_read_b64 v[150:151], v125 offset:16512
	v_fmac_f32_dpp v118, -v186, v32 quad_perm:[3,3,3,3] row_mask:0xf bank_mask:0xf
	v_fmac_f32_dpp v119, -v187, v33 quad_perm:[3,3,3,3] row_mask:0xf bank_mask:0xf
	v_fmac_f32_dpp v116, -v188, v34 quad_perm:[0,0,0,0] row_mask:0xf bank_mask:0xf
	ds_read_b64 v[152:153], v125 offset:16544
	v_fmac_f32_dpp v117, -v189, v35 quad_perm:[0,0,0,0] row_mask:0xf bank_mask:0xf
	v_fmac_f32_dpp v118, -v188, v36 quad_perm:[1,1,1,1] row_mask:0xf bank_mask:0xf
	v_fmac_f32_dpp v119, -v189, v37 quad_perm:[1,1,1,1] row_mask:0xf bank_mask:0xf
	ds_read_b32 v216, v124 offset:240
	v_fmac_f32_dpp v116, -v188, v38 quad_perm:[2,2,2,2] row_mask:0xf bank_mask:0xf
	v_fmac_f32_dpp v117, -v189, v39 quad_perm:[2,2,2,2] row_mask:0xf bank_mask:0xf
	v_fmac_f32_dpp v118, -v188, v40 quad_perm:[3,3,3,3] row_mask:0xf bank_mask:0xf
	ds_read_u16_d16_hi v244, v123 offset:16320
	v_fmac_f32_dpp v119, -v189, v41 quad_perm:[3,3,3,3] row_mask:0xf bank_mask:0xf
	v_fmac_f32_dpp v116, -v190, v42 quad_perm:[0,0,0,0] row_mask:0xf bank_mask:0xf
	v_fmac_f32_dpp v117, -v191, v43 quad_perm:[0,0,0,0] row_mask:0xf bank_mask:0xf
	v_fmac_f32_dpp v118, -v190, v44 quad_perm:[1,1,1,1] row_mask:0xf bank_mask:0xf
	v_fmac_f32_dpp v119, -v191, v45 quad_perm:[1,1,1,1] row_mask:0xf bank_mask:0xf
	v_fmac_f32_dpp v116, -v190, v46 quad_perm:[2,2,2,2] row_mask:0xf bank_mask:0xf
	v_fmac_f32_dpp v117, -v191, v47 quad_perm:[2,2,2,2] row_mask:0xf bank_mask:0xf
	v_fmac_f32_dpp v118, -v190, v48 quad_perm:[3,3,3,3] row_mask:0xf bank_mask:0xf
	v_fmac_f32_dpp v119, -v191, v49 quad_perm:[3,3,3,3] row_mask:0xf bank_mask:0xf
	v_fmac_f32_dpp v116, -v192, v50 quad_perm:[0,0,0,0] row_mask:0xf bank_mask:0xf
	v_fmac_f32_dpp v117, -v193, v51 quad_perm:[0,0,0,0] row_mask:0xf bank_mask:0xf
	v_fmac_f32_dpp v118, -v192, v52 quad_perm:[1,1,1,1] row_mask:0xf bank_mask:0xf
	v_fmac_f32_dpp v119, -v193, v53 quad_perm:[1,1,1,1] row_mask:0xf bank_mask:0xf
	v_fmac_f32_dpp v116, -v192, v54 quad_perm:[2,2,2,2] row_mask:0xf bank_mask:0xf
	v_fmac_f32_dpp v117, -v193, v55 quad_perm:[2,2,2,2] row_mask:0xf bank_mask:0xf
	v_fmac_f32_dpp v118, -v192, v56 quad_perm:[3,3,3,3] row_mask:0xf bank_mask:0xf
	v_fmac_f32_dpp v119, -v193, v57 quad_perm:[3,3,3,3] row_mask:0xf bank_mask:0xf
	v_fmac_f32_dpp v116, -v194, v58 quad_perm:[0,0,0,0] row_mask:0xf bank_mask:0xf
	v_fmac_f32_dpp v117, -v195, v59 quad_perm:[0,0,0,0] row_mask:0xf bank_mask:0xf
	v_fmac_f32_dpp v118, -v194, v60 quad_perm:[1,1,1,1] row_mask:0xf bank_mask:0xf
	v_fmac_f32_dpp v119, -v195, v61 quad_perm:[1,1,1,1] row_mask:0xf bank_mask:0xf
	v_fmac_f32_dpp v116, -v194, v62 quad_perm:[2,2,2,2] row_mask:0xf bank_mask:0xf
	v_fmac_f32_dpp v117, -v195, v63 quad_perm:[2,2,2,2] row_mask:0xf bank_mask:0xf
	v_fmac_f32_dpp v118, -v194, v64 quad_perm:[3,3,3,3] row_mask:0xf bank_mask:0xf
	v_fmac_f32_dpp v119, -v195, v65 quad_perm:[3,3,3,3] row_mask:0xf bank_mask:0xf
	v_fmac_f32_dpp v116, -v196, v66 quad_perm:[0,0,0,0] row_mask:0xf bank_mask:0xf
	v_fmac_f32_dpp v117, -v197, v67 quad_perm:[0,0,0,0] row_mask:0xf bank_mask:0xf
	v_add_f32_e32 v121, v117, v116
	v_add_f32_e32 v122, v118, v119
	v_add_f32_e32 v68, v122, v121
	s_waitcnt lgkmcnt(10)
; #define GDN_LOADROW(buf, rr_, i_) do { _Pragma("unroll") for (int j4 = 0; j4 < ((i_) + 3) / 4; ++j4) buf[j4] = *(const f32x4*)(Lm + (i_) * GP_LSTR + 4 * j4); rr_ = bf2f(*(const bf16*)(xsrc + (i_) * GP_STR * 2)) * scl[i_]; } while (0)
; template <int STRIP> __device__ __forceinline__ void ph_gdn_prep_fast(const bf16* __restrict__ proj, const float* __restrict__ small, const float* __restrict__ conv_w, const float* __restrict__ a_log, const float* __restrict__ dt_bias, ...
;     ...
; #pragma unroll
;             for (int i = 0; i < 64; i += 2) {
;                 GDN_LOADROW(bB, rB, i + 1);
;                 GDN_ROW(bA, rA, i);
;                 if (i + 2 < 64) GDN_LOADROW(bA, rA, i + 2);
;                 GDN_ROW(bB, rB, i + 1);
	v_mul_f32_dpp v120, v198, v4 quad_perm:[0,0,0,0] row_mask:0xf bank_mask:0xf
	v_fma_f32 v116, v215, v127, -v120
	v_mul_f32_dpp v117, -v199, v5 quad_perm:[0,0,0,0] row_mask:0xf bank_mask:0xf
	v_mul_f32_dpp v118, -v198, v6 quad_perm:[1,1,1,1] row_mask:0xf bank_mask:0xf
	v_mul_f32_dpp v119, -v199, v12 quad_perm:[1,1,1,1] row_mask:0xf bank_mask:0xf
	ds_read_b64 v[154:155], v125 offset:16592
	v_fmac_f32_dpp v116, -v198, v7 quad_perm:[2,2,2,2] row_mask:0xf bank_mask:0xf
	v_fmac_f32_dpp v117, -v199, v13 quad_perm:[2,2,2,2] row_mask:0xf bank_mask:0xf
	v_fmac_f32_dpp v118, -v198, v14 quad_perm:[3,3,3,3] row_mask:0xf bank_mask:0xf
	ds_read_b64 v[156:157], v125 offset:16624
	v_fmac_f32_dpp v119, -v199, v15 quad_perm:[3,3,3,3] row_mask:0xf bank_mask:0xf
	v_fmac_f32_dpp v116, -v200, v16 quad_perm:[0,0,0,0] row_mask:0xf bank_mask:0xf
	v_fmac_f32_dpp v117, -v201, v17 quad_perm:[0,0,0,0] row_mask:0xf bank_mask:0xf
	ds_read_b64 v[158:159], v125 offset:16656
	v_fmac_f32_dpp v118, -v200, v19 quad_perm:[1,1,1,1] row_mask:0xf bank_mask:0xf
	v_fmac_f32_dpp v119, -v201, v20 quad_perm:[1,1,1,1] row_mask:0xf bank_mask:0xf
	v_fmac_f32_dpp v116, -v200, v21 quad_perm:[2,2,2,2] row_mask:0xf bank_mask:0xf
	ds_read_b64 v[160:161], v125 offset:16688
	v_fmac_f32_dpp v117, -v201, v22 quad_perm:[2,2,2,2] row_mask:0xf bank_mask:0xf
	v_fmac_f32_dpp v118, -v200, v23 quad_perm:[3,3,3,3] row_mask:0xf bank_mask:0xf
	v_fmac_f32_dpp v119, -v201, v24 quad_perm:[3,3,3,3] row_mask:0xf bank_mask:0xf
	ds_read_b64 v[162:163], v125 offset:16720
	v_fmac_f32_dpp v116, -v202, v25 quad_perm:[0,0,0,0] row_mask:0xf bank_mask:0xf
	v_fmac_f32_dpp v117, -v203, v27 quad_perm:[0,0,0,0] row_mask:0xf bank_mask:0xf
	v_fmac_f32_dpp v118, -v202, v28 quad_perm:[1,1,1,1] row_mask:0xf bank_mask:0xf
	ds_read_b64 v[164:165], v125 offset:16752
	v_fmac_f32_dpp v119, -v203, v29 quad_perm:[1,1,1,1] row_mask:0xf bank_mask:0xf
	v_fmac_f32_dpp v116, -v202, v30 quad_perm:[2,2,2,2] row_mask:0xf bank_mask:0xf
	v_fmac_f32_dpp v117, -v203, v31 quad_perm:[2,2,2,2] row_mask:0xf bank_mask:0xf
	ds_read_b64 v[166:167], v125 offset:16784
	v_fmac_f32_dpp v118, -v202, v32 quad_perm:[3,3,3,3] row_mask:0xf bank_mask:0xf
	v_fmac_f32_dpp v119, -v203, v33 quad_perm:[3,3,3,3] row_mask:0xf bank_mask:0xf
	v_fmac_f32_dpp v116, -v204, v34 quad_perm:[0,0,0,0] row_mask:0xf bank_mask:0xf
	ds_read_b64 v[168:169], v125 offset:16816
	v_fmac_f32_dpp v117, -v205, v35 quad_perm:[0,0,0,0] row_mask:0xf bank_mask:0xf
	v_fmac_f32_dpp v118, -v204, v36 quad_perm:[1,1,1,1] row_mask:0xf bank_mask:0xf
	v_fmac_f32_dpp v119, -v205, v37 quad_perm:[1,1,1,1] row_mask:0xf bank_mask:0xf
	ds_read_b32 v217, v124 offset:244
	v_fmac_f32_dpp v116, -v204, v38 quad_perm:[2,2,2,2] row_mask:0xf bank_mask:0xf
	v_fmac_f32_dpp v117, -v205, v39 quad_perm:[2,2,2,2] row_mask:0xf bank_mask:0xf
	v_fmac_f32_dpp v118, -v204, v40 quad_perm:[3,3,3,3] row_mask:0xf bank_mask:0xf
	ds_read_u16_d16_hi v245, v123 offset:16592
	v_fmac_f32_dpp v119, -v205, v41 quad_perm:[3,3,3,3] row_mask:0xf bank_mask:0xf
	v_fmac_f32_dpp v116, -v206, v42 quad_perm:[0,0,0,0] row_mask:0xf bank_mask:0xf
	v_fmac_f32_dpp v117, -v207, v43 quad_perm:[0,0,0,0] row_mask:0xf bank_mask:0xf
	v_fmac_f32_dpp v118, -v206, v44 quad_perm:[1,1,1,1] row_mask:0xf bank_mask:0xf
	v_fmac_f32_dpp v119, -v207, v45 quad_perm:[1,1,1,1] row_mask:0xf bank_mask:0xf
	v_fmac_f32_dpp v116, -v206, v46 quad_perm:[2,2,2,2] row_mask:0xf bank_mask:0xf
	v_fmac_f32_dpp v117, -v207, v47 quad_perm:[2,2,2,2] row_mask:0xf bank_mask:0xf
	v_fmac_f32_dpp v118, -v206, v48 quad_perm:[3,3,3,3] row_mask:0xf bank_mask:0xf
	v_fmac_f32_dpp v119, -v207, v49 quad_perm:[3,3,3,3] row_mask:0xf bank_mask:0xf
	v_fmac_f32_dpp v116, -v132, v50 quad_perm:[0,0,0,0] row_mask:0xf bank_mask:0xf
	v_fmac_f32_dpp v117, -v133, v51 quad_perm:[0,0,0,0] row_mask:0xf bank_mask:0xf
	v_fmac_f32_dpp v118, -v132, v52 quad_perm:[1,1,1,1] row_mask:0xf bank_mask:0xf
	v_fmac_f32_dpp v119, -v133, v53 quad_perm:[1,1,1,1] row_mask:0xf bank_mask:0xf
	v_fmac_f32_dpp v116, -v132, v54 quad_perm:[2,2,2,2] row_mask:0xf bank_mask:0xf
	v_fmac_f32_dpp v117, -v133, v55 quad_perm:[2,2,2,2] row_mask:0xf bank_mask:0xf
	v_fmac_f32_dpp v118, -v132, v56 quad_perm:[3,3,3,3] row_mask:0xf bank_mask:0xf
	v_fmac_f32_dpp v119, -v133, v57 quad_perm:[3,3,3,3] row_mask:0xf bank_mask:0xf
	v_fmac_f32_dpp v116, -v134, v58 quad_perm:[0,0,0,0] row_mask:0xf bank_mask:0xf
	v_fmac_f32_dpp v117, -v135, v59 quad_perm:[0,0,0,0] row_mask:0xf bank_mask:0xf
	v_fmac_f32_dpp v118, -v134, v60 quad_perm:[1,1,1,1] row_mask:0xf bank_mask:0xf
	v_fmac_f32_dpp v119, -v135, v61 quad_perm:[1,1,1,1] row_mask:0xf bank_mask:0xf
	v_fmac_f32_dpp v116, -v134, v62 quad_perm:[2,2,2,2] row_mask:0xf bank_mask:0xf
	v_fmac_f32_dpp v117, -v135, v63 quad_perm:[2,2,2,2] row_mask:0xf bank_mask:0xf
	v_fmac_f32_dpp v118, -v134, v64 quad_perm:[3,3,3,3] row_mask:0xf bank_mask:0xf
	v_fmac_f32_dpp v119, -v135, v65 quad_perm:[3,3,3,3] row_mask:0xf bank_mask:0xf
	v_fmac_f32_dpp v116, -v136, v66 quad_perm:[0,0,0,0] row_mask:0xf bank_mask:0xf
	v_fmac_f32_dpp v117, -v137, v67 quad_perm:[0,0,0,0] row_mask:0xf bank_mask:0xf
	v_fmac_f32_dpp v118, -v136, v68 quad_perm:[1,1,1,1] row_mask:0xf bank_mask:0xf
	v_add_f32_e32 v121, v117, v116
	v_add_f32_e32 v122, v118, v119
	v_add_f32_e32 v69, v122, v121
	s_waitcnt lgkmcnt(10)
; #define GDN_LOADROW(buf, rr_, i_) do { _Pragma("unroll") for (int j4 = 0; j4 < ((i_) + 3) / 4; ++j4) buf[j4] = *(const f32x4*)(Lm + (i_) * GP_LSTR + 4 * j4); rr_ = bf2f(*(const bf16*)(xsrc + (i_) * GP_STR * 2)) * scl[i_]; } while (0)
; template <int STRIP> __device__ __forceinline__ void ph_gdn_prep_fast(const bf16* __restrict__ proj, const float* __restrict__ small, const float* __restrict__ conv_w, const float* __restrict__ a_log, const float* __restrict__ dt_bias, ...
;     ...
; #pragma unroll
;             for (int i = 0; i < 64; i += 2) {
;                 GDN_LOADROW(bB, rB, i + 1);
;                 GDN_ROW(bA, rA, i);
;                 if (i + 2 < 64) GDN_LOADROW(bA, rA, i + 2);
;                 GDN_ROW(bB, rB, i + 1);
	v_mul_f32_dpp v120, v138, v4 quad_perm:[0,0,0,0] row_mask:0xf bank_mask:0xf
	v_fma_f32 v116, v216, v244, -v120
	v_mul_f32_dpp v117, -v139, v5 quad_perm:[0,0,0,0] row_mask:0xf bank_mask:0xf
	v_mul_f32_dpp v118, -v138, v6 quad_perm:[1,1,1,1] row_mask:0xf bank_mask:0xf
	v_mul_f32_dpp v119, -v139, v12 quad_perm:[1,1,1,1] row_mask:0xf bank_mask:0xf
	ds_read_b64 v[170:171], v125 offset:16864
	v_fmac_f32_dpp v116, -v138, v7 quad_perm:[2,2,2,2] row_mask:0xf bank_mask:0xf
	v_fmac_f32_dpp v117, -v139, v13 quad_perm:[2,2,2,2] row_mask:0xf bank_mask:0xf
	v_fmac_f32_dpp v118, -v138, v14 quad_perm:[3,3,3,3] row_mask:0xf bank_mask:0xf
	ds_read_b64 v[172:173], v125 offset:16896
	v_fmac_f32_dpp v119, -v139, v15 quad_perm:[3,3,3,3] row_mask:0xf bank_mask:0xf
	v_fmac_f32_dpp v116, -v140, v16 quad_perm:[0,0,0,0] row_mask:0xf bank_mask:0xf
	v_fmac_f32_dpp v117, -v141, v17 quad_perm:[0,0,0,0] row_mask:0xf bank_mask:0xf
	ds_read_b64 v[174:175], v125 offset:16928
	v_fmac_f32_dpp v118, -v140, v19 quad_perm:[1,1,1,1] row_mask:0xf bank_mask:0xf
	v_fmac_f32_dpp v119, -v141, v20 quad_perm:[1,1,1,1] row_mask:0xf bank_mask:0xf
	v_fmac_f32_dpp v116, -v140, v21 quad_perm:[2,2,2,2] row_mask:0xf bank_mask:0xf
	ds_read_b64 v[176:177], v125 offset:16960
	v_fmac_f32_dpp v117, -v141, v22 quad_perm:[2,2,2,2] row_mask:0xf bank_mask:0xf
	v_fmac_f32_dpp v118, -v140, v23 quad_perm:[3,3,3,3] row_mask:0xf bank_mask:0xf
	v_fmac_f32_dpp v119, -v141, v24 quad_perm:[3,3,3,3] row_mask:0xf bank_mask:0xf
	ds_read_b64 v[178:179], v125 offset:16992
	v_fmac_f32_dpp v116, -v142, v25 quad_perm:[0,0,0,0] row_mask:0xf bank_mask:0xf
	v_fmac_f32_dpp v117, -v143, v27 quad_perm:[0,0,0,0] row_mask:0xf bank_mask:0xf
	v_fmac_f32_dpp v118, -v142, v28 quad_perm:[1,1,1,1] row_mask:0xf bank_mask:0xf
	ds_read_b64 v[186:187], v125 offset:17024
	v_fmac_f32_dpp v119, -v143, v29 quad_perm:[1,1,1,1] row_mask:0xf bank_mask:0xf
	v_fmac_f32_dpp v116, -v142, v30 quad_perm:[2,2,2,2] row_mask:0xf bank_mask:0xf
	v_fmac_f32_dpp v117, -v143, v31 quad_perm:[2,2,2,2] row_mask:0xf bank_mask:0xf
	ds_read_b64 v[188:189], v125 offset:17056
	v_fmac_f32_dpp v118, -v142, v32 quad_perm:[3,3,3,3] row_mask:0xf bank_mask:0xf
	v_fmac_f32_dpp v119, -v143, v33 quad_perm:[3,3,3,3] row_mask:0xf bank_mask:0xf
	v_fmac_f32_dpp v116, -v144, v34 quad_perm:[0,0,0,0] row_mask:0xf bank_mask:0xf
	ds_read_b64 v[190:191], v125 offset:17088
	v_fmac_f32_dpp v117, -v145, v35 quad_perm:[0,0,0,0] row_mask:0xf bank_mask:0xf
	v_fmac_f32_dpp v118, -v144, v36 quad_perm:[1,1,1,1] row_mask:0xf bank_mask:0xf
	v_fmac_f32_dpp v119, -v145, v37 quad_perm:[1,1,1,1] row_mask:0xf bank_mask:0xf
	ds_read_b32 v218, v124 offset:248
	v_fmac_f32_dpp v116, -v144, v38 quad_perm:[2,2,2,2] row_mask:0xf bank_mask:0xf
	v_fmac_f32_dpp v117, -v145, v39 quad_perm:[2,2,2,2] row_mask:0xf bank_mask:0xf
	v_fmac_f32_dpp v118, -v144, v40 quad_perm:[3,3,3,3] row_mask:0xf bank_mask:0xf
	ds_read_u16_d16_hi v246, v123 offset:16864
	v_fmac_f32_dpp v119, -v145, v41 quad_perm:[3,3,3,3] row_mask:0xf bank_mask:0xf
	v_fmac_f32_dpp v116, -v146, v42 quad_perm:[0,0,0,0] row_mask:0xf bank_mask:0xf
	v_fmac_f32_dpp v117, -v147, v43 quad_perm:[0,0,0,0] row_mask:0xf bank_mask:0xf
	v_fmac_f32_dpp v118, -v146, v44 quad_perm:[1,1,1,1] row_mask:0xf bank_mask:0xf
	v_fmac_f32_dpp v119, -v147, v45 quad_perm:[1,1,1,1] row_mask:0xf bank_mask:0xf
	v_fmac_f32_dpp v116, -v146, v46 quad_perm:[2,2,2,2] row_mask:0xf bank_mask:0xf
	v_fmac_f32_dpp v117, -v147, v47 quad_perm:[2,2,2,2] row_mask:0xf bank_mask:0xf
	v_fmac_f32_dpp v118, -v146, v48 quad_perm:[3,3,3,3] row_mask:0xf bank_mask:0xf
	v_fmac_f32_dpp v119, -v147, v49 quad_perm:[3,3,3,3] row_mask:0xf bank_mask:0xf
	v_fmac_f32_dpp v116, -v148, v50 quad_perm:[0,0,0,0] row_mask:0xf bank_mask:0xf
	v_fmac_f32_dpp v117, -v149, v51 quad_perm:[0,0,0,0] row_mask:0xf bank_mask:0xf
	v_fmac_f32_dpp v118, -v148, v52 quad_perm:[1,1,1,1] row_mask:0xf bank_mask:0xf
	v_fmac_f32_dpp v119, -v149, v53 quad_perm:[1,1,1,1] row_mask:0xf bank_mask:0xf
	v_fmac_f32_dpp v116, -v148, v54 quad_perm:[2,2,2,2] row_mask:0xf bank_mask:0xf
	v_fmac_f32_dpp v117, -v149, v55 quad_perm:[2,2,2,2] row_mask:0xf bank_mask:0xf
	v_fmac_f32_dpp v118, -v148, v56 quad_perm:[3,3,3,3] row_mask:0xf bank_mask:0xf
	v_fmac_f32_dpp v119, -v149, v57 quad_perm:[3,3,3,3] row_mask:0xf bank_mask:0xf
	v_fmac_f32_dpp v116, -v150, v58 quad_perm:[0,0,0,0] row_mask:0xf bank_mask:0xf
	v_fmac_f32_dpp v117, -v151, v59 quad_perm:[0,0,0,0] row_mask:0xf bank_mask:0xf
	v_fmac_f32_dpp v118, -v150, v60 quad_perm:[1,1,1,1] row_mask:0xf bank_mask:0xf
	v_fmac_f32_dpp v119, -v151, v61 quad_perm:[1,1,1,1] row_mask:0xf bank_mask:0xf
	v_fmac_f32_dpp v116, -v150, v62 quad_perm:[2,2,2,2] row_mask:0xf bank_mask:0xf
	v_fmac_f32_dpp v117, -v151, v63 quad_perm:[2,2,2,2] row_mask:0xf bank_mask:0xf
	v_fmac_f32_dpp v118, -v150, v64 quad_perm:[3,3,3,3] row_mask:0xf bank_mask:0xf
	v_fmac_f32_dpp v119, -v151, v65 quad_perm:[3,3,3,3] row_mask:0xf bank_mask:0xf
	v_fmac_f32_dpp v116, -v152, v66 quad_perm:[0,0,0,0] row_mask:0xf bank_mask:0xf
	v_fmac_f32_dpp v117, -v153, v67 quad_perm:[0,0,0,0] row_mask:0xf bank_mask:0xf
	v_fmac_f32_dpp v118, -v152, v68 quad_perm:[1,1,1,1] row_mask:0xf bank_mask:0xf
	v_fmac_f32_dpp v119, -v153, v69 quad_perm:[1,1,1,1] row_mask:0xf bank_mask:0xf
	v_add_f32_e32 v121, v117, v116
	v_add_f32_e32 v122, v118, v119
	v_add_f32_e32 v70, v122, v121
	s_waitcnt lgkmcnt(10)
; __device__ __forceinline__ float bf2f(bf16 v) { return __uint_as_float(((unsigned)v) << 16); }
; #define GDN_LOADROW(buf, rr_, i_) do { _Pragma("unroll") for (int j4 = 0; j4 < ((i_) + 3) / 4; ++j4) buf[j4] = *(const f32x4*)(Lm + (i_) * GP_LSTR + 4 * j4); rr_ = bf2f(*(const bf16*)(xsrc + (i_) * GP_STR * 2)) * scl[i_]; } while (0)
; template <int STRIP> __device__ __forceinline__ void ph_gdn_prep_fast(const bf16* __restrict__ proj, const float* __restrict__ small, const float* __restrict__ conv_w, const float* __restrict__ a_log, const float* __restrict__ dt_bias, ...
;     ...
;             f32x4 bA[16], bB[16]; float rA, rB = 0.f;
;             rA = bf2f(*(const bf16*)xsrc) * scl[0];
;     ...
; #pragma unroll
;             for (int i = 0; i < 64; i += 2) {
;                 GDN_LOADROW(bB, rB, i + 1);
;                 GDN_ROW(bA, rA, i);
;                 if (i + 2 < 64) GDN_LOADROW(bA, rA, i + 2);
;                 GDN_ROW(bB, rB, i + 1);
;             }
	v_mul_f32_dpp v120, v154, v4 quad_perm:[0,0,0,0] row_mask:0xf bank_mask:0xf
	v_fma_f32 v116, v217, v245, -v120
	v_mul_f32_dpp v117, -v155, v5 quad_perm:[0,0,0,0] row_mask:0xf bank_mask:0xf
	v_mul_f32_dpp v118, -v154, v6 quad_perm:[1,1,1,1] row_mask:0xf bank_mask:0xf
	v_mul_f32_dpp v119, -v155, v12 quad_perm:[1,1,1,1] row_mask:0xf bank_mask:0xf
	ds_read_b64 v[192:193], v125 offset:17136
	v_fmac_f32_dpp v116, -v154, v7 quad_perm:[2,2,2,2] row_mask:0xf bank_mask:0xf
	v_fmac_f32_dpp v117, -v155, v13 quad_perm:[2,2,2,2] row_mask:0xf bank_mask:0xf
	v_fmac_f32_dpp v118, -v154, v14 quad_perm:[3,3,3,3] row_mask:0xf bank_mask:0xf
	ds_read_b64 v[194:195], v125 offset:17168
	v_fmac_f32_dpp v119, -v155, v15 quad_perm:[3,3,3,3] row_mask:0xf bank_mask:0xf
	v_fmac_f32_dpp v116, -v156, v16 quad_perm:[0,0,0,0] row_mask:0xf bank_mask:0xf
	v_fmac_f32_dpp v117, -v157, v17 quad_perm:[0,0,0,0] row_mask:0xf bank_mask:0xf
	ds_read_b64 v[196:197], v125 offset:17200
	v_fmac_f32_dpp v118, -v156, v19 quad_perm:[1,1,1,1] row_mask:0xf bank_mask:0xf
	v_fmac_f32_dpp v119, -v157, v20 quad_perm:[1,1,1,1] row_mask:0xf bank_mask:0xf
	v_fmac_f32_dpp v116, -v156, v21 quad_perm:[2,2,2,2] row_mask:0xf bank_mask:0xf
	ds_read_b64 v[198:199], v125 offset:17232
	v_fmac_f32_dpp v117, -v157, v22 quad_perm:[2,2,2,2] row_mask:0xf bank_mask:0xf
	v_fmac_f32_dpp v118, -v156, v23 quad_perm:[3,3,3,3] row_mask:0xf bank_mask:0xf
	v_fmac_f32_dpp v119, -v157, v24 quad_perm:[3,3,3,3] row_mask:0xf bank_mask:0xf
	ds_read_b64 v[200:201], v125 offset:17264
	v_fmac_f32_dpp v116, -v158, v25 quad_perm:[0,0,0,0] row_mask:0xf bank_mask:0xf
	v_fmac_f32_dpp v117, -v159, v27 quad_perm:[0,0,0,0] row_mask:0xf bank_mask:0xf
	v_fmac_f32_dpp v118, -v158, v28 quad_perm:[1,1,1,1] row_mask:0xf bank_mask:0xf
	ds_read_b64 v[202:203], v125 offset:17296
	v_fmac_f32_dpp v119, -v159, v29 quad_perm:[1,1,1,1] row_mask:0xf bank_mask:0xf
	v_fmac_f32_dpp v116, -v158, v30 quad_perm:[2,2,2,2] row_mask:0xf bank_mask:0xf
	v_fmac_f32_dpp v117, -v159, v31 quad_perm:[2,2,2,2] row_mask:0xf bank_mask:0xf
	ds_read_b64 v[204:205], v125 offset:17328
	v_fmac_f32_dpp v118, -v158, v32 quad_perm:[3,3,3,3] row_mask:0xf bank_mask:0xf
	v_fmac_f32_dpp v119, -v159, v33 quad_perm:[3,3,3,3] row_mask:0xf bank_mask:0xf
	v_fmac_f32_dpp v116, -v160, v34 quad_perm:[0,0,0,0] row_mask:0xf bank_mask:0xf
	ds_read_b64 v[206:207], v125 offset:17360
	v_fmac_f32_dpp v117, -v161, v35 quad_perm:[0,0,0,0] row_mask:0xf bank_mask:0xf
	v_fmac_f32_dpp v118, -v160, v36 quad_perm:[1,1,1,1] row_mask:0xf bank_mask:0xf
	v_fmac_f32_dpp v119, -v161, v37 quad_perm:[1,1,1,1] row_mask:0xf bank_mask:0xf
	ds_read_b32 v219, v124 offset:252
	v_fmac_f32_dpp v116, -v160, v38 quad_perm:[2,2,2,2] row_mask:0xf bank_mask:0xf
	v_fmac_f32_dpp v117, -v161, v39 quad_perm:[2,2,2,2] row_mask:0xf bank_mask:0xf
	v_fmac_f32_dpp v118, -v160, v40 quad_perm:[3,3,3,3] row_mask:0xf bank_mask:0xf
	ds_read_u16_d16_hi v247, v123 offset:17136
	v_fmac_f32_dpp v119, -v161, v41 quad_perm:[3,3,3,3] row_mask:0xf bank_mask:0xf
	v_fmac_f32_dpp v116, -v162, v42 quad_perm:[0,0,0,0] row_mask:0xf bank_mask:0xf
	v_fmac_f32_dpp v117, -v163, v43 quad_perm:[0,0,0,0] row_mask:0xf bank_mask:0xf
	v_fmac_f32_dpp v118, -v162, v44 quad_perm:[1,1,1,1] row_mask:0xf bank_mask:0xf
	v_fmac_f32_dpp v119, -v163, v45 quad_perm:[1,1,1,1] row_mask:0xf bank_mask:0xf
	v_fmac_f32_dpp v116, -v162, v46 quad_perm:[2,2,2,2] row_mask:0xf bank_mask:0xf
	v_fmac_f32_dpp v117, -v163, v47 quad_perm:[2,2,2,2] row_mask:0xf bank_mask:0xf
	v_fmac_f32_dpp v118, -v162, v48 quad_perm:[3,3,3,3] row_mask:0xf bank_mask:0xf
	v_fmac_f32_dpp v119, -v163, v49 quad_perm:[3,3,3,3] row_mask:0xf bank_mask:0xf
	v_fmac_f32_dpp v116, -v164, v50 quad_perm:[0,0,0,0] row_mask:0xf bank_mask:0xf
	v_fmac_f32_dpp v117, -v165, v51 quad_perm:[0,0,0,0] row_mask:0xf bank_mask:0xf
	v_fmac_f32_dpp v118, -v164, v52 quad_perm:[1,1,1,1] row_mask:0xf bank_mask:0xf
	v_fmac_f32_dpp v119, -v165, v53 quad_perm:[1,1,1,1] row_mask:0xf bank_mask:0xf
	v_fmac_f32_dpp v116, -v164, v54 quad_perm:[2,2,2,2] row_mask:0xf bank_mask:0xf
	v_fmac_f32_dpp v117, -v165, v55 quad_perm:[2,2,2,2] row_mask:0xf bank_mask:0xf
	v_fmac_f32_dpp v118, -v164, v56 quad_perm:[3,3,3,3] row_mask:0xf bank_mask:0xf
	v_fmac_f32_dpp v119, -v165, v57 quad_perm:[3,3,3,3] row_mask:0xf bank_mask:0xf
	v_fmac_f32_dpp v116, -v166, v58 quad_perm:[0,0,0,0] row_mask:0xf bank_mask:0xf
	v_fmac_f32_dpp v117, -v167, v59 quad_perm:[0,0,0,0] row_mask:0xf bank_mask:0xf
	v_fmac_f32_dpp v118, -v166, v60 quad_perm:[1,1,1,1] row_mask:0xf bank_mask:0xf
	v_fmac_f32_dpp v119, -v167, v61 quad_perm:[1,1,1,1] row_mask:0xf bank_mask:0xf
	v_fmac_f32_dpp v116, -v166, v62 quad_perm:[2,2,2,2] row_mask:0xf bank_mask:0xf
	v_fmac_f32_dpp v117, -v167, v63 quad_perm:[2,2,2,2] row_mask:0xf bank_mask:0xf
	v_fmac_f32_dpp v118, -v166, v64 quad_perm:[3,3,3,3] row_mask:0xf bank_mask:0xf
	v_fmac_f32_dpp v119, -v167, v65 quad_perm:[3,3,3,3] row_mask:0xf bank_mask:0xf
	v_fmac_f32_dpp v116, -v168, v66 quad_perm:[0,0,0,0] row_mask:0xf bank_mask:0xf
	v_fmac_f32_dpp v117, -v169, v67 quad_perm:[0,0,0,0] row_mask:0xf bank_mask:0xf
	v_fmac_f32_dpp v118, -v168, v68 quad_perm:[1,1,1,1] row_mask:0xf bank_mask:0xf
	v_fmac_f32_dpp v119, -v169, v69 quad_perm:[1,1,1,1] row_mask:0xf bank_mask:0xf
	v_fmac_f32_dpp v116, -v168, v70 quad_perm:[2,2,2,2] row_mask:0xf bank_mask:0xf
	v_add_f32_e32 v121, v117, v116
	v_add_f32_e32 v122, v118, v119
	v_add_f32_e32 v71, v122, v121
	s_waitcnt lgkmcnt(10)
; __device__ __forceinline__ float bf2f(bf16 v) { return __uint_as_float(((unsigned)v) << 16); }
; #define GDN_LOADROW(buf, rr_, i_) do { _Pragma("unroll") for (int j4 = 0; j4 < ((i_) + 3) / 4; ++j4) buf[j4] = *(const f32x4*)(Lm + (i_) * GP_LSTR + 4 * j4); rr_ = bf2f(*(const bf16*)(xsrc + (i_) * GP_STR * 2)) * scl[i_]; } while (0)
; template <int STRIP> __device__ __forceinline__ void ph_gdn_prep_fast(const bf16* __restrict__ proj, const float* __restrict__ small, const float* __restrict__ conv_w, const float* __restrict__ a_log, const float* __restrict__ dt_bias, ...
;     ...
;             f32x4 bA[16], bB[16]; float rA, rB = 0.f;
;             rA = bf2f(*(const bf16*)xsrc) * scl[0];
;     ...
; #pragma unroll
;             for (int i = 0; i < 64; i += 2) {
;                 GDN_LOADROW(bB, rB, i + 1);
;                 GDN_ROW(bA, rA, i);
;                 if (i + 2 < 64) GDN_LOADROW(bA, rA, i + 2);
;                 GDN_ROW(bB, rB, i + 1);
;             }
	v_mul_f32_dpp v120, v170, v4 quad_perm:[0,0,0,0] row_mask:0xf bank_mask:0xf
	v_fma_f32 v116, v218, v246, -v120
	v_mul_f32_dpp v117, -v171, v5 quad_perm:[0,0,0,0] row_mask:0xf bank_mask:0xf
	v_mul_f32_dpp v118, -v170, v6 quad_perm:[1,1,1,1] row_mask:0xf bank_mask:0xf
	v_mul_f32_dpp v119, -v171, v12 quad_perm:[1,1,1,1] row_mask:0xf bank_mask:0xf
	v_fmac_f32_dpp v116, -v170, v7 quad_perm:[2,2,2,2] row_mask:0xf bank_mask:0xf
	v_fmac_f32_dpp v117, -v171, v13 quad_perm:[2,2,2,2] row_mask:0xf bank_mask:0xf
	v_fmac_f32_dpp v118, -v170, v14 quad_perm:[3,3,3,3] row_mask:0xf bank_mask:0xf
	v_fmac_f32_dpp v119, -v171, v15 quad_perm:[3,3,3,3] row_mask:0xf bank_mask:0xf
	v_fmac_f32_dpp v116, -v172, v16 quad_perm:[0,0,0,0] row_mask:0xf bank_mask:0xf
	v_fmac_f32_dpp v117, -v173, v17 quad_perm:[0,0,0,0] row_mask:0xf bank_mask:0xf
	v_fmac_f32_dpp v118, -v172, v19 quad_perm:[1,1,1,1] row_mask:0xf bank_mask:0xf
	v_fmac_f32_dpp v119, -v173, v20 quad_perm:[1,1,1,1] row_mask:0xf bank_mask:0xf
	v_fmac_f32_dpp v116, -v172, v21 quad_perm:[2,2,2,2] row_mask:0xf bank_mask:0xf
	v_fmac_f32_dpp v117, -v173, v22 quad_perm:[2,2,2,2] row_mask:0xf bank_mask:0xf
	v_fmac_f32_dpp v118, -v172, v23 quad_perm:[3,3,3,3] row_mask:0xf bank_mask:0xf
	v_fmac_f32_dpp v119, -v173, v24 quad_perm:[3,3,3,3] row_mask:0xf bank_mask:0xf
	v_fmac_f32_dpp v116, -v174, v25 quad_perm:[0,0,0,0] row_mask:0xf bank_mask:0xf
	v_fmac_f32_dpp v117, -v175, v27 quad_perm:[0,0,0,0] row_mask:0xf bank_mask:0xf
	v_fmac_f32_dpp v118, -v174, v28 quad_perm:[1,1,1,1] row_mask:0xf bank_mask:0xf
	v_fmac_f32_dpp v119, -v175, v29 quad_perm:[1,1,1,1] row_mask:0xf bank_mask:0xf
	v_fmac_f32_dpp v116, -v174, v30 quad_perm:[2,2,2,2] row_mask:0xf bank_mask:0xf
	v_fmac_f32_dpp v117, -v175, v31 quad_perm:[2,2,2,2] row_mask:0xf bank_mask:0xf
	v_fmac_f32_dpp v118, -v174, v32 quad_perm:[3,3,3,3] row_mask:0xf bank_mask:0xf
	v_fmac_f32_dpp v119, -v175, v33 quad_perm:[3,3,3,3] row_mask:0xf bank_mask:0xf
	v_fmac_f32_dpp v116, -v176, v34 quad_perm:[0,0,0,0] row_mask:0xf bank_mask:0xf
	v_fmac_f32_dpp v117, -v177, v35 quad_perm:[0,0,0,0] row_mask:0xf bank_mask:0xf
	v_fmac_f32_dpp v118, -v176, v36 quad_perm:[1,1,1,1] row_mask:0xf bank_mask:0xf
	v_fmac_f32_dpp v119, -v177, v37 quad_perm:[1,1,1,1] row_mask:0xf bank_mask:0xf
	v_fmac_f32_dpp v116, -v176, v38 quad_perm:[2,2,2,2] row_mask:0xf bank_mask:0xf
	v_fmac_f32_dpp v117, -v177, v39 quad_perm:[2,2,2,2] row_mask:0xf bank_mask:0xf
	v_fmac_f32_dpp v118, -v176, v40 quad_perm:[3,3,3,3] row_mask:0xf bank_mask:0xf
	v_fmac_f32_dpp v119, -v177, v41 quad_perm:[3,3,3,3] row_mask:0xf bank_mask:0xf
	v_fmac_f32_dpp v116, -v178, v42 quad_perm:[0,0,0,0] row_mask:0xf bank_mask:0xf
	v_fmac_f32_dpp v117, -v179, v43 quad_perm:[0,0,0,0] row_mask:0xf bank_mask:0xf
	v_fmac_f32_dpp v118, -v178, v44 quad_perm:[1,1,1,1] row_mask:0xf bank_mask:0xf
	v_fmac_f32_dpp v119, -v179, v45 quad_perm:[1,1,1,1] row_mask:0xf bank_mask:0xf
	v_fmac_f32_dpp v116, -v178, v46 quad_perm:[2,2,2,2] row_mask:0xf bank_mask:0xf
	v_fmac_f32_dpp v117, -v179, v47 quad_perm:[2,2,2,2] row_mask:0xf bank_mask:0xf
	v_fmac_f32_dpp v118, -v178, v48 quad_perm:[3,3,3,3] row_mask:0xf bank_mask:0xf
	v_fmac_f32_dpp v119, -v179, v49 quad_perm:[3,3,3,3] row_mask:0xf bank_mask:0xf
	v_fmac_f32_dpp v116, -v186, v50 quad_perm:[0,0,0,0] row_mask:0xf bank_mask:0xf
	v_fmac_f32_dpp v117, -v187, v51 quad_perm:[0,0,0,0] row_mask:0xf bank_mask:0xf
	v_fmac_f32_dpp v118, -v186, v52 quad_perm:[1,1,1,1] row_mask:0xf bank_mask:0xf
	v_fmac_f32_dpp v119, -v187, v53 quad_perm:[1,1,1,1] row_mask:0xf bank_mask:0xf
	v_fmac_f32_dpp v116, -v186, v54 quad_perm:[2,2,2,2] row_mask:0xf bank_mask:0xf
	v_fmac_f32_dpp v117, -v187, v55 quad_perm:[2,2,2,2] row_mask:0xf bank_mask:0xf
	v_fmac_f32_dpp v118, -v186, v56 quad_perm:[3,3,3,3] row_mask:0xf bank_mask:0xf
	v_fmac_f32_dpp v119, -v187, v57 quad_perm:[3,3,3,3] row_mask:0xf bank_mask:0xf
	v_fmac_f32_dpp v116, -v188, v58 quad_perm:[0,0,0,0] row_mask:0xf bank_mask:0xf
	v_fmac_f32_dpp v117, -v189, v59 quad_perm:[0,0,0,0] row_mask:0xf bank_mask:0xf
	v_fmac_f32_dpp v118, -v188, v60 quad_perm:[1,1,1,1] row_mask:0xf bank_mask:0xf
	v_fmac_f32_dpp v119, -v189, v61 quad_perm:[1,1,1,1] row_mask:0xf bank_mask:0xf
	v_fmac_f32_dpp v116, -v188, v62 quad_perm:[2,2,2,2] row_mask:0xf bank_mask:0xf
	v_fmac_f32_dpp v117, -v189, v63 quad_perm:[2,2,2,2] row_mask:0xf bank_mask:0xf
	v_fmac_f32_dpp v118, -v188, v64 quad_perm:[3,3,3,3] row_mask:0xf bank_mask:0xf
	v_fmac_f32_dpp v119, -v189, v65 quad_perm:[3,3,3,3] row_mask:0xf bank_mask:0xf
	v_fmac_f32_dpp v116, -v190, v66 quad_perm:[0,0,0,0] row_mask:0xf bank_mask:0xf
	v_fmac_f32_dpp v117, -v191, v67 quad_perm:[0,0,0,0] row_mask:0xf bank_mask:0xf
	v_fmac_f32_dpp v118, -v190, v68 quad_perm:[1,1,1,1] row_mask:0xf bank_mask:0xf
	v_fmac_f32_dpp v119, -v191, v69 quad_perm:[1,1,1,1] row_mask:0xf bank_mask:0xf
	v_fmac_f32_dpp v116, -v190, v70 quad_perm:[2,2,2,2] row_mask:0xf bank_mask:0xf
	v_fmac_f32_dpp v117, -v191, v71 quad_perm:[2,2,2,2] row_mask:0xf bank_mask:0xf
	v_add_f32_e32 v121, v117, v116
	v_add_f32_e32 v122, v118, v119
	v_add_f32_e32 v26, v122, v121
	s_waitcnt lgkmcnt(0)
; __device__ __forceinline__ float bf2f(bf16 v) { return __uint_as_float(((unsigned)v) << 16); }
; #define GDN_LOADROW(buf, rr_, i_) do { _Pragma("unroll") for (int j4 = 0; j4 < ((i_) + 3) / 4; ++j4) buf[j4] = *(const f32x4*)(Lm + (i_) * GP_LSTR + 4 * j4); rr_ = bf2f(*(const bf16*)(xsrc + (i_) * GP_STR * 2)) * scl[i_]; } while (0)
; template <int STRIP> __device__ __forceinline__ void ph_gdn_prep_fast(const bf16* __restrict__ proj, const float* __restrict__ small, const float* __restrict__ conv_w, const float* __restrict__ a_log, const float* __restrict__ dt_bias, ...
;     ...
;             f32x4 bA[16], bB[16]; float rA, rB = 0.f;
;             rA = bf2f(*(const bf16*)xsrc) * scl[0];
;     ...
; #pragma unroll
;             for (int i = 0; i < 64; i += 2) {
;                 GDN_LOADROW(bB, rB, i + 1);
;                 GDN_ROW(bA, rA, i);
;                 if (i + 2 < 64) GDN_LOADROW(bA, rA, i + 2);
;                 GDN_ROW(bB, rB, i + 1);
;             }
;     ...
;             if (STRIP == 3) { if (U[63] == 12345.678f) EGL[ci] = U[5]; } else
;             if (!isw) { const int v = cc >> 4, c15 = cc & 15; bf16* dst = UF + ((size_t)ci * 8 + v) * 64 * 16;
	v_mul_f32_dpp v120, v192, v4 quad_perm:[0,0,0,0] row_mask:0xf bank_mask:0xf
	v_fma_f32 v116, v219, v247, -v120
	v_mul_f32_dpp v117, -v193, v5 quad_perm:[0,0,0,0] row_mask:0xf bank_mask:0xf
	v_mul_f32_dpp v118, -v192, v6 quad_perm:[1,1,1,1] row_mask:0xf bank_mask:0xf
	v_mul_f32_dpp v119, -v193, v12 quad_perm:[1,1,1,1] row_mask:0xf bank_mask:0xf
	v_fmac_f32_dpp v116, -v192, v7 quad_perm:[2,2,2,2] row_mask:0xf bank_mask:0xf
	v_fmac_f32_dpp v117, -v193, v13 quad_perm:[2,2,2,2] row_mask:0xf bank_mask:0xf
	v_fmac_f32_dpp v118, -v192, v14 quad_perm:[3,3,3,3] row_mask:0xf bank_mask:0xf
	v_fmac_f32_dpp v119, -v193, v15 quad_perm:[3,3,3,3] row_mask:0xf bank_mask:0xf
	v_fmac_f32_dpp v116, -v194, v16 quad_perm:[0,0,0,0] row_mask:0xf bank_mask:0xf
	v_fmac_f32_dpp v117, -v195, v17 quad_perm:[0,0,0,0] row_mask:0xf bank_mask:0xf
	v_fmac_f32_dpp v118, -v194, v19 quad_perm:[1,1,1,1] row_mask:0xf bank_mask:0xf
	v_fmac_f32_dpp v119, -v195, v20 quad_perm:[1,1,1,1] row_mask:0xf bank_mask:0xf
	v_fmac_f32_dpp v116, -v194, v21 quad_perm:[2,2,2,2] row_mask:0xf bank_mask:0xf
	v_fmac_f32_dpp v117, -v195, v22 quad_perm:[2,2,2,2] row_mask:0xf bank_mask:0xf
	v_fmac_f32_dpp v118, -v194, v23 quad_perm:[3,3,3,3] row_mask:0xf bank_mask:0xf
	v_fmac_f32_dpp v119, -v195, v24 quad_perm:[3,3,3,3] row_mask:0xf bank_mask:0xf
	v_fmac_f32_dpp v116, -v196, v25 quad_perm:[0,0,0,0] row_mask:0xf bank_mask:0xf
	v_fmac_f32_dpp v117, -v197, v27 quad_perm:[0,0,0,0] row_mask:0xf bank_mask:0xf
	v_fmac_f32_dpp v118, -v196, v28 quad_perm:[1,1,1,1] row_mask:0xf bank_mask:0xf
	v_fmac_f32_dpp v119, -v197, v29 quad_perm:[1,1,1,1] row_mask:0xf bank_mask:0xf
	v_fmac_f32_dpp v116, -v196, v30 quad_perm:[2,2,2,2] row_mask:0xf bank_mask:0xf
	v_fmac_f32_dpp v117, -v197, v31 quad_perm:[2,2,2,2] row_mask:0xf bank_mask:0xf
	v_fmac_f32_dpp v118, -v196, v32 quad_perm:[3,3,3,3] row_mask:0xf bank_mask:0xf
	v_fmac_f32_dpp v119, -v197, v33 quad_perm:[3,3,3,3] row_mask:0xf bank_mask:0xf
	v_fmac_f32_dpp v116, -v198, v34 quad_perm:[0,0,0,0] row_mask:0xf bank_mask:0xf
	v_fmac_f32_dpp v117, -v199, v35 quad_perm:[0,0,0,0] row_mask:0xf bank_mask:0xf
	v_fmac_f32_dpp v118, -v198, v36 quad_perm:[1,1,1,1] row_mask:0xf bank_mask:0xf
	v_fmac_f32_dpp v119, -v199, v37 quad_perm:[1,1,1,1] row_mask:0xf bank_mask:0xf
	v_fmac_f32_dpp v116, -v198, v38 quad_perm:[2,2,2,2] row_mask:0xf bank_mask:0xf
	v_fmac_f32_dpp v117, -v199, v39 quad_perm:[2,2,2,2] row_mask:0xf bank_mask:0xf
	v_fmac_f32_dpp v118, -v198, v40 quad_perm:[3,3,3,3] row_mask:0xf bank_mask:0xf
	v_fmac_f32_dpp v119, -v199, v41 quad_perm:[3,3,3,3] row_mask:0xf bank_mask:0xf
	v_fmac_f32_dpp v116, -v200, v42 quad_perm:[0,0,0,0] row_mask:0xf bank_mask:0xf
	v_fmac_f32_dpp v117, -v201, v43 quad_perm:[0,0,0,0] row_mask:0xf bank_mask:0xf
	v_fmac_f32_dpp v118, -v200, v44 quad_perm:[1,1,1,1] row_mask:0xf bank_mask:0xf
	v_fmac_f32_dpp v119, -v201, v45 quad_perm:[1,1,1,1] row_mask:0xf bank_mask:0xf
	v_fmac_f32_dpp v116, -v200, v46 quad_perm:[2,2,2,2] row_mask:0xf bank_mask:0xf
	v_fmac_f32_dpp v117, -v201, v47 quad_perm:[2,2,2,2] row_mask:0xf bank_mask:0xf
	v_fmac_f32_dpp v118, -v200, v48 quad_perm:[3,3,3,3] row_mask:0xf bank_mask:0xf
	v_fmac_f32_dpp v119, -v201, v49 quad_perm:[3,3,3,3] row_mask:0xf bank_mask:0xf
	v_fmac_f32_dpp v116, -v202, v50 quad_perm:[0,0,0,0] row_mask:0xf bank_mask:0xf
	v_fmac_f32_dpp v117, -v203, v51 quad_perm:[0,0,0,0] row_mask:0xf bank_mask:0xf
	v_fmac_f32_dpp v118, -v202, v52 quad_perm:[1,1,1,1] row_mask:0xf bank_mask:0xf
	v_fmac_f32_dpp v119, -v203, v53 quad_perm:[1,1,1,1] row_mask:0xf bank_mask:0xf
	v_fmac_f32_dpp v116, -v202, v54 quad_perm:[2,2,2,2] row_mask:0xf bank_mask:0xf
	v_fmac_f32_dpp v117, -v203, v55 quad_perm:[2,2,2,2] row_mask:0xf bank_mask:0xf
	v_fmac_f32_dpp v118, -v202, v56 quad_perm:[3,3,3,3] row_mask:0xf bank_mask:0xf
	v_fmac_f32_dpp v119, -v203, v57 quad_perm:[3,3,3,3] row_mask:0xf bank_mask:0xf
	v_fmac_f32_dpp v116, -v204, v58 quad_perm:[0,0,0,0] row_mask:0xf bank_mask:0xf
	v_fmac_f32_dpp v117, -v205, v59 quad_perm:[0,0,0,0] row_mask:0xf bank_mask:0xf
	v_fmac_f32_dpp v118, -v204, v60 quad_perm:[1,1,1,1] row_mask:0xf bank_mask:0xf
	v_fmac_f32_dpp v119, -v205, v61 quad_perm:[1,1,1,1] row_mask:0xf bank_mask:0xf
	v_fmac_f32_dpp v116, -v204, v62 quad_perm:[2,2,2,2] row_mask:0xf bank_mask:0xf
	v_fmac_f32_dpp v117, -v205, v63 quad_perm:[2,2,2,2] row_mask:0xf bank_mask:0xf
	v_fmac_f32_dpp v118, -v204, v64 quad_perm:[3,3,3,3] row_mask:0xf bank_mask:0xf
	v_fmac_f32_dpp v119, -v205, v65 quad_perm:[3,3,3,3] row_mask:0xf bank_mask:0xf
	v_fmac_f32_dpp v116, -v206, v66 quad_perm:[0,0,0,0] row_mask:0xf bank_mask:0xf
	v_fmac_f32_dpp v117, -v207, v67 quad_perm:[0,0,0,0] row_mask:0xf bank_mask:0xf
	v_fmac_f32_dpp v118, -v206, v68 quad_perm:[1,1,1,1] row_mask:0xf bank_mask:0xf
	v_fmac_f32_dpp v119, -v207, v69 quad_perm:[1,1,1,1] row_mask:0xf bank_mask:0xf
	v_fmac_f32_dpp v116, -v206, v70 quad_perm:[2,2,2,2] row_mask:0xf bank_mask:0xf
	v_fmac_f32_dpp v117, -v207, v71 quad_perm:[2,2,2,2] row_mask:0xf bank_mask:0xf
	v_fmac_f32_dpp v118, -v206, v26 quad_perm:[3,3,3,3] row_mask:0xf bank_mask:0xf
	v_add_f32_e32 v121, v117, v116
	v_add_f32_e32 v122, v118, v119
	v_add_f32_e32 v72, v122, v121
	v_add_u32_e32 v8, v79, v8
	v_ashrrev_i32_e32 v9, 31, v8
	v_lshlrev_b64 v[8:9], 14, v[8:9]
	v_lshlrev_b32_e32 v73, 4, v78
	s_and_saveexec_b64 s[0:1], vcc
	s_xor_b64 s[0:1], exec, s[0:1]
	s_cbranch_execz .LBB0_1305
; __device__ __forceinline__ bf16 f2bf(float f) { return (bf16)(pk2(f, 0.f) & 0xffffu); }
; __device__ __forceinline__ int gperm(int x) { return (x & ~31) | ((x & 12) << 1) | ((x & 16) >> 2) | (x & 3); }
; template <int STRIP> __device__ __forceinline__ void ph_gdn_prep_fast(const bf16* __restrict__ proj, const float* __restrict__ small, const float* __restrict__ conv_w, const float* __restrict__ a_log, const float* __restrict__ dt_bias, ...
;     ...
;             else { bf16* dst = WP + (size_t)ci * 64 * 128 + gperm(cc);
; #pragma unroll
;                 for (int i = 0; i < 64; ++i) __builtin_nontemporal_store(f2bf(U[i]), dst + i * 128); }
	v_and_b32_e32 v2, 24, v18
	v_lshrrev_b32_e32 v18, 2, v78
	v_and_b32_e32 v18, 4, v18
	v_and_b32_e32 v73, 0x63, v78
	v_or3_b32 v2, v18, v73, v2
	v_lshl_add_u64 v[74:75], s[34:35], 0, v[8:9]
	v_lshlrev_b32_e32 v2, 1, v2
	v_lshl_add_u64 v[74:75], v[74:75], 0, v[2:3]
	v_cvt_pk_bf16_f32 v2, v4, s0
	global_store_short v[74:75], v2, off nt
	v_cvt_pk_bf16_f32 v2, v5, s0
	global_store_short v[74:75], v2, off offset:256 nt
	v_cvt_pk_bf16_f32 v2, v6, s0
	global_store_short v[74:75], v2, off offset:512 nt
	v_cvt_pk_bf16_f32 v2, v12, s0
	global_store_short v[74:75], v2, off offset:768 nt
	v_cvt_pk_bf16_f32 v2, v7, s0
	global_store_short v[74:75], v2, off offset:1024 nt
	v_cvt_pk_bf16_f32 v2, v13, s0
	global_store_short v[74:75], v2, off offset:1280 nt
	v_cvt_pk_bf16_f32 v2, v14, s0
	global_store_short v[74:75], v2, off offset:1536 nt
	v_cvt_pk_bf16_f32 v2, v15, s0
	global_store_short v[74:75], v2, off offset:1792 nt
	v_cvt_pk_bf16_f32 v2, v16, s0
	global_store_short v[74:75], v2, off offset:2048 nt
	v_cvt_pk_bf16_f32 v2, v17, s0
	global_store_short v[74:75], v2, off offset:2304 nt
	v_cvt_pk_bf16_f32 v2, v19, s0
	global_store_short v[74:75], v2, off offset:2560 nt
	v_cvt_pk_bf16_f32 v2, v20, s0
	global_store_short v[74:75], v2, off offset:2816 nt
	v_cvt_pk_bf16_f32 v2, v21, s0
	global_store_short v[74:75], v2, off offset:3072 nt
	v_cvt_pk_bf16_f32 v2, v22, s0
	v_add_co_u32_e32 v4, vcc, s79, v74
	global_store_short v[74:75], v2, off offset:3328 nt
	v_cvt_pk_bf16_f32 v2, v23, s0
	v_addc_co_u32_e32 v5, vcc, 0, v75, vcc
	global_store_short v[74:75], v2, off offset:3584 nt
	v_cvt_pk_bf16_f32 v2, v24, s0
	v_add_co_u32_e32 v6, vcc, s76, v74
	global_store_short v[74:75], v2, off offset:3840 nt
	v_cvt_pk_bf16_f32 v2, v25, s0
	v_addc_co_u32_e32 v7, vcc, 0, v75, vcc
	global_store_short v[6:7], v2, off offset:-4096 nt
	v_cvt_pk_bf16_f32 v2, v27, s0
	global_store_short v[4:5], v2, off offset:256 nt
	v_cvt_pk_bf16_f32 v2, v28, s0
	global_store_short v[4:5], v2, off offset:512 nt
	v_cvt_pk_bf16_f32 v2, v29, s0
	global_store_short v[4:5], v2, off offset:768 nt
	v_cvt_pk_bf16_f32 v2, v30, s0
	global_store_short v[4:5], v2, off offset:1024 nt
	v_cvt_pk_bf16_f32 v2, v31, s0
	global_store_short v[4:5], v2, off offset:1280 nt
	v_cvt_pk_bf16_f32 v2, v32, s0
	global_store_short v[4:5], v2, off offset:1536 nt
	v_cvt_pk_bf16_f32 v2, v33, s0
	global_store_short v[4:5], v2, off offset:1792 nt
	v_cvt_pk_bf16_f32 v2, v34, s0
	global_store_short v[4:5], v2, off offset:2048 nt
	v_cvt_pk_bf16_f32 v2, v35, s0
	global_store_short v[4:5], v2, off offset:2304 nt
	v_cvt_pk_bf16_f32 v2, v36, s0
	global_store_short v[4:5], v2, off offset:2560 nt
	v_cvt_pk_bf16_f32 v2, v37, s0
	global_store_short v[4:5], v2, off offset:2816 nt
	v_cvt_pk_bf16_f32 v2, v38, s0
	global_store_short v[4:5], v2, off offset:3072 nt
	v_cvt_pk_bf16_f32 v2, v39, s0
	global_store_short v[4:5], v2, off offset:3328 nt
	v_cvt_pk_bf16_f32 v2, v40, s0
	global_store_short v[4:5], v2, off offset:3584 nt
	v_cvt_pk_bf16_f32 v2, v41, s0
	global_store_short v[4:5], v2, off offset:3840 nt
	v_cvt_pk_bf16_f32 v2, v42, s0
	global_store_short v[6:7], v2, off nt
	v_cvt_pk_bf16_f32 v2, v43, s0
	global_store_short v[6:7], v2, off offset:256 nt
	v_cvt_pk_bf16_f32 v2, v44, s0
	global_store_short v[6:7], v2, off offset:512 nt
	v_cvt_pk_bf16_f32 v2, v45, s0
	global_store_short v[6:7], v2, off offset:768 nt
	v_cvt_pk_bf16_f32 v2, v46, s0
	global_store_short v[6:7], v2, off offset:1024 nt
	v_cvt_pk_bf16_f32 v2, v47, s0
	global_store_short v[6:7], v2, off offset:1280 nt
	v_cvt_pk_bf16_f32 v2, v48, s0
	global_store_short v[6:7], v2, off offset:1536 nt
	v_cvt_pk_bf16_f32 v2, v49, s0
	global_store_short v[6:7], v2, off offset:1792 nt
	v_cvt_pk_bf16_f32 v2, v50, s0
	global_store_short v[6:7], v2, off offset:2048 nt
	v_cvt_pk_bf16_f32 v2, v51, s0
	global_store_short v[6:7], v2, off offset:2304 nt
	v_cvt_pk_bf16_f32 v2, v52, s0
	global_store_short v[6:7], v2, off offset:2560 nt
	v_cvt_pk_bf16_f32 v2, v53, s0
	global_store_short v[6:7], v2, off offset:2816 nt
	v_cvt_pk_bf16_f32 v2, v54, s0
	global_store_short v[6:7], v2, off offset:3072 nt
	v_cvt_pk_bf16_f32 v2, v55, s0
	global_store_short v[6:7], v2, off offset:3328 nt
	v_cvt_pk_bf16_f32 v2, v56, s0
	s_movk_i32 s2, 0x3000
	global_store_short v[6:7], v2, off offset:3584 nt
	v_cvt_pk_bf16_f32 v2, v57, s0
	v_add_co_u32_e32 v4, vcc, s2, v74
	global_store_short v[6:7], v2, off offset:3840 nt
	v_cvt_pk_bf16_f32 v2, v58, s0
	v_addc_co_u32_e32 v5, vcc, 0, v75, vcc
	global_store_short v[4:5], v2, off nt
	v_cvt_pk_bf16_f32 v2, v59, s0
	global_store_short v[4:5], v2, off offset:256 nt
	v_cvt_pk_bf16_f32 v2, v60, s0
	global_store_short v[4:5], v2, off offset:512 nt
	v_cvt_pk_bf16_f32 v2, v61, s0
	global_store_short v[4:5], v2, off offset:768 nt
	v_cvt_pk_bf16_f32 v2, v62, s0
	global_store_short v[4:5], v2, off offset:1024 nt
	v_cvt_pk_bf16_f32 v2, v63, s0
	global_store_short v[4:5], v2, off offset:1280 nt
	v_cvt_pk_bf16_f32 v2, v64, s0
	global_store_short v[4:5], v2, off offset:1536 nt
	v_cvt_pk_bf16_f32 v2, v65, s0
	global_store_short v[4:5], v2, off offset:1792 nt
	v_cvt_pk_bf16_f32 v2, v66, s0
	global_store_short v[4:5], v2, off offset:2048 nt
	v_cvt_pk_bf16_f32 v2, v67, s0
	global_store_short v[4:5], v2, off offset:2304 nt
	v_cvt_pk_bf16_f32 v2, v68, s0
	global_store_short v[4:5], v2, off offset:2560 nt
	v_cvt_pk_bf16_f32 v2, v69, s0
	global_store_short v[4:5], v2, off offset:2816 nt
	v_cvt_pk_bf16_f32 v2, v70, s0
	global_store_short v[4:5], v2, off offset:3072 nt
	v_cvt_pk_bf16_f32 v2, v71, s0
	global_store_short v[4:5], v2, off offset:3328 nt
	v_cvt_pk_bf16_f32 v2, v26, s0
	global_store_short v[4:5], v2, off offset:3584 nt
	v_cvt_pk_bf16_f32 v2, v72, s0
	global_store_short v[4:5], v2, off offset:3840 nt
	v_lshlrev_b32_e32 v73, 4, v78

; __global__ void __launch_bounds__(NTHREADS, 2) mega(Params P) {
	.amdhsa_kernel _Z4mega6Params
		.amdhsa_group_segment_fixed_size 0
		.amdhsa_private_segment_fixed_size 0
		.amdhsa_kernarg_size 440
		.amdhsa_user_sgpr_count 2
		.amdhsa_user_sgpr_dispatch_ptr 0
		.amdhsa_user_sgpr_queue_ptr 0
		.amdhsa_user_sgpr_kernarg_segment_ptr 1
		.amdhsa_user_sgpr_dispatch_id 0
		.amdhsa_user_sgpr_kernarg_preload_length 0
		.amdhsa_user_sgpr_kernarg_preload_offset 0
		.amdhsa_user_sgpr_private_segment_size 0
		.amdhsa_uses_dynamic_stack 0
		.amdhsa_enable_private_segment 0
		.amdhsa_system_sgpr_workgroup_id_x 1
		.amdhsa_system_sgpr_workgroup_id_y 0
		.amdhsa_system_sgpr_workgroup_id_z 0
		.amdhsa_system_sgpr_workgroup_info 0
		.amdhsa_system_vgpr_workitem_id 0
		.amdhsa_next_free_vgpr 256
		.amdhsa_next_free_sgpr 102
		.amdhsa_accum_offset 256
		.amdhsa_reserve_vcc 1
		.amdhsa_float_round_mode_32 0
		.amdhsa_float_round_mode_16_64 0
		.amdhsa_float_denorm_mode_32 3
		.amdhsa_float_denorm_mode_16_64 3
		.amdhsa_dx10_clamp 1
		.amdhsa_ieee_mode 1
		.amdhsa_fp16_overflow 0
		.amdhsa_tg_split 0
		.amdhsa_exception_fp_ieee_invalid_op 0
		.amdhsa_exception_fp_denorm_src 0
		.amdhsa_exception_fp_ieee_div_zero 0
		.amdhsa_exception_fp_ieee_overflow 0
		.amdhsa_exception_fp_ieee_underflow 0
		.amdhsa_exception_fp_ieee_inexact 0
		.amdhsa_exception_int_div_zero 0
	.end_amdhsa_kernel

; __global__ void __launch_bounds__(NTHREADS, 2) mega(Params P) {
amdhsa.kernels:
  - .agpr_count:     0
    .args:
      - .offset:         0
        .size:           184
        .value_kind:     by_value
      - .offset:         184
        .size:           4
        .value_kind:     hidden_block_count_x
      - .offset:         188
        .size:           4
        .value_kind:     hidden_block_count_y
      - .offset:         192
        .size:           4
        .value_kind:     hidden_block_count_z
      - .offset:         196
        .size:           2
        .value_kind:     hidden_group_size_x
      - .offset:         198
        .size:           2
        .value_kind:     hidden_group_size_y
      - .offset:         200
        .size:           2
        .value_kind:     hidden_group_size_z
      - .offset:         202
        .size:           2
        .value_kind:     hidden_remainder_x
      - .offset:         204
        .size:           2
        .value_kind:     hidden_remainder_y
      - .offset:         206
        .size:           2
        .value_kind:     hidden_remainder_z
      - .offset:         224
        .size:           8
        .value_kind:     hidden_global_offset_x
      - .offset:         232
        .size:           8
        .value_kind:     hidden_global_offset_y
      - .offset:         240
        .size:           8
        .value_kind:     hidden_global_offset_z
      - .offset:         248
        .size:           2
        .value_kind:     hidden_grid_dims
      - .offset:         304
        .size:           4
        .value_kind:     hidden_dynamic_lds_size
    .group_segment_fixed_size: 0
    .kernarg_segment_align: 8
    .kernarg_segment_size: 440
    .language:       OpenCL C
    .language_version:
      - 2
      - 0
    .max_flat_workgroup_size: 512
    .name:           _Z4mega6Params
    .private_segment_fixed_size: 0
    .sgpr_count:     108
    .sgpr_spill_count: 74
    .symbol:         _Z4mega6Params.kd
    .uniform_work_group_size: 1
    .uses_dynamic_stack: false
    .vgpr_count:     256
    .vgpr_spill_count: 0
    .wavefront_size: 64
